# GEMM 8-phase loops: dropped the partial s_waitcnt lgkmcnt(8) before the phase-1/5 scheduling barrier (the tail form already omits it; lgkmcnt(0) after the barrier covers the reads)
# baseline (speedup 1.0000x reference)
; #define STAGE(P, BASE, br, kt) do { const long _g = (long)(br) * K + (long)(kt) * 64; \
;     _Pragma("unroll") for (int _i = 0; _i < 2; ++_i) { const int _b = tidx * 16 + _i * 8192; int _r, _c; stage_rc8(_b, _r, _c); \
;       __builtin_amdgcn_global_load_lds((const unsigned*)(BASE + _g + (long)_r * K + _c), (LAS unsigned*)((LAS char*)(P) + _b), 16, 0, 0); } } while (0)
; #define LDA(dst, b, h) _Pragma("unroll") for (int m = 0; m < 4; ++m) _Pragma("unroll") for (int k = 0; k < 2; ++k) \
;     dst[m][k] = *reinterpret_cast<const bf16x8*>((const char*)SA(b, h) + lds_byte8(wr * 64 + m * 16 + fr, k * 32 + fq * 8))
; #define LDB(dst, b, h) _Pragma("unroll") for (int n = 0; n < 2; ++n) _Pragma("unroll") for (int k = 0; k < 2; ++k) \
;     dst[n][k] = *reinterpret_cast<const bf16x8*>((const char*)SB(b, h) + lds_byte8(wc * 32 + n * 16 + fr, k * 32 + fq * 8))
; #define MMA(ai, bj, At_, Bt_) do { __builtin_amdgcn_s_setprio(1); \
;     _Pragma("unroll") for (int m = 0; m < 4; ++m) _Pragma("unroll") for (int n = 0; n < 2; ++n) _Pragma("unroll") for (int k = 0; k < 2; ++k) \
;       acc[ai][bj][m][n] = MFMA16(Bt_[n][k], At_[m][k], acc[ai][bj][m][n]); \
;     __builtin_amdgcn_s_setprio(0); } while (0)
; #define WAIT_V(n) asm volatile("s_waitcnt vmcnt(" #n ")" ::: "memory")
; #define WAIT_L(n) asm volatile("s_waitcnt lgkmcnt(" #n ")" ::: "memory")
; #define BAR __builtin_amdgcn_s_barrier()
; #define SCHED __builtin_amdgcn_sched_barrier(0)
; template <class FL, class FS>
; DI void gemm8_tile(char* shmc, const bf16_t* __restrict__ A, const bf16_t* __restrict__ Bt, const int K, const int brow, const int bcol, FL fl, FS fs) {
;     ...
;     LDB(B0, 0, 0); SCHED; LDA(At, 0, 0); STAGE(SA(1, 1), A, brow + HALF, t + 1);
;     WAIT_L(8); BAR; WAIT_L(0); MMA(0, 0, At, B0); BAR; SCHED;
;     LDB(B1, 0, 1); STAGE(SB(0, 0), Bt, bcol, t + 2);
;     BAR; WAIT_L(0); MMA(0, 1, At, B1); BAR;
;     LDA(At, 0, 1); STAGE(SA(0, 0), A, brow, t + 2);
;     BAR; WAIT_L(0); MMA(1, 0, At, B0); BAR; SCHED;
;     STAGE(SB(0, 1), Bt, bcol + HALF, t + 2);
;     WAIT_V(6); BAR; MMA(1, 1, At, B1); BAR;
.Lg1_p1skip:
	s_nop 0
	s_barrier
	s_waitcnt lgkmcnt(0)
	s_setprio 1
	s_waitcnt lgkmcnt(0)
	v_mfma_f32_16x16x32_bf16 v[124:127], v[172:175], v[192:195], v[124:127]
	v_mfma_f32_16x16x32_bf16 v[120:123], v[184:187], v[192:195], v[120:123]
	v_mfma_f32_16x16x32_bf16 v[116:119], v[172:175], v[200:203], v[116:119]
	v_mfma_f32_16x16x32_bf16 v[112:115], v[184:187], v[200:203], v[112:115]
	v_mfma_f32_16x16x32_bf16 v[108:111], v[172:175], v[208:211], v[108:111]
	v_mfma_f32_16x16x32_bf16 v[104:107], v[184:187], v[208:211], v[104:107]
	v_mfma_f32_16x16x32_bf16 v[100:103], v[172:175], v[216:219], v[100:103]
	v_mfma_f32_16x16x32_bf16 v[96:99], v[184:187], v[216:219], v[96:99]
	v_mfma_f32_16x16x32_bf16 v[124:127], v[176:179], v[196:199], v[124:127]
	v_mfma_f32_16x16x32_bf16 v[120:123], v[188:191], v[196:199], v[120:123]
	v_mfma_f32_16x16x32_bf16 v[116:119], v[176:179], v[204:207], v[116:119]
	v_mfma_f32_16x16x32_bf16 v[112:115], v[188:191], v[204:207], v[112:115]
	v_mfma_f32_16x16x32_bf16 v[108:111], v[176:179], v[212:215], v[108:111]
	v_mfma_f32_16x16x32_bf16 v[104:107], v[188:191], v[212:215], v[104:107]
	v_mfma_f32_16x16x32_bf16 v[100:103], v[176:179], v[220:223], v[100:103]
	v_mfma_f32_16x16x32_bf16 v[96:99], v[188:191], v[220:223], v[96:99]
	s_setprio 0
	s_barrier
	v_lshl_add_u64 v[242:243], s[12:13], 0, v[134:135]
	v_readfirstlane_b32 s1, v149
	v_lshl_add_u64 v[244:245], v[242:243], 0, s[24:25]
	s_mov_b32 m0, s1
	ds_read_b128 v[224:227], v166
	ds_read_b128 v[228:231], v166 offset:1024
	ds_read_b128 v[232:235], v166 offset:2048
	ds_read_b128 v[236:239], v166 offset:3072
	global_load_lds_dwordx4 v[244:245], off
	v_lshl_add_u64 v[244:245], s[12:13], 0, v[136:137]
	v_readfirstlane_b32 s1, v155
	v_lshl_add_u64 v[246:247], v[244:245], 0, s[24:25]
	s_mov_b32 m0, s1
	s_nop 0
	global_load_lds_dwordx4 v[246:247], off
	s_barrier
	s_waitcnt lgkmcnt(0)
	s_setprio 1
	s_waitcnt lgkmcnt(0)
	v_mfma_f32_16x16x32_bf16 v[92:95], v[224:227], v[192:195], v[92:95]
	v_mfma_f32_16x16x32_bf16 v[88:91], v[232:235], v[192:195], v[88:91]
	v_mfma_f32_16x16x32_bf16 v[84:87], v[224:227], v[200:203], v[84:87]
	v_mfma_f32_16x16x32_bf16 v[80:83], v[232:235], v[200:203], v[80:83]
	v_mfma_f32_16x16x32_bf16 v[76:79], v[224:227], v[208:211], v[76:79]
	v_mfma_f32_16x16x32_bf16 v[72:75], v[232:235], v[208:211], v[72:75]
	v_mfma_f32_16x16x32_bf16 v[68:71], v[224:227], v[216:219], v[68:71]
	v_mfma_f32_16x16x32_bf16 v[64:67], v[232:235], v[216:219], v[64:67]
	v_mfma_f32_16x16x32_bf16 v[92:95], v[228:231], v[196:199], v[92:95]
	v_mfma_f32_16x16x32_bf16 v[88:91], v[236:239], v[196:199], v[88:91]
	v_mfma_f32_16x16x32_bf16 v[84:87], v[228:231], v[204:207], v[84:87]
	v_mfma_f32_16x16x32_bf16 v[80:83], v[236:239], v[204:207], v[80:83]
	v_mfma_f32_16x16x32_bf16 v[76:79], v[228:231], v[212:215], v[76:79]
	v_mfma_f32_16x16x32_bf16 v[72:75], v[236:239], v[212:215], v[72:75]
	v_mfma_f32_16x16x32_bf16 v[68:71], v[228:231], v[220:223], v[68:71]
	v_mfma_f32_16x16x32_bf16 v[64:67], v[236:239], v[220:223], v[64:67]
	s_setprio 0
	v_readfirstlane_b32 s1, v147
	v_lshl_add_u64 v[246:247], v[180:181], 0, s[26:27]
	s_mov_b32 m0, s1
	v_readfirstlane_b32 s1, v153
	s_barrier
	ds_read_b128 v[192:195], v152 offset:16384
	ds_read_b128 v[196:199], v152 offset:17408
	ds_read_b128 v[200:203], v151 offset:16384
	ds_read_b128 v[204:207], v151 offset:17408
	ds_read_b128 v[208:211], v150 offset:16384
	ds_read_b128 v[212:215], v150 offset:17408
	ds_read_b128 v[216:219], v148 offset:16384
	ds_read_b128 v[220:223], v148 offset:17408
	global_load_lds_dwordx4 v[246:247], off
	v_lshl_add_u64 v[246:247], v[240:241], 0, s[26:27]
	s_mov_b32 m0, s1
	s_nop 0
	global_load_lds_dwordx4 v[246:247], off
	s_barrier
	s_waitcnt lgkmcnt(0)
	s_setprio 1
	s_waitcnt lgkmcnt(0)
	v_mfma_f32_16x16x32_bf16 v[60:63], v[172:175], v[192:195], v[60:63]
	v_mfma_f32_16x16x32_bf16 v[56:59], v[184:187], v[192:195], v[56:59]
	v_mfma_f32_16x16x32_bf16 v[52:55], v[172:175], v[200:203], v[52:55]
	v_mfma_f32_16x16x32_bf16 v[48:51], v[184:187], v[200:203], v[48:51]
	v_mfma_f32_16x16x32_bf16 v[44:47], v[172:175], v[208:211], v[44:47]
	v_mfma_f32_16x16x32_bf16 v[40:43], v[184:187], v[208:211], v[40:43]
	v_mfma_f32_16x16x32_bf16 v[36:39], v[172:175], v[216:219], v[36:39]
	v_mfma_f32_16x16x32_bf16 v[32:35], v[184:187], v[216:219], v[32:35]
	v_mfma_f32_16x16x32_bf16 v[60:63], v[176:179], v[196:199], v[60:63]
	v_mfma_f32_16x16x32_bf16 v[56:59], v[188:191], v[196:199], v[56:59]
	v_mfma_f32_16x16x32_bf16 v[52:55], v[176:179], v[204:207], v[52:55]
	v_mfma_f32_16x16x32_bf16 v[48:51], v[188:191], v[204:207], v[48:51]
	v_mfma_f32_16x16x32_bf16 v[44:47], v[176:179], v[212:215], v[44:47]
	v_mfma_f32_16x16x32_bf16 v[40:43], v[188:191], v[212:215], v[40:43]
	v_mfma_f32_16x16x32_bf16 v[36:39], v[176:179], v[220:223], v[36:39]
	v_mfma_f32_16x16x32_bf16 v[32:35], v[188:191], v[220:223], v[32:35]
	s_setprio 0
	s_barrier
	v_readfirstlane_b32 s1, v157
	v_lshl_add_u64 v[172:173], v[242:243], 0, s[28:29]
	s_mov_b32 m0, s1
	v_readfirstlane_b32 s1, v158
	global_load_lds_dwordx4 v[172:173], off
	v_lshl_add_u64 v[172:173], v[244:245], 0, s[28:29]
	s_mov_b32 m0, s1
	s_nop 0
	global_load_lds_dwordx4 v[172:173], off
	s_cmp_eq_u32 s0, -2
	s_cselect_b32 s1, s98, 0
	s_cmp_lg_u32 s1, 0
	s_cbranch_scc1 .Lg1_w22
	s_waitcnt vmcnt(6)
; #define STAGE(P, BASE, br, kt) do { const long _g = (long)(br) * K + (long)(kt) * 64; \
;     _Pragma("unroll") for (int _i = 0; _i < 2; ++_i) { const int _b = tidx * 16 + _i * 8192; int _r, _c; stage_rc8(_b, _r, _c); \
;       __builtin_amdgcn_global_load_lds((const unsigned*)(BASE + _g + (long)_r * K + _c), (LAS unsigned*)((LAS char*)(P) + _b), 16, 0, 0); } } while (0)
; #define LDA(dst, b, h) _Pragma("unroll") for (int m = 0; m < 4; ++m) _Pragma("unroll") for (int k = 0; k < 2; ++k) \
;     dst[m][k] = *reinterpret_cast<const bf16x8*>((const char*)SA(b, h) + lds_byte8(wr * 64 + m * 16 + fr, k * 32 + fq * 8))
; #define LDB(dst, b, h) _Pragma("unroll") for (int n = 0; n < 2; ++n) _Pragma("unroll") for (int k = 0; k < 2; ++k) \
;     dst[n][k] = *reinterpret_cast<const bf16x8*>((const char*)SB(b, h) + lds_byte8(wc * 32 + n * 16 + fr, k * 32 + fq * 8))
; #define MMA(ai, bj, At_, Bt_) do { __builtin_amdgcn_s_setprio(1); \
;     _Pragma("unroll") for (int m = 0; m < 4; ++m) _Pragma("unroll") for (int n = 0; n < 2; ++n) _Pragma("unroll") for (int k = 0; k < 2; ++k) \
;       acc[ai][bj][m][n] = MFMA16(Bt_[n][k], At_[m][k], acc[ai][bj][m][n]); \
;     __builtin_amdgcn_s_setprio(0); } while (0)
; #define WAIT_V(n) asm volatile("s_waitcnt vmcnt(" #n ")" ::: "memory")
; #define WAIT_L(n) asm volatile("s_waitcnt lgkmcnt(" #n ")" ::: "memory")
; #define BAR __builtin_amdgcn_s_barrier()
; #define SCHED __builtin_amdgcn_sched_barrier(0)
; template <class FL, class FS>
; DI void gemm8_tile(char* shmc, const bf16_t* __restrict__ A, const bf16_t* __restrict__ Bt, const int K, const int brow, const int bcol, FL fl, FS fs) {
;     ...
;     WAIT_V(6); BAR; MMA(1, 1, At, B1); BAR;
;     LDB(B0, 1, 0); SCHED; LDA(At, 1, 0); STAGE(SA(0, 1), A, brow + HALF, t + 2);
;     WAIT_L(8); BAR; WAIT_L(0); MMA(0, 0, At, B0); BAR; SCHED;
;     LDB(B1, 1, 1); STAGE(SB(1, 0), Bt, bcol, t + 3);
;     BAR; WAIT_L(0); MMA(0, 1, At, B1); BAR;
;     LDA(At, 1, 1); STAGE(SA(1, 0), A, brow, t + 3);
;     BAR; WAIT_L(0); MMA(1, 0, At, B0); BAR; SCHED;
.Lg1_wd:
	s_barrier
	s_setprio 1
	v_mfma_f32_16x16x32_bf16 v[28:31], v[224:227], v[192:195], v[28:31]
	v_mfma_f32_16x16x32_bf16 v[24:27], v[232:235], v[192:195], v[24:27]
	v_mfma_f32_16x16x32_bf16 v[20:23], v[224:227], v[200:203], v[20:23]
	v_mfma_f32_16x16x32_bf16 v[16:19], v[232:235], v[200:203], v[16:19]
	v_mfma_f32_16x16x32_bf16 v[12:15], v[224:227], v[208:211], v[12:15]
	v_mfma_f32_16x16x32_bf16 v[8:11], v[232:235], v[208:211], v[8:11]
	v_mfma_f32_16x16x32_bf16 v[4:7], v[224:227], v[216:219], v[4:7]
	v_mfma_f32_16x16x32_bf16 v[0:3], v[232:235], v[216:219], v[0:3]
	v_mfma_f32_16x16x32_bf16 v[28:31], v[228:231], v[196:199], v[28:31]
	v_mfma_f32_16x16x32_bf16 v[24:27], v[236:239], v[196:199], v[24:27]
	v_mfma_f32_16x16x32_bf16 v[20:23], v[228:231], v[204:207], v[20:23]
	v_mfma_f32_16x16x32_bf16 v[16:19], v[236:239], v[204:207], v[16:19]
	v_mfma_f32_16x16x32_bf16 v[12:15], v[228:231], v[212:215], v[12:15]
	v_mfma_f32_16x16x32_bf16 v[8:11], v[236:239], v[212:215], v[8:11]
	v_mfma_f32_16x16x32_bf16 v[4:7], v[228:231], v[220:223], v[4:7]
	v_mfma_f32_16x16x32_bf16 v[0:3], v[236:239], v[220:223], v[0:3]
	s_setprio 0
	s_barrier
	ds_read_b128 v[172:175], v156
	ds_read_b128 v[176:179], v156 offset:1024
	ds_read_b128 v[184:187], v156 offset:2048
	ds_read_b128 v[188:191], v156 offset:3072
	v_readfirstlane_b32 s1, v159
	v_lshl_add_u64 v[224:225], v[180:181], 0, s[30:31]
	s_mov_b32 m0, s1
	v_readfirstlane_b32 s1, v160
	ds_read_b128 v[192:195], v152 offset:32768
	ds_read_b128 v[196:199], v152 offset:33792
	ds_read_b128 v[200:203], v151 offset:32768
	ds_read_b128 v[204:207], v151 offset:33792
	ds_read_b128 v[208:211], v150 offset:32768
	ds_read_b128 v[212:215], v150 offset:33792
	ds_read_b128 v[216:219], v148 offset:32768
	ds_read_b128 v[220:223], v148 offset:33792
	global_load_lds_dwordx4 v[224:225], off
	v_lshl_add_u64 v[224:225], v[240:241], 0, s[30:31]
	s_mov_b32 m0, s1
	s_nop 0
	global_load_lds_dwordx4 v[224:225], off
	s_nop 0
	s_barrier
	s_waitcnt lgkmcnt(0)
	s_setprio 1
	s_waitcnt lgkmcnt(0)
	v_mfma_f32_16x16x32_bf16 v[124:127], v[172:175], v[192:195], v[124:127]
	v_mfma_f32_16x16x32_bf16 v[120:123], v[184:187], v[192:195], v[120:123]
	v_mfma_f32_16x16x32_bf16 v[116:119], v[172:175], v[200:203], v[116:119]
	v_mfma_f32_16x16x32_bf16 v[112:115], v[184:187], v[200:203], v[112:115]
	v_mfma_f32_16x16x32_bf16 v[108:111], v[172:175], v[208:211], v[108:111]
	v_mfma_f32_16x16x32_bf16 v[104:107], v[184:187], v[208:211], v[104:107]
	v_mfma_f32_16x16x32_bf16 v[100:103], v[172:175], v[216:219], v[100:103]
	v_mfma_f32_16x16x32_bf16 v[96:99], v[184:187], v[216:219], v[96:99]
	v_mfma_f32_16x16x32_bf16 v[124:127], v[176:179], v[196:199], v[124:127]
	v_mfma_f32_16x16x32_bf16 v[120:123], v[188:191], v[196:199], v[120:123]
	v_mfma_f32_16x16x32_bf16 v[116:119], v[176:179], v[204:207], v[116:119]
	v_mfma_f32_16x16x32_bf16 v[112:115], v[188:191], v[204:207], v[112:115]
	v_mfma_f32_16x16x32_bf16 v[108:111], v[176:179], v[212:215], v[108:111]
	v_mfma_f32_16x16x32_bf16 v[104:107], v[188:191], v[212:215], v[104:107]
	v_mfma_f32_16x16x32_bf16 v[100:103], v[176:179], v[220:223], v[100:103]
	v_mfma_f32_16x16x32_bf16 v[96:99], v[188:191], v[220:223], v[96:99]
	s_setprio 0
	s_barrier
	v_readfirstlane_b32 s1, v161
	v_lshl_add_u64 v[246:247], v[242:243], 0, s[34:35]
	s_mov_b32 m0, s1
	v_readfirstlane_b32 s1, v162
	ds_read_b128 v[224:227], v154
	ds_read_b128 v[228:231], v154 offset:1024
	ds_read_b128 v[232:235], v154 offset:2048
	ds_read_b128 v[236:239], v154 offset:3072
	global_load_lds_dwordx4 v[246:247], off
	v_lshl_add_u64 v[246:247], v[244:245], 0, s[34:35]
	s_mov_b32 m0, s1
	s_nop 0
	global_load_lds_dwordx4 v[246:247], off
	s_barrier
	s_waitcnt lgkmcnt(0)
	s_setprio 1
	s_waitcnt lgkmcnt(0)
	v_mfma_f32_16x16x32_bf16 v[92:95], v[224:227], v[192:195], v[92:95]
	v_mfma_f32_16x16x32_bf16 v[88:91], v[232:235], v[192:195], v[88:91]
	v_mfma_f32_16x16x32_bf16 v[84:87], v[224:227], v[200:203], v[84:87]
	v_mfma_f32_16x16x32_bf16 v[80:83], v[232:235], v[200:203], v[80:83]
	v_mfma_f32_16x16x32_bf16 v[76:79], v[224:227], v[208:211], v[76:79]
	v_mfma_f32_16x16x32_bf16 v[72:75], v[232:235], v[208:211], v[72:75]
	v_mfma_f32_16x16x32_bf16 v[68:71], v[224:227], v[216:219], v[68:71]
	v_mfma_f32_16x16x32_bf16 v[64:67], v[232:235], v[216:219], v[64:67]
	v_mfma_f32_16x16x32_bf16 v[92:95], v[228:231], v[196:199], v[92:95]
	v_mfma_f32_16x16x32_bf16 v[88:91], v[236:239], v[196:199], v[88:91]
	v_mfma_f32_16x16x32_bf16 v[84:87], v[228:231], v[204:207], v[84:87]
	v_mfma_f32_16x16x32_bf16 v[80:83], v[236:239], v[204:207], v[80:83]
	v_mfma_f32_16x16x32_bf16 v[76:79], v[228:231], v[212:215], v[76:79]
	v_mfma_f32_16x16x32_bf16 v[72:75], v[236:239], v[212:215], v[72:75]
	v_mfma_f32_16x16x32_bf16 v[68:71], v[228:231], v[220:223], v[68:71]
	v_mfma_f32_16x16x32_bf16 v[64:67], v[236:239], v[220:223], v[64:67]
	s_setprio 0
	v_readfirstlane_b32 s1, v163
	v_lshl_add_u64 v[180:181], v[180:181], 0, s[36:37]
	s_mov_b32 m0, s1
	v_readfirstlane_b32 s1, v164
	s_barrier
	ds_read_b128 v[192:195], v152 offset:49152
	ds_read_b128 v[196:199], v152 offset:50176
	ds_read_b128 v[200:203], v151 offset:49152
	ds_read_b128 v[204:207], v151 offset:50176
	ds_read_b128 v[208:211], v150 offset:49152
	ds_read_b128 v[212:215], v150 offset:50176
	ds_read_b128 v[216:219], v148 offset:49152
	ds_read_b128 v[220:223], v148 offset:50176
	global_load_lds_dwordx4 v[180:181], off
	v_lshl_add_u64 v[180:181], v[240:241], 0, s[36:37]
	s_mov_b32 m0, s1
	s_nop 0
	global_load_lds_dwordx4 v[180:181], off
	s_barrier
; #define STAGE(P, BASE, br, kt) do { const long _g = (long)(br) * K + (long)(kt) * 64; \
;     _Pragma("unroll") for (int _i = 0; _i < 2; ++_i) { const int _b = tidx * 16 + _i * 8192; int _r, _c; stage_rc8(_b, _r, _c); \
;       __builtin_amdgcn_global_load_lds((const unsigned*)(BASE + _g + (long)_r * K + _c), (LAS unsigned*)((LAS char*)(P) + _b), 16, 0, 0); } } while (0)
; #define LDA(dst, b, h) _Pragma("unroll") for (int m = 0; m < 4; ++m) _Pragma("unroll") for (int k = 0; k < 2; ++k) \
;     dst[m][k] = *reinterpret_cast<const bf16x8*>((const char*)SA(b, h) + lds_byte8(wr * 64 + m * 16 + fr, k * 32 + fq * 8))
; #define LDB(dst, b, h) _Pragma("unroll") for (int n = 0; n < 2; ++n) _Pragma("unroll") for (int k = 0; k < 2; ++k) \
;     dst[n][k] = *reinterpret_cast<const bf16x8*>((const char*)SB(b, h) + lds_byte8(wc * 32 + n * 16 + fr, k * 32 + fq * 8))
; #define MMA(ai, bj, At_, Bt_) do { __builtin_amdgcn_s_setprio(1); \
;     _Pragma("unroll") for (int m = 0; m < 4; ++m) _Pragma("unroll") for (int n = 0; n < 2; ++n) _Pragma("unroll") for (int k = 0; k < 2; ++k) \
;       acc[ai][bj][m][n] = MFMA16(Bt_[n][k], At_[m][k], acc[ai][bj][m][n]); \
;     __builtin_amdgcn_s_setprio(0); } while (0)
; #define WAIT_V(n) asm volatile("s_waitcnt vmcnt(" #n ")" ::: "memory")
; #define WAIT_L(n) asm volatile("s_waitcnt lgkmcnt(" #n ")" ::: "memory")
; #define BAR __builtin_amdgcn_s_barrier()
; #define SCHED __builtin_amdgcn_sched_barrier(0)
; template <class FL, class FS>
; DI void gemm8_tile(char* shmc, const bf16_t* __restrict__ A, const bf16_t* __restrict__ Bt, const int K, const int brow, const int bcol, FL fl, FS fs) {
;     ...
;     BAR; WAIT_L(0); MMA(1, 0, At, B0); BAR; SCHED;
;     STAGE(SB(1, 1), Bt, bcol + HALF, t + 3);
;     WAIT_V(6); BAR; MMA(1, 1, At, B1); BAR;
;   }
;   { LDB(B0, 0, 0); LDA(At, 0, 0); STAGE(SA(1, 1), A, brow + HALF, nt - 1);
;     BAR; WAIT_L(0); MMA(0, 0, At, B0); BAR;
	s_waitcnt lgkmcnt(0)
	s_setprio 1
	s_waitcnt lgkmcnt(0)
	v_mfma_f32_16x16x32_bf16 v[60:63], v[172:175], v[192:195], v[60:63]
	v_mfma_f32_16x16x32_bf16 v[56:59], v[184:187], v[192:195], v[56:59]
	v_mfma_f32_16x16x32_bf16 v[52:55], v[172:175], v[200:203], v[52:55]
	v_mfma_f32_16x16x32_bf16 v[48:51], v[184:187], v[200:203], v[48:51]
	v_mfma_f32_16x16x32_bf16 v[44:47], v[172:175], v[208:211], v[44:47]
	v_mfma_f32_16x16x32_bf16 v[40:43], v[184:187], v[208:211], v[40:43]
	v_mfma_f32_16x16x32_bf16 v[36:39], v[172:175], v[216:219], v[36:39]
	v_mfma_f32_16x16x32_bf16 v[32:35], v[184:187], v[216:219], v[32:35]
	v_mfma_f32_16x16x32_bf16 v[60:63], v[176:179], v[196:199], v[60:63]
	v_mfma_f32_16x16x32_bf16 v[56:59], v[188:191], v[196:199], v[56:59]
	v_mfma_f32_16x16x32_bf16 v[52:55], v[176:179], v[204:207], v[52:55]
	v_mfma_f32_16x16x32_bf16 v[48:51], v[188:191], v[204:207], v[48:51]
	v_mfma_f32_16x16x32_bf16 v[44:47], v[176:179], v[212:215], v[44:47]
	v_mfma_f32_16x16x32_bf16 v[40:43], v[188:191], v[212:215], v[40:43]
	v_mfma_f32_16x16x32_bf16 v[36:39], v[176:179], v[220:223], v[36:39]
	v_mfma_f32_16x16x32_bf16 v[32:35], v[188:191], v[220:223], v[32:35]
	s_setprio 0
	s_barrier
	v_readfirstlane_b32 s1, v165
	v_lshl_add_u64 v[172:173], v[242:243], 0, s[38:39]
	s_mov_b32 m0, s1
	v_readfirstlane_b32 s1, v167
	global_load_lds_dwordx4 v[172:173], off
	v_lshl_add_u64 v[172:173], v[244:245], 0, s[38:39]
	s_mov_b32 m0, s1
	s_nop 0
	global_load_lds_dwordx4 v[172:173], off
	s_waitcnt vmcnt(6)
	s_barrier
	s_setprio 1
	v_mfma_f32_16x16x32_bf16 v[28:31], v[224:227], v[192:195], v[28:31]
	v_mfma_f32_16x16x32_bf16 v[24:27], v[232:235], v[192:195], v[24:27]
	v_mfma_f32_16x16x32_bf16 v[20:23], v[224:227], v[200:203], v[20:23]
	v_mfma_f32_16x16x32_bf16 v[16:19], v[232:235], v[200:203], v[16:19]
	v_mfma_f32_16x16x32_bf16 v[12:15], v[224:227], v[208:211], v[12:15]
	v_mfma_f32_16x16x32_bf16 v[8:11], v[232:235], v[208:211], v[8:11]
	v_mfma_f32_16x16x32_bf16 v[4:7], v[224:227], v[216:219], v[4:7]
	v_mfma_f32_16x16x32_bf16 v[0:3], v[232:235], v[216:219], v[0:3]
	v_mfma_f32_16x16x32_bf16 v[28:31], v[228:231], v[196:199], v[28:31]
	v_mfma_f32_16x16x32_bf16 v[24:27], v[236:239], v[196:199], v[24:27]
	v_mfma_f32_16x16x32_bf16 v[20:23], v[228:231], v[204:207], v[20:23]
	v_mfma_f32_16x16x32_bf16 v[16:19], v[236:239], v[204:207], v[16:19]
	v_mfma_f32_16x16x32_bf16 v[12:15], v[228:231], v[212:215], v[12:15]
	v_mfma_f32_16x16x32_bf16 v[8:11], v[236:239], v[212:215], v[8:11]
	v_mfma_f32_16x16x32_bf16 v[4:7], v[228:231], v[220:223], v[4:7]
	v_mfma_f32_16x16x32_bf16 v[0:3], v[236:239], v[220:223], v[0:3]
	s_setprio 0
	s_add_i32 s0, s0, 2
	v_lshl_add_u64 v[134:135], v[134:135], 0, s[24:25]
	v_lshl_add_u64 v[136:137], v[136:137], 0, s[24:25]
	v_lshl_add_u64 v[138:139], v[138:139], 0, s[24:25]
	s_cmp_lt_u32 s0, 12
	v_lshl_add_u64 v[140:141], v[140:141], 0, s[24:25]
	s_barrier
	s_cbranch_scc1 .LBB0_202
	v_readfirstlane_b32 s0, v169
	v_lshl_add_u64 v[130:131], v[130:131], 0, s[40:41]
	s_mov_b32 m0, s0
	v_readfirstlane_b32 s0, v168
	ds_read_b128 v[134:137], v170
	ds_read_b128 v[138:141], v170 offset:1024
	ds_read_b128 v[158:161], v170 offset:2048
	ds_read_b128 v[162:165], v170 offset:3072
	ds_read_b128 v[170:173], v152
	ds_read_b128 v[174:177], v152 offset:1024
	ds_read_b128 v[178:181], v151
	ds_read_b128 v[184:187], v151 offset:1024
	ds_read_b128 v[188:191], v150
	ds_read_b128 v[192:195], v150 offset:1024
	ds_read_b128 v[196:199], v148
	ds_read_b128 v[200:203], v148 offset:1024
	global_load_lds_dwordx4 v[130:131], off
	v_lshl_add_u64 v[130:131], v[132:133], 0, s[40:41]
	s_mov_b32 m0, s0
	s_nop 0
	global_load_lds_dwordx4 v[130:131], off
	s_barrier
	s_waitcnt lgkmcnt(0)
	s_setprio 1
	s_waitcnt lgkmcnt(0)
	v_mfma_f32_16x16x32_bf16 v[124:127], v[134:137], v[170:173], v[124:127]
	v_mfma_f32_16x16x32_bf16 v[120:123], v[158:161], v[170:173], v[120:123]
	v_mfma_f32_16x16x32_bf16 v[116:119], v[134:137], v[178:181], v[116:119]
	v_mfma_f32_16x16x32_bf16 v[112:115], v[158:161], v[178:181], v[112:115]
	v_mfma_f32_16x16x32_bf16 v[100:103], v[134:137], v[196:199], v[100:103]
	v_mfma_f32_16x16x32_bf16 v[96:99], v[158:161], v[196:199], v[96:99]
	v_mfma_f32_16x16x32_bf16 v[124:127], v[138:141], v[174:177], v[124:127]
	v_mfma_f32_16x16x32_bf16 v[120:123], v[162:165], v[174:177], v[120:123]
	v_mfma_f32_16x16x32_bf16 v[116:119], v[138:141], v[184:187], v[116:119]
	v_mfma_f32_16x16x32_bf16 v[112:115], v[162:165], v[184:187], v[112:115]
	v_mfma_f32_16x16x32_bf16 v[108:111], v[134:137], v[188:191], v[108:111]
	v_mfma_f32_16x16x32_bf16 v[104:107], v[158:161], v[188:191], v[104:107]
	v_mfma_f32_16x16x32_bf16 v[100:103], v[138:141], v[200:203], v[100:103]
	v_mfma_f32_16x16x32_bf16 v[96:99], v[162:165], v[200:203], v[96:99]
	v_mfma_f32_16x16x32_bf16 v[130:133], v[138:141], v[192:195], v[108:111]
	v_mfma_f32_16x16x32_bf16 v[204:207], v[162:165], v[192:195], v[104:107]
	s_setprio 0
	s_barrier
	s_nop 0
	ds_read_b128 v[104:107], v166
	ds_read_b128 v[108:111], v166 offset:1024
	ds_read_b128 v[208:211], v166 offset:2048
	ds_read_b128 v[166:169], v166 offset:3072
	s_barrier
; #define LDA(dst, b, h) _Pragma("unroll") for (int m = 0; m < 4; ++m) _Pragma("unroll") for (int k = 0; k < 2; ++k) \
;     dst[m][k] = *reinterpret_cast<const bf16x8*>((const char*)SA(b, h) + lds_byte8(wr * 64 + m * 16 + fr, k * 32 + fq * 8))
; #define LDB(dst, b, h) _Pragma("unroll") for (int n = 0; n < 2; ++n) _Pragma("unroll") for (int k = 0; k < 2; ++k) \
;     dst[n][k] = *reinterpret_cast<const bf16x8*>((const char*)SB(b, h) + lds_byte8(wc * 32 + n * 16 + fr, k * 32 + fq * 8))
; #define MMA(ai, bj, At_, Bt_) do { __builtin_amdgcn_s_setprio(1); \
;     _Pragma("unroll") for (int m = 0; m < 4; ++m) _Pragma("unroll") for (int n = 0; n < 2; ++n) _Pragma("unroll") for (int k = 0; k < 2; ++k) \
;       acc[ai][bj][m][n] = MFMA16(Bt_[n][k], At_[m][k], acc[ai][bj][m][n]); \
;     __builtin_amdgcn_s_setprio(0); } while (0)
; #define WAIT_V(n) asm volatile("s_waitcnt vmcnt(" #n ")" ::: "memory")
; #define WAIT_L(n) asm volatile("s_waitcnt lgkmcnt(" #n ")" ::: "memory")
; #define BAR __builtin_amdgcn_s_barrier()
; template <class FL, class FS>
; DI void gemm8_tile(char* shmc, const bf16_t* __restrict__ A, const bf16_t* __restrict__ Bt, const int K, const int brow, const int bcol, FL fl, FS fs) {
;     ...
;     BAR; WAIT_L(0); MMA(0, 0, At, B0); BAR;
;     LDB(B1, 0, 1); BAR; WAIT_L(0); MMA(0, 1, At, B1); BAR;
;     LDA(At, 0, 1); WAIT_V(4); BAR; WAIT_L(0); MMA(1, 0, At, B0); MMA(1, 1, At, B1); BAR; }
;   { LDB(B0, 1, 0); LDA(At, 1, 0); WAIT_V(2); BAR; WAIT_L(0); MMA(0, 0, At, B0); BAR;
	s_waitcnt lgkmcnt(0)
	s_setprio 1
	s_waitcnt lgkmcnt(3)
	v_mfma_f32_16x16x32_bf16 v[84:87], v[104:107], v[178:181], v[84:87]
	s_waitcnt lgkmcnt(1)
	v_mfma_f32_16x16x32_bf16 v[80:83], v[208:211], v[178:181], v[80:83]
	v_mfma_f32_16x16x32_bf16 v[68:71], v[104:107], v[196:199], v[68:71]
	v_mfma_f32_16x16x32_bf16 v[64:67], v[208:211], v[196:199], v[64:67]
	v_mfma_f32_16x16x32_bf16 v[92:95], v[104:107], v[170:173], v[92:95]
	v_mfma_f32_16x16x32_bf16 v[88:91], v[208:211], v[170:173], v[88:91]
	v_mfma_f32_16x16x32_bf16 v[84:87], v[108:111], v[184:187], v[84:87]
	s_waitcnt lgkmcnt(0)
	v_mfma_f32_16x16x32_bf16 v[80:83], v[166:169], v[184:187], v[80:83]
	v_mfma_f32_16x16x32_bf16 v[76:79], v[104:107], v[188:191], v[76:79]
	v_mfma_f32_16x16x32_bf16 v[72:75], v[208:211], v[188:191], v[72:75]
	v_mfma_f32_16x16x32_bf16 v[68:71], v[108:111], v[200:203], v[68:71]
	v_mfma_f32_16x16x32_bf16 v[64:67], v[166:169], v[200:203], v[64:67]
	v_mfma_f32_16x16x32_bf16 v[212:215], v[108:111], v[174:177], v[92:95]
	v_mfma_f32_16x16x32_bf16 v[170:173], v[166:169], v[174:177], v[88:91]
	v_mfma_f32_16x16x32_bf16 v[174:177], v[108:111], v[192:195], v[76:79]
	v_mfma_f32_16x16x32_bf16 v[178:181], v[166:169], v[192:195], v[72:75]
	s_setprio 0
	s_barrier
	s_nop 0
	ds_read_b128 v[72:75], v152 offset:16384
	ds_read_b128 v[76:79], v152 offset:17408
	ds_read_b128 v[88:91], v151 offset:16384
	ds_read_b128 v[92:95], v151 offset:17408
	ds_read_b128 v[184:187], v150 offset:16384
	ds_read_b128 v[188:191], v150 offset:17408
	ds_read_b128 v[192:195], v148 offset:16384
	ds_read_b128 v[196:199], v148 offset:17408
	s_waitcnt vmcnt(4)
	s_barrier
	s_waitcnt lgkmcnt(0)
	s_setprio 1
	s_waitcnt lgkmcnt(7)
	v_mfma_f32_16x16x32_bf16 v[60:63], v[134:137], v[72:75], v[60:63]
	v_mfma_f32_16x16x32_bf16 v[56:59], v[158:161], v[72:75], v[56:59]
	s_waitcnt lgkmcnt(5)
	v_mfma_f32_16x16x32_bf16 v[52:55], v[134:137], v[88:91], v[52:55]
	v_mfma_f32_16x16x32_bf16 v[48:51], v[158:161], v[88:91], v[48:51]
	s_waitcnt lgkmcnt(1)
	v_mfma_f32_16x16x32_bf16 v[36:39], v[134:137], v[192:195], v[36:39]
	v_mfma_f32_16x16x32_bf16 v[32:35], v[158:161], v[192:195], v[32:35]
	v_mfma_f32_16x16x32_bf16 v[60:63], v[138:141], v[76:79], v[60:63]
	v_mfma_f32_16x16x32_bf16 v[56:59], v[162:165], v[76:79], v[56:59]
	v_mfma_f32_16x16x32_bf16 v[52:55], v[138:141], v[92:95], v[52:55]
	v_mfma_f32_16x16x32_bf16 v[48:51], v[162:165], v[92:95], v[48:51]
	v_mfma_f32_16x16x32_bf16 v[44:47], v[134:137], v[184:187], v[44:47]
	v_mfma_f32_16x16x32_bf16 v[40:43], v[158:161], v[184:187], v[40:43]
	s_waitcnt lgkmcnt(0)
	v_mfma_f32_16x16x32_bf16 v[36:39], v[138:141], v[196:199], v[36:39]
	v_mfma_f32_16x16x32_bf16 v[32:35], v[162:165], v[196:199], v[32:35]
	v_mfma_f32_16x16x32_bf16 v[200:203], v[138:141], v[188:191], v[44:47]
	v_mfma_f32_16x16x32_bf16 v[216:219], v[162:165], v[188:191], v[40:43]
	s_setprio 0
	s_setprio 1
	v_mfma_f32_16x16x32_bf16 v[20:23], v[104:107], v[88:91], v[20:23]
	v_mfma_f32_16x16x32_bf16 v[16:19], v[208:211], v[88:91], v[16:19]
	v_mfma_f32_16x16x32_bf16 v[4:7], v[104:107], v[192:195], v[4:7]
	v_mfma_f32_16x16x32_bf16 v[0:3], v[208:211], v[192:195], v[0:3]
	v_mfma_f32_16x16x32_bf16 v[28:31], v[104:107], v[72:75], v[28:31]
	v_mfma_f32_16x16x32_bf16 v[24:27], v[208:211], v[72:75], v[24:27]
	v_mfma_f32_16x16x32_bf16 v[20:23], v[108:111], v[92:95], v[20:23]
	v_mfma_f32_16x16x32_bf16 v[16:19], v[166:169], v[92:95], v[16:19]
	v_mfma_f32_16x16x32_bf16 v[12:15], v[104:107], v[184:187], v[12:15]
	v_mfma_f32_16x16x32_bf16 v[8:11], v[208:211], v[184:187], v[8:11]
	v_mfma_f32_16x16x32_bf16 v[4:7], v[108:111], v[196:199], v[4:7]
	v_mfma_f32_16x16x32_bf16 v[0:3], v[166:169], v[196:199], v[0:3]
	v_mfma_f32_16x16x32_bf16 v[134:137], v[108:111], v[76:79], v[28:31]
	v_mfma_f32_16x16x32_bf16 v[138:141], v[166:169], v[76:79], v[24:27]
	v_mfma_f32_16x16x32_bf16 v[158:161], v[108:111], v[188:191], v[12:15]
	v_mfma_f32_16x16x32_bf16 v[162:165], v[166:169], v[188:191], v[8:11]
	s_setprio 0
	s_barrier
	s_nop 0
	ds_read_b128 v[8:11], v156
	ds_read_b128 v[12:15], v156 offset:1024
	ds_read_b128 v[166:169], v156 offset:2048
	ds_read_b128 v[184:187], v156 offset:3072
	ds_read_b128 v[24:27], v152 offset:32768
	ds_read_b128 v[28:31], v152 offset:33792
	ds_read_b128 v[40:43], v151 offset:32768
	ds_read_b128 v[44:47], v151 offset:33792
	ds_read_b128 v[188:191], v150 offset:32768
	ds_read_b128 v[192:195], v150 offset:33792
	ds_read_b128 v[196:199], v148 offset:32768
	ds_read_b128 v[208:211], v148 offset:33792
	s_waitcnt vmcnt(2)
	s_barrier
; #define LDA(dst, b, h) _Pragma("unroll") for (int m = 0; m < 4; ++m) _Pragma("unroll") for (int k = 0; k < 2; ++k) \
;     dst[m][k] = *reinterpret_cast<const bf16x8*>((const char*)SA(b, h) + lds_byte8(wr * 64 + m * 16 + fr, k * 32 + fq * 8))
; #define LDB(dst, b, h) _Pragma("unroll") for (int n = 0; n < 2; ++n) _Pragma("unroll") for (int k = 0; k < 2; ++k) \
;     dst[n][k] = *reinterpret_cast<const bf16x8*>((const char*)SB(b, h) + lds_byte8(wc * 32 + n * 16 + fr, k * 32 + fq * 8))
; #define MMA(ai, bj, At_, Bt_) do { __builtin_amdgcn_s_setprio(1); \
;     _Pragma("unroll") for (int m = 0; m < 4; ++m) _Pragma("unroll") for (int n = 0; n < 2; ++n) _Pragma("unroll") for (int k = 0; k < 2; ++k) \
;       acc[ai][bj][m][n] = MFMA16(Bt_[n][k], At_[m][k], acc[ai][bj][m][n]); \
;     __builtin_amdgcn_s_setprio(0); } while (0)
; #define WAIT_V(n) asm volatile("s_waitcnt vmcnt(" #n ")" ::: "memory")
; #define WAIT_L(n) asm volatile("s_waitcnt lgkmcnt(" #n ")" ::: "memory")
; #define BAR __builtin_amdgcn_s_barrier()
; template <class FL, class FS>
; DI void gemm8_tile(char* shmc, const bf16_t* __restrict__ A, const bf16_t* __restrict__ Bt, const int K, const int brow, const int bcol, FL fl, FS fs) {
;     ...
;   { LDB(B0, 1, 0); LDA(At, 1, 0); WAIT_V(2); BAR; WAIT_L(0); MMA(0, 0, At, B0); BAR;
;     LDB(B1, 1, 1); WAIT_V(0); BAR; WAIT_L(0); MMA(0, 1, At, B1); BAR;
;     LDA(At, 1, 1); BAR; WAIT_L(0); MMA(1, 0, At, B0); MMA(1, 1, At, B1); BAR; }
;   if (wr == 0) BAR;
	s_waitcnt lgkmcnt(0)
	s_setprio 1
	s_waitcnt lgkmcnt(7)
	v_mfma_f32_16x16x32_bf16 v[72:75], v[8:11], v[24:27], v[124:127]
	s_waitcnt lgkmcnt(6)
	v_mfma_f32_16x16x32_bf16 v[124:127], v[12:15], v[28:31], v[72:75]
	v_mfma_f32_16x16x32_bf16 v[72:75], v[166:169], v[24:27], v[120:123]
	v_mfma_f32_16x16x32_bf16 v[120:123], v[184:187], v[28:31], v[72:75]
	s_waitcnt lgkmcnt(5)
	v_mfma_f32_16x16x32_bf16 v[72:75], v[8:11], v[40:43], v[116:119]
	s_waitcnt lgkmcnt(4)
	v_mfma_f32_16x16x32_bf16 v[108:111], v[12:15], v[44:47], v[72:75]
	v_mfma_f32_16x16x32_bf16 v[72:75], v[166:169], v[40:43], v[112:115]
	v_mfma_f32_16x16x32_bf16 v[104:107], v[184:187], v[44:47], v[72:75]
	s_waitcnt lgkmcnt(3)
	v_mfma_f32_16x16x32_bf16 v[72:75], v[8:11], v[188:191], v[130:133]
	s_waitcnt lgkmcnt(2)
	v_mfma_f32_16x16x32_bf16 v[92:95], v[12:15], v[192:195], v[72:75]
	v_mfma_f32_16x16x32_bf16 v[72:75], v[166:169], v[188:191], v[204:207]
	v_mfma_f32_16x16x32_bf16 v[88:91], v[184:187], v[192:195], v[72:75]
	s_waitcnt lgkmcnt(1)
	v_mfma_f32_16x16x32_bf16 v[72:75], v[8:11], v[196:199], v[100:103]
	s_waitcnt lgkmcnt(0)
	v_mfma_f32_16x16x32_bf16 v[76:79], v[12:15], v[208:211], v[72:75]
	v_mfma_f32_16x16x32_bf16 v[72:75], v[166:169], v[196:199], v[96:99]
	v_mfma_f32_16x16x32_bf16 v[72:75], v[184:187], v[208:211], v[72:75]
	s_setprio 0
	s_barrier
	ds_read_b128 v[130:133], v154
	ds_read_b128 v[204:207], v154 offset:1024
	ds_read_b128 v[220:223], v154 offset:2048
	ds_read_b128 v[154:157], v154 offset:3072
	s_waitcnt vmcnt(0)
	s_barrier
	s_waitcnt lgkmcnt(0)
	s_setprio 1
	s_waitcnt lgkmcnt(3)
	v_mfma_f32_16x16x32_bf16 v[96:99], v[130:133], v[24:27], v[212:215]
	s_waitcnt lgkmcnt(1)
	v_mfma_f32_16x16x32_bf16 v[24:27], v[220:223], v[24:27], v[170:173]
	s_waitcnt lgkmcnt(0)
	v_mfma_f32_16x16x32_bf16 v[112:115], v[154:157], v[28:31], v[24:27]
	v_mfma_f32_16x16x32_bf16 v[24:27], v[130:133], v[40:43], v[84:87]
	v_mfma_f32_16x16x32_bf16 v[100:103], v[204:207], v[44:47], v[24:27]
	v_mfma_f32_16x16x32_bf16 v[24:27], v[220:223], v[40:43], v[80:83]
	v_mfma_f32_16x16x32_bf16 v[116:119], v[204:207], v[28:31], v[96:99]
	v_mfma_f32_16x16x32_bf16 v[96:99], v[154:157], v[44:47], v[24:27]
	v_mfma_f32_16x16x32_bf16 v[24:27], v[130:133], v[188:191], v[174:177]
	v_mfma_f32_16x16x32_bf16 v[84:87], v[204:207], v[192:195], v[24:27]
	v_mfma_f32_16x16x32_bf16 v[24:27], v[220:223], v[188:191], v[178:181]
	v_mfma_f32_16x16x32_bf16 v[80:83], v[154:157], v[192:195], v[24:27]
	v_mfma_f32_16x16x32_bf16 v[24:27], v[130:133], v[196:199], v[68:71]
	v_mfma_f32_16x16x32_bf16 v[68:71], v[204:207], v[208:211], v[24:27]
	v_mfma_f32_16x16x32_bf16 v[24:27], v[220:223], v[196:199], v[64:67]
	v_mfma_f32_16x16x32_bf16 v[64:67], v[154:157], v[208:211], v[24:27]
	s_setprio 0
	s_barrier
	ds_read_b128 v[170:173], v152 offset:49152
	ds_read_b128 v[174:177], v152 offset:50176
	ds_read_b128 v[178:181], v151 offset:49152
	ds_read_b128 v[188:191], v151 offset:50176
	ds_read_b128 v[192:195], v150 offset:49152
	ds_read_b128 v[150:153], v150 offset:50176
	ds_read_b128 v[196:199], v148 offset:49152
	ds_read_b128 v[208:211], v148 offset:50176
	s_barrier
	s_waitcnt lgkmcnt(0)
	s_setprio 1
	s_waitcnt lgkmcnt(7)
	v_mfma_f32_16x16x32_bf16 v[24:27], v[8:11], v[170:173], v[60:63]
	s_waitcnt lgkmcnt(6)
	v_mfma_f32_16x16x32_bf16 v[60:63], v[12:15], v[174:177], v[24:27]
	v_mfma_f32_16x16x32_bf16 v[24:27], v[166:169], v[170:173], v[56:59]
	v_mfma_f32_16x16x32_bf16 v[56:59], v[184:187], v[174:177], v[24:27]
	s_waitcnt lgkmcnt(5)
	v_mfma_f32_16x16x32_bf16 v[24:27], v[8:11], v[178:181], v[52:55]
	s_waitcnt lgkmcnt(4)
	v_mfma_f32_16x16x32_bf16 v[44:47], v[12:15], v[188:191], v[24:27]
	v_mfma_f32_16x16x32_bf16 v[24:27], v[166:169], v[178:181], v[48:51]
	v_mfma_f32_16x16x32_bf16 v[40:43], v[184:187], v[188:191], v[24:27]
	s_waitcnt lgkmcnt(3)
	v_mfma_f32_16x16x32_bf16 v[24:27], v[8:11], v[192:195], v[200:203]
	s_waitcnt lgkmcnt(1)
	v_mfma_f32_16x16x32_bf16 v[8:11], v[8:11], v[196:199], v[36:39]
	v_mfma_f32_16x16x32_bf16 v[28:31], v[12:15], v[150:153], v[24:27]
	v_mfma_f32_16x16x32_bf16 v[24:27], v[166:169], v[192:195], v[216:219]
	s_waitcnt lgkmcnt(0)
	v_mfma_f32_16x16x32_bf16 v[12:15], v[12:15], v[208:211], v[8:11]
	v_mfma_f32_16x16x32_bf16 v[8:11], v[166:169], v[196:199], v[32:35]
	v_mfma_f32_16x16x32_bf16 v[24:27], v[184:187], v[150:153], v[24:27]
	v_mfma_f32_16x16x32_bf16 v[8:11], v[184:187], v[208:211], v[8:11]
	s_setprio 0
	s_setprio 1
	v_mfma_f32_16x16x32_bf16 v[32:35], v[130:133], v[170:173], v[134:137]
	v_mfma_f32_16x16x32_bf16 v[52:55], v[204:207], v[174:177], v[32:35]
	v_mfma_f32_16x16x32_bf16 v[32:35], v[220:223], v[170:173], v[138:141]
	v_mfma_f32_16x16x32_bf16 v[16:19], v[220:223], v[178:181], v[16:19]
	v_mfma_f32_16x16x32_bf16 v[48:51], v[154:157], v[174:177], v[32:35]
	v_mfma_f32_16x16x32_bf16 v[20:23], v[130:133], v[178:181], v[20:23]
	v_mfma_f32_16x16x32_bf16 v[32:35], v[154:157], v[188:191], v[16:19]
	v_mfma_f32_16x16x32_bf16 v[16:19], v[130:133], v[192:195], v[158:161]
	v_mfma_f32_16x16x32_bf16 v[36:39], v[204:207], v[188:191], v[20:23]
	v_mfma_f32_16x16x32_bf16 v[20:23], v[204:207], v[150:153], v[16:19]
	v_mfma_f32_16x16x32_bf16 v[16:19], v[220:223], v[192:195], v[162:165]
	v_mfma_f32_16x16x32_bf16 v[4:7], v[130:133], v[196:199], v[4:7]
	v_mfma_f32_16x16x32_bf16 v[0:3], v[220:223], v[196:199], v[0:3]
	v_mfma_f32_16x16x32_bf16 v[16:19], v[154:157], v[150:153], v[16:19]
	v_mfma_f32_16x16x32_bf16 v[4:7], v[204:207], v[208:211], v[4:7]
	v_mfma_f32_16x16x32_bf16 v[0:3], v[154:157], v[208:211], v[0:3]
	s_setprio 0
	v_cmp_gt_u32_e32 vcc, s48, v128
	s_barrier
	s_and_saveexec_b64 s[0:1], vcc
	s_cbranch_execz .LBB0_205
	s_barrier

; #define STAGE(P, BASE, br, kt) do { const long _g = (long)(br) * K + (long)(kt) * 64; \
;     _Pragma("unroll") for (int _i = 0; _i < 2; ++_i) { const int _b = tidx * 16 + _i * 8192; int _r, _c; stage_rc8(_b, _r, _c); \
;       __builtin_amdgcn_global_load_lds((const unsigned*)(BASE + _g + (long)_r * K + _c), (LAS unsigned*)((LAS char*)(P) + _b), 16, 0, 0); } } while (0)
; #define LDA(dst, b, h) _Pragma("unroll") for (int m = 0; m < 4; ++m) _Pragma("unroll") for (int k = 0; k < 2; ++k) \
;     dst[m][k] = *reinterpret_cast<const bf16x8*>((const char*)SA(b, h) + lds_byte8(wr * 64 + m * 16 + fr, k * 32 + fq * 8))
; #define LDB(dst, b, h) _Pragma("unroll") for (int n = 0; n < 2; ++n) _Pragma("unroll") for (int k = 0; k < 2; ++k) \
;     dst[n][k] = *reinterpret_cast<const bf16x8*>((const char*)SB(b, h) + lds_byte8(wc * 32 + n * 16 + fr, k * 32 + fq * 8))
; #define MMA(ai, bj, At_, Bt_) do { __builtin_amdgcn_s_setprio(1); \
;     _Pragma("unroll") for (int m = 0; m < 4; ++m) _Pragma("unroll") for (int n = 0; n < 2; ++n) _Pragma("unroll") for (int k = 0; k < 2; ++k) \
;       acc[ai][bj][m][n] = MFMA16(Bt_[n][k], At_[m][k], acc[ai][bj][m][n]); \
;     __builtin_amdgcn_s_setprio(0); } while (0)
; #define WAIT_V(n) asm volatile("s_waitcnt vmcnt(" #n ")" ::: "memory")
; #define WAIT_L(n) asm volatile("s_waitcnt lgkmcnt(" #n ")" ::: "memory")
; #define BAR __builtin_amdgcn_s_barrier()
; #define SCHED __builtin_amdgcn_sched_barrier(0)
; template <class FL, class FS>
; DI void gemm8_tile(char* shmc, const bf16_t* __restrict__ A, const bf16_t* __restrict__ Bt, const int K, const int brow, const int bcol, FL fl, FS fs) {
;     ...
;     LDB(B0, 0, 0); SCHED; LDA(At, 0, 0); STAGE(SA(1, 1), A, brow + HALF, t + 1);
;     WAIT_L(8); BAR; WAIT_L(0); MMA(0, 0, At, B0); BAR; SCHED;
;     LDB(B1, 0, 1); STAGE(SB(0, 0), Bt, bcol, t + 2);
;     BAR; WAIT_L(0); MMA(0, 1, At, B1); BAR;
;     LDA(At, 0, 1); STAGE(SA(0, 0), A, brow, t + 2);
;     BAR; WAIT_L(0); MMA(1, 0, At, B0); BAR; SCHED;
;     STAGE(SB(0, 1), Bt, bcol + HALF, t + 2);
;     WAIT_V(6); BAR; MMA(1, 1, At, B1); BAR;
.Lg2_p1skip:
	s_nop 0
	s_barrier
	s_waitcnt lgkmcnt(0)
	s_setprio 1
	s_waitcnt lgkmcnt(0)
	v_mfma_f32_16x16x32_bf16 v[124:127], v[170:173], v[190:193], v[124:127]
	v_mfma_f32_16x16x32_bf16 v[120:123], v[178:181], v[190:193], v[120:123]
	v_mfma_f32_16x16x32_bf16 v[116:119], v[170:173], v[198:201], v[116:119]
	v_mfma_f32_16x16x32_bf16 v[112:115], v[178:181], v[198:201], v[112:115]
	v_mfma_f32_16x16x32_bf16 v[108:111], v[170:173], v[206:209], v[108:111]
	v_mfma_f32_16x16x32_bf16 v[104:107], v[178:181], v[206:209], v[104:107]
	v_mfma_f32_16x16x32_bf16 v[100:103], v[170:173], v[214:217], v[100:103]
	v_mfma_f32_16x16x32_bf16 v[96:99], v[178:181], v[214:217], v[96:99]
	v_mfma_f32_16x16x32_bf16 v[124:127], v[174:177], v[194:197], v[124:127]
	v_mfma_f32_16x16x32_bf16 v[120:123], v[186:189], v[194:197], v[120:123]
	v_mfma_f32_16x16x32_bf16 v[116:119], v[174:177], v[202:205], v[116:119]
	v_mfma_f32_16x16x32_bf16 v[112:115], v[186:189], v[202:205], v[112:115]
	v_mfma_f32_16x16x32_bf16 v[108:111], v[174:177], v[210:213], v[108:111]
	v_mfma_f32_16x16x32_bf16 v[104:107], v[186:189], v[210:213], v[104:107]
	v_mfma_f32_16x16x32_bf16 v[100:103], v[174:177], v[218:221], v[100:103]
	v_mfma_f32_16x16x32_bf16 v[96:99], v[186:189], v[218:221], v[96:99]
	s_setprio 0
	s_barrier
	v_lshl_add_u64 v[242:243], s[4:5], 0, v[132:133]
	v_readfirstlane_b32 s1, v141
	v_lshl_add_u64 v[244:245], v[242:243], 0, s[20:21]
	s_mov_b32 m0, s1
	ds_read_b128 v[222:225], v164
	ds_read_b128 v[226:229], v164 offset:1024
	ds_read_b128 v[230:233], v164 offset:2048
	ds_read_b128 v[234:237], v164 offset:3072
	global_load_lds_dwordx4 v[244:245], off
	v_lshl_add_u64 v[244:245], s[4:5], 0, v[134:135]
	v_readfirstlane_b32 s1, v143
	v_lshl_add_u64 v[246:247], v[244:245], 0, s[20:21]
	s_mov_b32 m0, s1
	s_nop 0
	global_load_lds_dwordx4 v[246:247], off
	s_barrier
	s_waitcnt lgkmcnt(0)
	s_setprio 1
	s_waitcnt lgkmcnt(0)
	v_mfma_f32_16x16x32_bf16 v[92:95], v[222:225], v[190:193], v[92:95]
	v_mfma_f32_16x16x32_bf16 v[88:91], v[230:233], v[190:193], v[88:91]
	v_mfma_f32_16x16x32_bf16 v[84:87], v[222:225], v[198:201], v[84:87]
	v_mfma_f32_16x16x32_bf16 v[80:83], v[230:233], v[198:201], v[80:83]
	v_mfma_f32_16x16x32_bf16 v[76:79], v[222:225], v[206:209], v[76:79]
	v_mfma_f32_16x16x32_bf16 v[72:75], v[230:233], v[206:209], v[72:75]
	v_mfma_f32_16x16x32_bf16 v[68:71], v[222:225], v[214:217], v[68:71]
	v_mfma_f32_16x16x32_bf16 v[64:67], v[230:233], v[214:217], v[64:67]
	v_mfma_f32_16x16x32_bf16 v[92:95], v[226:229], v[194:197], v[92:95]
	v_mfma_f32_16x16x32_bf16 v[88:91], v[234:237], v[194:197], v[88:91]
	v_mfma_f32_16x16x32_bf16 v[84:87], v[226:229], v[202:205], v[84:87]
	v_mfma_f32_16x16x32_bf16 v[80:83], v[234:237], v[202:205], v[80:83]
	v_mfma_f32_16x16x32_bf16 v[76:79], v[226:229], v[210:213], v[76:79]
	v_mfma_f32_16x16x32_bf16 v[72:75], v[234:237], v[210:213], v[72:75]
	v_mfma_f32_16x16x32_bf16 v[68:71], v[226:229], v[218:221], v[68:71]
	v_mfma_f32_16x16x32_bf16 v[64:67], v[234:237], v[218:221], v[64:67]
	s_setprio 0
	v_readfirstlane_b32 s1, v140
	v_lshl_add_u64 v[246:247], v[238:239], 0, s[22:23]
	s_mov_b32 m0, s1
	v_readfirstlane_b32 s1, v142
	s_barrier
	ds_read_b128 v[190:193], v152 offset:16384
	ds_read_b128 v[194:197], v152 offset:17408
	ds_read_b128 v[198:201], v151 offset:16384
	ds_read_b128 v[202:205], v151 offset:17408
	ds_read_b128 v[206:209], v150 offset:16384
	ds_read_b128 v[210:213], v150 offset:17408
	ds_read_b128 v[214:217], v149 offset:16384
	ds_read_b128 v[218:221], v149 offset:17408
	global_load_lds_dwordx4 v[246:247], off
	v_lshl_add_u64 v[246:247], v[240:241], 0, s[22:23]
	s_mov_b32 m0, s1
	s_nop 0
	global_load_lds_dwordx4 v[246:247], off
	s_barrier
	s_waitcnt lgkmcnt(0)
	s_setprio 1
	s_waitcnt lgkmcnt(0)
	v_mfma_f32_16x16x32_bf16 v[60:63], v[170:173], v[190:193], v[60:63]
	v_mfma_f32_16x16x32_bf16 v[56:59], v[178:181], v[190:193], v[56:59]
	v_mfma_f32_16x16x32_bf16 v[52:55], v[170:173], v[198:201], v[52:55]
	v_mfma_f32_16x16x32_bf16 v[48:51], v[178:181], v[198:201], v[48:51]
	v_mfma_f32_16x16x32_bf16 v[44:47], v[170:173], v[206:209], v[44:47]
	v_mfma_f32_16x16x32_bf16 v[40:43], v[178:181], v[206:209], v[40:43]
	v_mfma_f32_16x16x32_bf16 v[36:39], v[170:173], v[214:217], v[36:39]
	v_mfma_f32_16x16x32_bf16 v[32:35], v[178:181], v[214:217], v[32:35]
	v_mfma_f32_16x16x32_bf16 v[60:63], v[174:177], v[194:197], v[60:63]
	v_mfma_f32_16x16x32_bf16 v[56:59], v[186:189], v[194:197], v[56:59]
	v_mfma_f32_16x16x32_bf16 v[52:55], v[174:177], v[202:205], v[52:55]
	v_mfma_f32_16x16x32_bf16 v[48:51], v[186:189], v[202:205], v[48:51]
	v_mfma_f32_16x16x32_bf16 v[44:47], v[174:177], v[210:213], v[44:47]
	v_mfma_f32_16x16x32_bf16 v[40:43], v[186:189], v[210:213], v[40:43]
	v_mfma_f32_16x16x32_bf16 v[36:39], v[174:177], v[218:221], v[36:39]
	v_mfma_f32_16x16x32_bf16 v[32:35], v[186:189], v[218:221], v[32:35]
	s_setprio 0
	s_barrier
	v_readfirstlane_b32 s1, v155
	v_lshl_add_u64 v[170:171], v[242:243], 0, s[24:25]
	s_mov_b32 m0, s1
	v_readfirstlane_b32 s1, v156
	global_load_lds_dwordx4 v[170:171], off
	v_lshl_add_u64 v[170:171], v[244:245], 0, s[24:25]
	s_mov_b32 m0, s1
	s_nop 0
	global_load_lds_dwordx4 v[170:171], off
	s_cmp_eq_u32 s0, -2
	s_cselect_b32 s101, s98, 0
	s_cmp_lg_u32 s101, 0
	s_cbranch_scc1 .Lg2_w22
	s_waitcnt vmcnt(6)
; #define STAGE(P, BASE, br, kt) do { const long _g = (long)(br) * K + (long)(kt) * 64; \
;     _Pragma("unroll") for (int _i = 0; _i < 2; ++_i) { const int _b = tidx * 16 + _i * 8192; int _r, _c; stage_rc8(_b, _r, _c); \
;       __builtin_amdgcn_global_load_lds((const unsigned*)(BASE + _g + (long)_r * K + _c), (LAS unsigned*)((LAS char*)(P) + _b), 16, 0, 0); } } while (0)
; #define LDA(dst, b, h) _Pragma("unroll") for (int m = 0; m < 4; ++m) _Pragma("unroll") for (int k = 0; k < 2; ++k) \
;     dst[m][k] = *reinterpret_cast<const bf16x8*>((const char*)SA(b, h) + lds_byte8(wr * 64 + m * 16 + fr, k * 32 + fq * 8))
; #define LDB(dst, b, h) _Pragma("unroll") for (int n = 0; n < 2; ++n) _Pragma("unroll") for (int k = 0; k < 2; ++k) \
;     dst[n][k] = *reinterpret_cast<const bf16x8*>((const char*)SB(b, h) + lds_byte8(wc * 32 + n * 16 + fr, k * 32 + fq * 8))
; #define MMA(ai, bj, At_, Bt_) do { __builtin_amdgcn_s_setprio(1); \
;     _Pragma("unroll") for (int m = 0; m < 4; ++m) _Pragma("unroll") for (int n = 0; n < 2; ++n) _Pragma("unroll") for (int k = 0; k < 2; ++k) \
;       acc[ai][bj][m][n] = MFMA16(Bt_[n][k], At_[m][k], acc[ai][bj][m][n]); \
;     __builtin_amdgcn_s_setprio(0); } while (0)
; #define WAIT_V(n) asm volatile("s_waitcnt vmcnt(" #n ")" ::: "memory")
; #define WAIT_L(n) asm volatile("s_waitcnt lgkmcnt(" #n ")" ::: "memory")
; #define BAR __builtin_amdgcn_s_barrier()
; #define SCHED __builtin_amdgcn_sched_barrier(0)
; template <class FL, class FS>
; DI void gemm8_tile(char* shmc, const bf16_t* __restrict__ A, const bf16_t* __restrict__ Bt, const int K, const int brow, const int bcol, FL fl, FS fs) {
;     ...
;     WAIT_V(6); BAR; MMA(1, 1, At, B1); BAR;
;     LDB(B0, 1, 0); SCHED; LDA(At, 1, 0); STAGE(SA(0, 1), A, brow + HALF, t + 2);
;     WAIT_L(8); BAR; WAIT_L(0); MMA(0, 0, At, B0); BAR; SCHED;
;     LDB(B1, 1, 1); STAGE(SB(1, 0), Bt, bcol, t + 3);
;     BAR; WAIT_L(0); MMA(0, 1, At, B1); BAR;
;     LDA(At, 1, 1); STAGE(SA(1, 0), A, brow, t + 3);
;     BAR; WAIT_L(0); MMA(1, 0, At, B0); BAR; SCHED;
.Lg2_wd:
	s_barrier
	s_setprio 1
	v_mfma_f32_16x16x32_bf16 v[28:31], v[222:225], v[190:193], v[28:31]
	v_mfma_f32_16x16x32_bf16 v[24:27], v[230:233], v[190:193], v[24:27]
	v_mfma_f32_16x16x32_bf16 v[20:23], v[222:225], v[198:201], v[20:23]
	v_mfma_f32_16x16x32_bf16 v[16:19], v[230:233], v[198:201], v[16:19]
	v_mfma_f32_16x16x32_bf16 v[12:15], v[222:225], v[206:209], v[12:15]
	v_mfma_f32_16x16x32_bf16 v[8:11], v[230:233], v[206:209], v[8:11]
	v_mfma_f32_16x16x32_bf16 v[4:7], v[222:225], v[214:217], v[4:7]
	v_mfma_f32_16x16x32_bf16 v[0:3], v[230:233], v[214:217], v[0:3]
	v_mfma_f32_16x16x32_bf16 v[28:31], v[226:229], v[194:197], v[28:31]
	v_mfma_f32_16x16x32_bf16 v[24:27], v[234:237], v[194:197], v[24:27]
	v_mfma_f32_16x16x32_bf16 v[20:23], v[226:229], v[202:205], v[20:23]
	v_mfma_f32_16x16x32_bf16 v[16:19], v[234:237], v[202:205], v[16:19]
	v_mfma_f32_16x16x32_bf16 v[12:15], v[226:229], v[210:213], v[12:15]
	v_mfma_f32_16x16x32_bf16 v[8:11], v[234:237], v[210:213], v[8:11]
	v_mfma_f32_16x16x32_bf16 v[4:7], v[226:229], v[218:221], v[4:7]
	v_mfma_f32_16x16x32_bf16 v[0:3], v[234:237], v[218:221], v[0:3]
	s_setprio 0
	s_barrier
	ds_read_b128 v[170:173], v154
	ds_read_b128 v[174:177], v154 offset:1024
	ds_read_b128 v[178:181], v154 offset:2048
	ds_read_b128 v[186:189], v154 offset:3072
	v_readfirstlane_b32 s1, v157
	v_lshl_add_u64 v[222:223], v[238:239], 0, s[26:27]
	s_mov_b32 m0, s1
	v_readfirstlane_b32 s1, v158
	ds_read_b128 v[190:193], v152 offset:32768
	ds_read_b128 v[194:197], v152 offset:33792
	ds_read_b128 v[198:201], v151 offset:32768
	ds_read_b128 v[202:205], v151 offset:33792
	ds_read_b128 v[206:209], v150 offset:32768
	ds_read_b128 v[210:213], v150 offset:33792
	ds_read_b128 v[214:217], v149 offset:32768
	ds_read_b128 v[218:221], v149 offset:33792
	global_load_lds_dwordx4 v[222:223], off
	v_lshl_add_u64 v[222:223], v[240:241], 0, s[26:27]
	s_mov_b32 m0, s1
	s_nop 0
	global_load_lds_dwordx4 v[222:223], off
	s_nop 0
	s_barrier
	s_waitcnt lgkmcnt(0)
	s_setprio 1
	s_waitcnt lgkmcnt(0)
	v_mfma_f32_16x16x32_bf16 v[124:127], v[170:173], v[190:193], v[124:127]
	v_mfma_f32_16x16x32_bf16 v[120:123], v[178:181], v[190:193], v[120:123]
	v_mfma_f32_16x16x32_bf16 v[116:119], v[170:173], v[198:201], v[116:119]
	v_mfma_f32_16x16x32_bf16 v[112:115], v[178:181], v[198:201], v[112:115]
	v_mfma_f32_16x16x32_bf16 v[108:111], v[170:173], v[206:209], v[108:111]
	v_mfma_f32_16x16x32_bf16 v[104:107], v[178:181], v[206:209], v[104:107]
	v_mfma_f32_16x16x32_bf16 v[100:103], v[170:173], v[214:217], v[100:103]
	v_mfma_f32_16x16x32_bf16 v[96:99], v[178:181], v[214:217], v[96:99]
	v_mfma_f32_16x16x32_bf16 v[124:127], v[174:177], v[194:197], v[124:127]
	v_mfma_f32_16x16x32_bf16 v[120:123], v[186:189], v[194:197], v[120:123]
	v_mfma_f32_16x16x32_bf16 v[116:119], v[174:177], v[202:205], v[116:119]
	v_mfma_f32_16x16x32_bf16 v[112:115], v[186:189], v[202:205], v[112:115]
	v_mfma_f32_16x16x32_bf16 v[108:111], v[174:177], v[210:213], v[108:111]
	v_mfma_f32_16x16x32_bf16 v[104:107], v[186:189], v[210:213], v[104:107]
	v_mfma_f32_16x16x32_bf16 v[100:103], v[174:177], v[218:221], v[100:103]
	v_mfma_f32_16x16x32_bf16 v[96:99], v[186:189], v[218:221], v[96:99]
	s_setprio 0
	s_barrier
	v_readfirstlane_b32 s1, v159
	v_lshl_add_u64 v[246:247], v[242:243], 0, s[28:29]
	s_mov_b32 m0, s1
	v_readfirstlane_b32 s1, v160
	ds_read_b128 v[222:225], v153
	ds_read_b128 v[226:229], v153 offset:1024
	ds_read_b128 v[230:233], v153 offset:2048
	ds_read_b128 v[234:237], v153 offset:3072
	global_load_lds_dwordx4 v[246:247], off
	v_lshl_add_u64 v[246:247], v[244:245], 0, s[28:29]
	s_mov_b32 m0, s1
	s_nop 0
	global_load_lds_dwordx4 v[246:247], off
	s_barrier
	s_waitcnt lgkmcnt(0)
	s_setprio 1
	s_waitcnt lgkmcnt(0)
	v_mfma_f32_16x16x32_bf16 v[92:95], v[222:225], v[190:193], v[92:95]
	v_mfma_f32_16x16x32_bf16 v[88:91], v[230:233], v[190:193], v[88:91]
	v_mfma_f32_16x16x32_bf16 v[84:87], v[222:225], v[198:201], v[84:87]
	v_mfma_f32_16x16x32_bf16 v[80:83], v[230:233], v[198:201], v[80:83]
	v_mfma_f32_16x16x32_bf16 v[76:79], v[222:225], v[206:209], v[76:79]
	v_mfma_f32_16x16x32_bf16 v[72:75], v[230:233], v[206:209], v[72:75]
	v_mfma_f32_16x16x32_bf16 v[68:71], v[222:225], v[214:217], v[68:71]
	v_mfma_f32_16x16x32_bf16 v[64:67], v[230:233], v[214:217], v[64:67]
	v_mfma_f32_16x16x32_bf16 v[92:95], v[226:229], v[194:197], v[92:95]
	v_mfma_f32_16x16x32_bf16 v[88:91], v[234:237], v[194:197], v[88:91]
	v_mfma_f32_16x16x32_bf16 v[84:87], v[226:229], v[202:205], v[84:87]
	v_mfma_f32_16x16x32_bf16 v[80:83], v[234:237], v[202:205], v[80:83]
	v_mfma_f32_16x16x32_bf16 v[76:79], v[226:229], v[210:213], v[76:79]
	v_mfma_f32_16x16x32_bf16 v[72:75], v[234:237], v[210:213], v[72:75]
	v_mfma_f32_16x16x32_bf16 v[68:71], v[226:229], v[218:221], v[68:71]
	v_mfma_f32_16x16x32_bf16 v[64:67], v[234:237], v[218:221], v[64:67]
	s_setprio 0
	v_readfirstlane_b32 s1, v161
	v_lshl_add_u64 v[238:239], v[238:239], 0, s[30:31]
	s_mov_b32 m0, s1
	v_readfirstlane_b32 s1, v162
	s_barrier
	ds_read_b128 v[190:193], v152 offset:49152
	ds_read_b128 v[194:197], v152 offset:50176
	ds_read_b128 v[198:201], v151 offset:49152
	ds_read_b128 v[202:205], v151 offset:50176
	ds_read_b128 v[206:209], v150 offset:49152
	ds_read_b128 v[210:213], v150 offset:50176
	ds_read_b128 v[214:217], v149 offset:49152
	ds_read_b128 v[218:221], v149 offset:50176
	global_load_lds_dwordx4 v[238:239], off
	v_lshl_add_u64 v[238:239], v[240:241], 0, s[30:31]
	s_mov_b32 m0, s1
	s_nop 0
	global_load_lds_dwordx4 v[238:239], off
	s_barrier
; #define STAGE(P, BASE, br, kt) do { const long _g = (long)(br) * K + (long)(kt) * 64; \
;     _Pragma("unroll") for (int _i = 0; _i < 2; ++_i) { const int _b = tidx * 16 + _i * 8192; int _r, _c; stage_rc8(_b, _r, _c); \
;       __builtin_amdgcn_global_load_lds((const unsigned*)(BASE + _g + (long)_r * K + _c), (LAS unsigned*)((LAS char*)(P) + _b), 16, 0, 0); } } while (0)
; #define LDA(dst, b, h) _Pragma("unroll") for (int m = 0; m < 4; ++m) _Pragma("unroll") for (int k = 0; k < 2; ++k) \
;     dst[m][k] = *reinterpret_cast<const bf16x8*>((const char*)SA(b, h) + lds_byte8(wr * 64 + m * 16 + fr, k * 32 + fq * 8))
; #define LDB(dst, b, h) _Pragma("unroll") for (int n = 0; n < 2; ++n) _Pragma("unroll") for (int k = 0; k < 2; ++k) \
;     dst[n][k] = *reinterpret_cast<const bf16x8*>((const char*)SB(b, h) + lds_byte8(wc * 32 + n * 16 + fr, k * 32 + fq * 8))
; #define MMA(ai, bj, At_, Bt_) do { __builtin_amdgcn_s_setprio(1); \
;     _Pragma("unroll") for (int m = 0; m < 4; ++m) _Pragma("unroll") for (int n = 0; n < 2; ++n) _Pragma("unroll") for (int k = 0; k < 2; ++k) \
;       acc[ai][bj][m][n] = MFMA16(Bt_[n][k], At_[m][k], acc[ai][bj][m][n]); \
;     __builtin_amdgcn_s_setprio(0); } while (0)
; #define WAIT_V(n) asm volatile("s_waitcnt vmcnt(" #n ")" ::: "memory")
; #define WAIT_L(n) asm volatile("s_waitcnt lgkmcnt(" #n ")" ::: "memory")
; #define BAR __builtin_amdgcn_s_barrier()
; #define SCHED __builtin_amdgcn_sched_barrier(0)
; template <class FL, class FS>
; DI void gemm8_tile(char* shmc, const bf16_t* __restrict__ A, const bf16_t* __restrict__ Bt, const int K, const int brow, const int bcol, FL fl, FS fs) {
;     ...
;     BAR; WAIT_L(0); MMA(1, 0, At, B0); BAR; SCHED;
;     STAGE(SB(1, 1), Bt, bcol + HALF, t + 3);
;     WAIT_V(6); BAR; MMA(1, 1, At, B1); BAR;
;   }
;   { LDB(B0, 0, 0); LDA(At, 0, 0); STAGE(SA(1, 1), A, brow + HALF, nt - 1);
;     BAR; WAIT_L(0); MMA(0, 0, At, B0); BAR;
	s_waitcnt lgkmcnt(0)
	s_setprio 1
	s_waitcnt lgkmcnt(0)
	v_mfma_f32_16x16x32_bf16 v[60:63], v[170:173], v[190:193], v[60:63]
	v_mfma_f32_16x16x32_bf16 v[56:59], v[178:181], v[190:193], v[56:59]
	v_mfma_f32_16x16x32_bf16 v[52:55], v[170:173], v[198:201], v[52:55]
	v_mfma_f32_16x16x32_bf16 v[48:51], v[178:181], v[198:201], v[48:51]
	v_mfma_f32_16x16x32_bf16 v[44:47], v[170:173], v[206:209], v[44:47]
	v_mfma_f32_16x16x32_bf16 v[40:43], v[178:181], v[206:209], v[40:43]
	v_mfma_f32_16x16x32_bf16 v[36:39], v[170:173], v[214:217], v[36:39]
	v_mfma_f32_16x16x32_bf16 v[32:35], v[178:181], v[214:217], v[32:35]
	v_mfma_f32_16x16x32_bf16 v[60:63], v[174:177], v[194:197], v[60:63]
	v_mfma_f32_16x16x32_bf16 v[56:59], v[186:189], v[194:197], v[56:59]
	v_mfma_f32_16x16x32_bf16 v[52:55], v[174:177], v[202:205], v[52:55]
	v_mfma_f32_16x16x32_bf16 v[48:51], v[186:189], v[202:205], v[48:51]
	v_mfma_f32_16x16x32_bf16 v[44:47], v[174:177], v[210:213], v[44:47]
	v_mfma_f32_16x16x32_bf16 v[40:43], v[186:189], v[210:213], v[40:43]
	v_mfma_f32_16x16x32_bf16 v[36:39], v[174:177], v[218:221], v[36:39]
	v_mfma_f32_16x16x32_bf16 v[32:35], v[186:189], v[218:221], v[32:35]
	s_setprio 0
	s_barrier
	v_readfirstlane_b32 s1, v163
	v_lshl_add_u64 v[170:171], v[242:243], 0, s[34:35]
	s_mov_b32 m0, s1
	v_readfirstlane_b32 s1, v165
	global_load_lds_dwordx4 v[170:171], off
	v_lshl_add_u64 v[170:171], v[244:245], 0, s[34:35]
	s_mov_b32 m0, s1
	s_nop 0
	global_load_lds_dwordx4 v[170:171], off
	s_waitcnt vmcnt(6)
	s_barrier
	s_setprio 1
	v_mfma_f32_16x16x32_bf16 v[28:31], v[222:225], v[190:193], v[28:31]
	v_mfma_f32_16x16x32_bf16 v[24:27], v[230:233], v[190:193], v[24:27]
	v_mfma_f32_16x16x32_bf16 v[20:23], v[222:225], v[198:201], v[20:23]
	v_mfma_f32_16x16x32_bf16 v[16:19], v[230:233], v[198:201], v[16:19]
	v_mfma_f32_16x16x32_bf16 v[12:15], v[222:225], v[206:209], v[12:15]
	v_mfma_f32_16x16x32_bf16 v[8:11], v[230:233], v[206:209], v[8:11]
	v_mfma_f32_16x16x32_bf16 v[4:7], v[222:225], v[214:217], v[4:7]
	v_mfma_f32_16x16x32_bf16 v[0:3], v[230:233], v[214:217], v[0:3]
	v_mfma_f32_16x16x32_bf16 v[28:31], v[226:229], v[194:197], v[28:31]
	v_mfma_f32_16x16x32_bf16 v[24:27], v[234:237], v[194:197], v[24:27]
	v_mfma_f32_16x16x32_bf16 v[20:23], v[226:229], v[202:205], v[20:23]
	v_mfma_f32_16x16x32_bf16 v[16:19], v[234:237], v[202:205], v[16:19]
	v_mfma_f32_16x16x32_bf16 v[12:15], v[226:229], v[210:213], v[12:15]
	v_mfma_f32_16x16x32_bf16 v[8:11], v[234:237], v[210:213], v[8:11]
	v_mfma_f32_16x16x32_bf16 v[4:7], v[226:229], v[218:221], v[4:7]
	v_mfma_f32_16x16x32_bf16 v[0:3], v[234:237], v[218:221], v[0:3]
	s_setprio 0
	s_add_i32 s0, s0, 2
	v_lshl_add_u64 v[132:133], v[132:133], 0, s[36:37]
	v_lshl_add_u64 v[134:135], v[134:135], 0, s[36:37]
	v_lshl_add_u64 v[136:137], v[136:137], 0, s[36:37]
	s_cmp_lt_u32 s0, 12
	v_lshl_add_u64 v[138:139], v[138:139], 0, s[36:37]
	s_barrier
	s_cbranch_scc1 .LBB0_687
	v_readfirstlane_b32 s0, v167
	v_lshl_add_u64 v[128:129], v[128:129], 0, s[38:39]
	s_mov_b32 m0, s0
	v_readfirstlane_b32 s0, v166
	ds_read_b128 v[132:135], v168
	ds_read_b128 v[136:139], v168 offset:1024
	ds_read_b128 v[140:143], v168 offset:2048
	ds_read_b128 v[156:159], v168 offset:3072
	ds_read_b128 v[160:163], v152
	ds_read_b128 v[168:171], v152 offset:1024
	ds_read_b128 v[172:175], v151
	ds_read_b128 v[176:179], v151 offset:1024
	ds_read_b128 v[186:189], v150
	ds_read_b128 v[190:193], v150 offset:1024
	ds_read_b128 v[194:197], v149
	ds_read_b128 v[198:201], v149 offset:1024
	global_load_lds_dwordx4 v[128:129], off
	v_lshl_add_u64 v[128:129], v[130:131], 0, s[38:39]
	s_mov_b32 m0, s0
	s_nop 0
	global_load_lds_dwordx4 v[128:129], off
	s_barrier
	s_waitcnt lgkmcnt(0)
	s_setprio 1
	s_waitcnt lgkmcnt(0)
	v_mfma_f32_16x16x32_bf16 v[120:123], v[140:143], v[160:163], v[120:123]
	v_mfma_f32_16x16x32_bf16 v[100:103], v[132:135], v[194:197], v[100:103]
	v_mfma_f32_16x16x32_bf16 v[96:99], v[140:143], v[194:197], v[96:99]
	v_mfma_f32_16x16x32_bf16 v[124:127], v[132:135], v[160:163], v[124:127]
	v_mfma_f32_16x16x32_bf16 v[120:123], v[156:159], v[168:171], v[120:123]
	v_mfma_f32_16x16x32_bf16 v[116:119], v[132:135], v[172:175], v[116:119]
	v_mfma_f32_16x16x32_bf16 v[112:115], v[140:143], v[172:175], v[112:115]
	v_mfma_f32_16x16x32_bf16 v[108:111], v[132:135], v[186:189], v[108:111]
	v_mfma_f32_16x16x32_bf16 v[104:107], v[140:143], v[186:189], v[104:107]
	v_mfma_f32_16x16x32_bf16 v[100:103], v[136:139], v[198:201], v[100:103]
	v_mfma_f32_16x16x32_bf16 v[96:99], v[156:159], v[198:201], v[96:99]
	v_mfma_f32_16x16x32_bf16 v[124:127], v[136:139], v[168:171], v[124:127]
	v_mfma_f32_16x16x32_bf16 v[116:119], v[136:139], v[176:179], v[116:119]
	v_mfma_f32_16x16x32_bf16 v[128:131], v[156:159], v[176:179], v[112:115]
	v_mfma_f32_16x16x32_bf16 v[108:111], v[136:139], v[190:193], v[108:111]
	v_mfma_f32_16x16x32_bf16 v[202:205], v[156:159], v[190:193], v[104:107]
	s_setprio 0
	s_barrier
	ds_read_b128 v[104:107], v164
	ds_read_b128 v[112:115], v164 offset:1024
	ds_read_b128 v[206:209], v164 offset:2048
	ds_read_b128 v[164:167], v164 offset:3072
	s_barrier
; #define LDA(dst, b, h) _Pragma("unroll") for (int m = 0; m < 4; ++m) _Pragma("unroll") for (int k = 0; k < 2; ++k) \
;     dst[m][k] = *reinterpret_cast<const bf16x8*>((const char*)SA(b, h) + lds_byte8(wr * 64 + m * 16 + fr, k * 32 + fq * 8))
; #define LDB(dst, b, h) _Pragma("unroll") for (int n = 0; n < 2; ++n) _Pragma("unroll") for (int k = 0; k < 2; ++k) \
;     dst[n][k] = *reinterpret_cast<const bf16x8*>((const char*)SB(b, h) + lds_byte8(wc * 32 + n * 16 + fr, k * 32 + fq * 8))
; #define MMA(ai, bj, At_, Bt_) do { __builtin_amdgcn_s_setprio(1); \
;     _Pragma("unroll") for (int m = 0; m < 4; ++m) _Pragma("unroll") for (int n = 0; n < 2; ++n) _Pragma("unroll") for (int k = 0; k < 2; ++k) \
;       acc[ai][bj][m][n] = MFMA16(Bt_[n][k], At_[m][k], acc[ai][bj][m][n]); \
;     __builtin_amdgcn_s_setprio(0); } while (0)
; #define WAIT_V(n) asm volatile("s_waitcnt vmcnt(" #n ")" ::: "memory")
; #define WAIT_L(n) asm volatile("s_waitcnt lgkmcnt(" #n ")" ::: "memory")
; #define BAR __builtin_amdgcn_s_barrier()
; template <class FL, class FS>
; DI void gemm8_tile(char* shmc, const bf16_t* __restrict__ A, const bf16_t* __restrict__ Bt, const int K, const int brow, const int bcol, FL fl, FS fs) {
;     ...
;     BAR; WAIT_L(0); MMA(0, 0, At, B0); BAR;
;     LDB(B1, 0, 1); BAR; WAIT_L(0); MMA(0, 1, At, B1); BAR;
;     LDA(At, 0, 1); WAIT_V(4); BAR; WAIT_L(0); MMA(1, 0, At, B0); MMA(1, 1, At, B1); BAR; }
;   { LDB(B0, 1, 0); LDA(At, 1, 0); WAIT_V(2); BAR; WAIT_L(0); MMA(0, 0, At, B0); BAR;
	s_waitcnt lgkmcnt(0)
	s_setprio 1
	s_waitcnt lgkmcnt(3)
	v_mfma_f32_16x16x32_bf16 v[84:87], v[104:107], v[172:175], v[84:87]
	s_waitcnt lgkmcnt(1)
	v_mfma_f32_16x16x32_bf16 v[80:83], v[206:209], v[172:175], v[80:83]
	v_mfma_f32_16x16x32_bf16 v[68:71], v[104:107], v[194:197], v[68:71]
	v_mfma_f32_16x16x32_bf16 v[64:67], v[206:209], v[194:197], v[64:67]
	v_mfma_f32_16x16x32_bf16 v[92:95], v[104:107], v[160:163], v[92:95]
	v_mfma_f32_16x16x32_bf16 v[88:91], v[206:209], v[160:163], v[88:91]
	v_mfma_f32_16x16x32_bf16 v[84:87], v[112:115], v[176:179], v[84:87]
	s_waitcnt lgkmcnt(0)
	v_mfma_f32_16x16x32_bf16 v[80:83], v[164:167], v[176:179], v[80:83]
	v_mfma_f32_16x16x32_bf16 v[76:79], v[104:107], v[186:189], v[76:79]
	v_mfma_f32_16x16x32_bf16 v[72:75], v[206:209], v[186:189], v[72:75]
	v_mfma_f32_16x16x32_bf16 v[68:71], v[112:115], v[198:201], v[68:71]
	v_mfma_f32_16x16x32_bf16 v[64:67], v[164:167], v[198:201], v[64:67]
	v_mfma_f32_16x16x32_bf16 v[210:213], v[112:115], v[168:171], v[92:95]
	v_mfma_f32_16x16x32_bf16 v[160:163], v[164:167], v[168:171], v[88:91]
	v_mfma_f32_16x16x32_bf16 v[168:171], v[112:115], v[190:193], v[76:79]
	v_mfma_f32_16x16x32_bf16 v[172:175], v[164:167], v[190:193], v[72:75]
	s_setprio 0
	s_barrier
	s_nop 0
	ds_read_b128 v[72:75], v152 offset:16384
	ds_read_b128 v[76:79], v152 offset:17408
	ds_read_b128 v[88:91], v151 offset:16384
	ds_read_b128 v[92:95], v151 offset:17408
	ds_read_b128 v[176:179], v150 offset:16384
	ds_read_b128 v[186:189], v150 offset:17408
	ds_read_b128 v[190:193], v149 offset:16384
	ds_read_b128 v[194:197], v149 offset:17408
	s_waitcnt vmcnt(4)
	s_barrier
	s_waitcnt lgkmcnt(0)
	s_setprio 1
	s_waitcnt lgkmcnt(7)
	v_mfma_f32_16x16x32_bf16 v[60:63], v[132:135], v[72:75], v[60:63]
	v_mfma_f32_16x16x32_bf16 v[56:59], v[140:143], v[72:75], v[56:59]
	s_waitcnt lgkmcnt(5)
	v_mfma_f32_16x16x32_bf16 v[52:55], v[132:135], v[88:91], v[52:55]
	v_mfma_f32_16x16x32_bf16 v[48:51], v[140:143], v[88:91], v[48:51]
	s_waitcnt lgkmcnt(1)
	v_mfma_f32_16x16x32_bf16 v[36:39], v[132:135], v[190:193], v[36:39]
	v_mfma_f32_16x16x32_bf16 v[32:35], v[140:143], v[190:193], v[32:35]
	v_mfma_f32_16x16x32_bf16 v[60:63], v[136:139], v[76:79], v[60:63]
	v_mfma_f32_16x16x32_bf16 v[56:59], v[156:159], v[76:79], v[56:59]
	v_mfma_f32_16x16x32_bf16 v[52:55], v[136:139], v[92:95], v[52:55]
	v_mfma_f32_16x16x32_bf16 v[48:51], v[156:159], v[92:95], v[48:51]
	v_mfma_f32_16x16x32_bf16 v[44:47], v[132:135], v[176:179], v[44:47]
	v_mfma_f32_16x16x32_bf16 v[40:43], v[140:143], v[176:179], v[40:43]
	s_waitcnt lgkmcnt(0)
	v_mfma_f32_16x16x32_bf16 v[36:39], v[136:139], v[194:197], v[36:39]
	v_mfma_f32_16x16x32_bf16 v[32:35], v[156:159], v[194:197], v[32:35]
	v_mfma_f32_16x16x32_bf16 v[198:201], v[136:139], v[186:189], v[44:47]
	v_mfma_f32_16x16x32_bf16 v[214:217], v[156:159], v[186:189], v[40:43]
	s_setprio 0
	s_setprio 1
	v_mfma_f32_16x16x32_bf16 v[20:23], v[104:107], v[88:91], v[20:23]
	v_mfma_f32_16x16x32_bf16 v[16:19], v[206:209], v[88:91], v[16:19]
	v_mfma_f32_16x16x32_bf16 v[4:7], v[104:107], v[190:193], v[4:7]
	v_mfma_f32_16x16x32_bf16 v[0:3], v[206:209], v[190:193], v[0:3]
	v_mfma_f32_16x16x32_bf16 v[28:31], v[104:107], v[72:75], v[28:31]
	v_mfma_f32_16x16x32_bf16 v[24:27], v[206:209], v[72:75], v[24:27]
	v_mfma_f32_16x16x32_bf16 v[20:23], v[112:115], v[92:95], v[20:23]
	v_mfma_f32_16x16x32_bf16 v[16:19], v[164:167], v[92:95], v[16:19]
	v_mfma_f32_16x16x32_bf16 v[12:15], v[104:107], v[176:179], v[12:15]
	v_mfma_f32_16x16x32_bf16 v[8:11], v[206:209], v[176:179], v[8:11]
	v_mfma_f32_16x16x32_bf16 v[4:7], v[112:115], v[194:197], v[4:7]
	v_mfma_f32_16x16x32_bf16 v[0:3], v[164:167], v[194:197], v[0:3]
	v_mfma_f32_16x16x32_bf16 v[156:159], v[112:115], v[76:79], v[28:31]
	v_mfma_f32_16x16x32_bf16 v[218:221], v[164:167], v[76:79], v[24:27]
	v_mfma_f32_16x16x32_bf16 v[222:225], v[112:115], v[186:189], v[12:15]
	v_mfma_f32_16x16x32_bf16 v[176:179], v[164:167], v[186:189], v[8:11]
	s_setprio 0
	s_barrier
	s_nop 0
	ds_read_b128 v[8:11], v154
	ds_read_b128 v[12:15], v154 offset:1024
	ds_read_b128 v[164:167], v154 offset:2048
	ds_read_b128 v[186:189], v154 offset:3072
	ds_read_b128 v[24:27], v152 offset:32768
	ds_read_b128 v[28:31], v152 offset:33792
	ds_read_b128 v[40:43], v151 offset:32768
	ds_read_b128 v[44:47], v151 offset:33792
	ds_read_b128 v[190:193], v150 offset:32768
	ds_read_b128 v[194:197], v150 offset:33792
	ds_read_b128 v[206:209], v149 offset:32768
	ds_read_b128 v[226:229], v149 offset:33792
	s_waitcnt vmcnt(2)
	s_barrier
; #define LDA(dst, b, h) _Pragma("unroll") for (int m = 0; m < 4; ++m) _Pragma("unroll") for (int k = 0; k < 2; ++k) \
;     dst[m][k] = *reinterpret_cast<const bf16x8*>((const char*)SA(b, h) + lds_byte8(wr * 64 + m * 16 + fr, k * 32 + fq * 8))
; #define LDB(dst, b, h) _Pragma("unroll") for (int n = 0; n < 2; ++n) _Pragma("unroll") for (int k = 0; k < 2; ++k) \
;     dst[n][k] = *reinterpret_cast<const bf16x8*>((const char*)SB(b, h) + lds_byte8(wc * 32 + n * 16 + fr, k * 32 + fq * 8))
; #define MMA(ai, bj, At_, Bt_) do { __builtin_amdgcn_s_setprio(1); \
;     _Pragma("unroll") for (int m = 0; m < 4; ++m) _Pragma("unroll") for (int n = 0; n < 2; ++n) _Pragma("unroll") for (int k = 0; k < 2; ++k) \
;       acc[ai][bj][m][n] = MFMA16(Bt_[n][k], At_[m][k], acc[ai][bj][m][n]); \
;     __builtin_amdgcn_s_setprio(0); } while (0)
; #define WAIT_V(n) asm volatile("s_waitcnt vmcnt(" #n ")" ::: "memory")
; #define WAIT_L(n) asm volatile("s_waitcnt lgkmcnt(" #n ")" ::: "memory")
; #define BAR __builtin_amdgcn_s_barrier()
; template <class FL, class FS>
; DI void gemm8_tile(char* shmc, const bf16_t* __restrict__ A, const bf16_t* __restrict__ Bt, const int K, const int brow, const int bcol, FL fl, FS fs) {
;     ...
;   { LDB(B0, 1, 0); LDA(At, 1, 0); WAIT_V(2); BAR; WAIT_L(0); MMA(0, 0, At, B0); BAR;
;     LDB(B1, 1, 1); WAIT_V(0); BAR; WAIT_L(0); MMA(0, 1, At, B1); BAR;
;     LDA(At, 1, 1); BAR; WAIT_L(0); MMA(1, 0, At, B0); MMA(1, 1, At, B1); BAR; }
;   if (wr == 0) BAR;
	s_waitcnt lgkmcnt(0)
	s_setprio 1
	s_waitcnt lgkmcnt(7)
	v_mfma_f32_16x16x32_bf16 v[72:75], v[8:11], v[24:27], v[124:127]
	s_waitcnt lgkmcnt(6)
	v_mfma_f32_16x16x32_bf16 v[140:143], v[12:15], v[28:31], v[72:75]
	v_mfma_f32_16x16x32_bf16 v[72:75], v[164:167], v[24:27], v[120:123]
	v_mfma_f32_16x16x32_bf16 v[136:139], v[186:189], v[28:31], v[72:75]
	s_waitcnt lgkmcnt(5)
	v_mfma_f32_16x16x32_bf16 v[72:75], v[8:11], v[40:43], v[116:119]
	s_waitcnt lgkmcnt(4)
	v_mfma_f32_16x16x32_bf16 v[112:115], v[12:15], v[44:47], v[72:75]
	v_mfma_f32_16x16x32_bf16 v[72:75], v[164:167], v[40:43], v[128:131]
	v_mfma_f32_16x16x32_bf16 v[104:107], v[186:189], v[44:47], v[72:75]
	s_waitcnt lgkmcnt(3)
	v_mfma_f32_16x16x32_bf16 v[72:75], v[8:11], v[190:193], v[108:111]
	s_waitcnt lgkmcnt(2)
	v_mfma_f32_16x16x32_bf16 v[92:95], v[12:15], v[194:197], v[72:75]
	v_mfma_f32_16x16x32_bf16 v[72:75], v[164:167], v[190:193], v[202:205]
	v_mfma_f32_16x16x32_bf16 v[88:91], v[186:189], v[194:197], v[72:75]
	s_waitcnt lgkmcnt(1)
	v_mfma_f32_16x16x32_bf16 v[72:75], v[8:11], v[206:209], v[100:103]
	s_waitcnt lgkmcnt(0)
	v_mfma_f32_16x16x32_bf16 v[76:79], v[12:15], v[226:229], v[72:75]
	v_mfma_f32_16x16x32_bf16 v[72:75], v[164:167], v[206:209], v[96:99]
	v_mfma_f32_16x16x32_bf16 v[72:75], v[186:189], v[226:229], v[72:75]
	s_setprio 0
	s_barrier
	ds_read_b128 v[108:111], v153
	ds_read_b128 v[116:119], v153 offset:1024
	ds_read_b128 v[124:127], v153 offset:2048
	ds_read_b128 v[128:131], v153 offset:3072
	s_waitcnt vmcnt(0)
	s_barrier
	s_waitcnt lgkmcnt(0)
	s_setprio 1
	s_waitcnt lgkmcnt(3)
	v_mfma_f32_16x16x32_bf16 v[96:99], v[108:111], v[24:27], v[210:213]
	s_waitcnt lgkmcnt(1)
	v_mfma_f32_16x16x32_bf16 v[24:27], v[124:127], v[24:27], v[160:163]
	s_waitcnt lgkmcnt(0)
	v_mfma_f32_16x16x32_bf16 v[120:123], v[128:131], v[28:31], v[24:27]
	v_mfma_f32_16x16x32_bf16 v[24:27], v[108:111], v[40:43], v[84:87]
	v_mfma_f32_16x16x32_bf16 v[100:103], v[116:119], v[44:47], v[24:27]
	v_mfma_f32_16x16x32_bf16 v[24:27], v[124:127], v[40:43], v[80:83]
	v_mfma_f32_16x16x32_bf16 v[132:135], v[116:119], v[28:31], v[96:99]
	v_mfma_f32_16x16x32_bf16 v[96:99], v[128:131], v[44:47], v[24:27]
	v_mfma_f32_16x16x32_bf16 v[24:27], v[108:111], v[190:193], v[168:171]
	v_mfma_f32_16x16x32_bf16 v[84:87], v[116:119], v[194:197], v[24:27]
	v_mfma_f32_16x16x32_bf16 v[24:27], v[124:127], v[190:193], v[172:175]
	v_mfma_f32_16x16x32_bf16 v[80:83], v[128:131], v[194:197], v[24:27]
	v_mfma_f32_16x16x32_bf16 v[24:27], v[108:111], v[206:209], v[68:71]
	v_mfma_f32_16x16x32_bf16 v[68:71], v[116:119], v[226:229], v[24:27]
	v_mfma_f32_16x16x32_bf16 v[24:27], v[124:127], v[206:209], v[64:67]
	v_mfma_f32_16x16x32_bf16 v[64:67], v[128:131], v[226:229], v[24:27]
	s_setprio 0
	s_barrier
	ds_read_b128 v[160:163], v152 offset:49152
	ds_read_b128 v[152:155], v152 offset:50176
	ds_read_b128 v[168:171], v151 offset:49152
	ds_read_b128 v[172:175], v151 offset:50176
	ds_read_b128 v[190:193], v150 offset:49152
	ds_read_b128 v[194:197], v150 offset:50176
	ds_read_b128 v[202:205], v149 offset:49152
	ds_read_b128 v[206:209], v149 offset:50176
	s_barrier
	s_waitcnt lgkmcnt(0)
	s_setprio 1
	s_waitcnt lgkmcnt(7)
	v_mfma_f32_16x16x32_bf16 v[24:27], v[8:11], v[160:163], v[60:63]
	s_waitcnt lgkmcnt(6)
	v_mfma_f32_16x16x32_bf16 v[60:63], v[12:15], v[152:155], v[24:27]
	v_mfma_f32_16x16x32_bf16 v[24:27], v[164:167], v[160:163], v[56:59]
	v_mfma_f32_16x16x32_bf16 v[56:59], v[186:189], v[152:155], v[24:27]
	s_waitcnt lgkmcnt(5)
	v_mfma_f32_16x16x32_bf16 v[24:27], v[8:11], v[168:171], v[52:55]
	s_waitcnt lgkmcnt(4)
	v_mfma_f32_16x16x32_bf16 v[44:47], v[12:15], v[172:175], v[24:27]
	v_mfma_f32_16x16x32_bf16 v[24:27], v[164:167], v[168:171], v[48:51]
	v_mfma_f32_16x16x32_bf16 v[40:43], v[186:189], v[172:175], v[24:27]
	s_waitcnt lgkmcnt(3)
	v_mfma_f32_16x16x32_bf16 v[24:27], v[8:11], v[190:193], v[198:201]
	s_waitcnt lgkmcnt(1)
	v_mfma_f32_16x16x32_bf16 v[8:11], v[8:11], v[202:205], v[36:39]
	v_mfma_f32_16x16x32_bf16 v[28:31], v[12:15], v[194:197], v[24:27]
	v_mfma_f32_16x16x32_bf16 v[24:27], v[164:167], v[190:193], v[214:217]
	s_waitcnt lgkmcnt(0)
	v_mfma_f32_16x16x32_bf16 v[12:15], v[12:15], v[206:209], v[8:11]
	v_mfma_f32_16x16x32_bf16 v[8:11], v[164:167], v[202:205], v[32:35]
	v_mfma_f32_16x16x32_bf16 v[24:27], v[186:189], v[194:197], v[24:27]
	v_mfma_f32_16x16x32_bf16 v[8:11], v[186:189], v[206:209], v[8:11]
	s_setprio 0
	s_setprio 1
	v_mfma_f32_16x16x32_bf16 v[32:35], v[108:111], v[160:163], v[156:159]
	v_mfma_f32_16x16x32_bf16 v[52:55], v[116:119], v[152:155], v[32:35]
	v_mfma_f32_16x16x32_bf16 v[32:35], v[124:127], v[160:163], v[218:221]
	v_mfma_f32_16x16x32_bf16 v[16:19], v[124:127], v[168:171], v[16:19]
	v_mfma_f32_16x16x32_bf16 v[48:51], v[128:131], v[152:155], v[32:35]
	v_mfma_f32_16x16x32_bf16 v[20:23], v[108:111], v[168:171], v[20:23]
	v_mfma_f32_16x16x32_bf16 v[32:35], v[128:131], v[172:175], v[16:19]
	v_mfma_f32_16x16x32_bf16 v[16:19], v[108:111], v[190:193], v[222:225]
	v_mfma_f32_16x16x32_bf16 v[36:39], v[116:119], v[172:175], v[20:23]
	v_mfma_f32_16x16x32_bf16 v[20:23], v[116:119], v[194:197], v[16:19]
	v_mfma_f32_16x16x32_bf16 v[16:19], v[124:127], v[190:193], v[176:179]
	v_mfma_f32_16x16x32_bf16 v[4:7], v[108:111], v[202:205], v[4:7]
	v_mfma_f32_16x16x32_bf16 v[0:3], v[124:127], v[202:205], v[0:3]
	v_mfma_f32_16x16x32_bf16 v[16:19], v[128:131], v[194:197], v[16:19]
	v_mfma_f32_16x16x32_bf16 v[4:7], v[116:119], v[206:209], v[4:7]
	v_mfma_f32_16x16x32_bf16 v[0:3], v[128:131], v[206:209], v[0:3]
	s_setprio 0
	v_cmp_gt_u32_e32 vcc, s52, v144
	s_barrier
	s_and_saveexec_b64 s[0:1], vcc
	s_cbranch_execz .Lg2_wr0
	s_barrier

; #define STAGE(P, BASE, br, kt) do { const long _g = (long)(br) * K + (long)(kt) * 64; \
;     _Pragma("unroll") for (int _i = 0; _i < 2; ++_i) { const int _b = tidx * 16 + _i * 8192; int _r, _c; stage_rc8(_b, _r, _c); \
;       __builtin_amdgcn_global_load_lds((const unsigned*)(BASE + _g + (long)_r * K + _c), (LAS unsigned*)((LAS char*)(P) + _b), 16, 0, 0); } } while (0)
; #define LDA(dst, b, h) _Pragma("unroll") for (int m = 0; m < 4; ++m) _Pragma("unroll") for (int k = 0; k < 2; ++k) \
;     dst[m][k] = *reinterpret_cast<const bf16x8*>((const char*)SA(b, h) + lds_byte8(wr * 64 + m * 16 + fr, k * 32 + fq * 8))
; #define LDB(dst, b, h) _Pragma("unroll") for (int n = 0; n < 2; ++n) _Pragma("unroll") for (int k = 0; k < 2; ++k) \
;     dst[n][k] = *reinterpret_cast<const bf16x8*>((const char*)SB(b, h) + lds_byte8(wc * 32 + n * 16 + fr, k * 32 + fq * 8))
; #define MMA(ai, bj, At_, Bt_) do { __builtin_amdgcn_s_setprio(1); \
;     _Pragma("unroll") for (int m = 0; m < 4; ++m) _Pragma("unroll") for (int n = 0; n < 2; ++n) _Pragma("unroll") for (int k = 0; k < 2; ++k) \
;       acc[ai][bj][m][n] = MFMA16(Bt_[n][k], At_[m][k], acc[ai][bj][m][n]); \
;     __builtin_amdgcn_s_setprio(0); } while (0)
; #define WAIT_V(n) asm volatile("s_waitcnt vmcnt(" #n ")" ::: "memory")
; #define WAIT_L(n) asm volatile("s_waitcnt lgkmcnt(" #n ")" ::: "memory")
; #define BAR __builtin_amdgcn_s_barrier()
; #define SCHED __builtin_amdgcn_sched_barrier(0)
; template <class FL, class FS>
; DI void gemm8_tile(char* shmc, const bf16_t* __restrict__ A, const bf16_t* __restrict__ Bt, const int K, const int brow, const int bcol, FL fl, FS fs) {
;     ...
;     LDB(B0, 0, 0); SCHED; LDA(At, 0, 0); STAGE(SA(1, 1), A, brow + HALF, t + 1);
;     WAIT_L(8); BAR; WAIT_L(0); MMA(0, 0, At, B0); BAR; SCHED;
;     LDB(B1, 0, 1); STAGE(SB(0, 0), Bt, bcol, t + 2);
;     BAR; WAIT_L(0); MMA(0, 1, At, B1); BAR;
;     LDA(At, 0, 1); STAGE(SA(0, 0), A, brow, t + 2);
;     BAR; WAIT_L(0); MMA(1, 0, At, B0); BAR; SCHED;
;     STAGE(SB(0, 1), Bt, bcol + HALF, t + 2);
;     WAIT_V(6); BAR; MMA(1, 1, At, B1); BAR;
.Lg3_p1skip:
	s_nop 0
	s_barrier
	s_waitcnt lgkmcnt(0)
	s_setprio 1
	s_waitcnt lgkmcnt(0)
	v_mfma_f32_16x16x32_bf16 v[124:127], v[170:173], v[188:191], v[124:127]
	v_mfma_f32_16x16x32_bf16 v[120:123], v[178:181], v[188:191], v[120:123]
	v_mfma_f32_16x16x32_bf16 v[116:119], v[170:173], v[196:199], v[116:119]
	v_mfma_f32_16x16x32_bf16 v[112:115], v[178:181], v[196:199], v[112:115]
	v_mfma_f32_16x16x32_bf16 v[108:111], v[170:173], v[204:207], v[108:111]
	v_mfma_f32_16x16x32_bf16 v[104:107], v[178:181], v[204:207], v[104:107]
	v_mfma_f32_16x16x32_bf16 v[100:103], v[170:173], v[212:215], v[100:103]
	v_mfma_f32_16x16x32_bf16 v[96:99], v[178:181], v[212:215], v[96:99]
	v_mfma_f32_16x16x32_bf16 v[124:127], v[174:177], v[192:195], v[124:127]
	v_mfma_f32_16x16x32_bf16 v[120:123], v[184:187], v[192:195], v[120:123]
	v_mfma_f32_16x16x32_bf16 v[116:119], v[174:177], v[200:203], v[116:119]
	v_mfma_f32_16x16x32_bf16 v[112:115], v[184:187], v[200:203], v[112:115]
	v_mfma_f32_16x16x32_bf16 v[108:111], v[174:177], v[208:211], v[108:111]
	v_mfma_f32_16x16x32_bf16 v[104:107], v[184:187], v[208:211], v[104:107]
	v_mfma_f32_16x16x32_bf16 v[100:103], v[174:177], v[216:219], v[100:103]
	v_mfma_f32_16x16x32_bf16 v[96:99], v[184:187], v[216:219], v[96:99]
	s_setprio 0
	s_barrier
	v_lshl_add_u64 v[240:241], s[10:11], 0, v[132:133]
	v_readfirstlane_b32 s1, v148
	v_lshl_add_u64 v[242:243], v[240:241], 0, s[20:21]
	s_mov_b32 m0, s1
	ds_read_b128 v[220:223], v165
	ds_read_b128 v[224:227], v165 offset:1024
	ds_read_b128 v[228:231], v165 offset:2048
	ds_read_b128 v[232:235], v165 offset:3072
	global_load_lds_dwordx4 v[242:243], off
	v_lshl_add_u64 v[242:243], s[10:11], 0, v[134:135]
	v_readfirstlane_b32 s1, v154
	v_lshl_add_u64 v[244:245], v[242:243], 0, s[20:21]
	s_mov_b32 m0, s1
	s_nop 0
	global_load_lds_dwordx4 v[244:245], off
	s_barrier
	s_waitcnt lgkmcnt(0)
	s_setprio 1
	s_waitcnt lgkmcnt(0)
	v_mfma_f32_16x16x32_bf16 v[92:95], v[220:223], v[188:191], v[92:95]
	v_mfma_f32_16x16x32_bf16 v[88:91], v[228:231], v[188:191], v[88:91]
	v_mfma_f32_16x16x32_bf16 v[84:87], v[220:223], v[196:199], v[84:87]
	v_mfma_f32_16x16x32_bf16 v[80:83], v[228:231], v[196:199], v[80:83]
	v_mfma_f32_16x16x32_bf16 v[76:79], v[220:223], v[204:207], v[76:79]
	v_mfma_f32_16x16x32_bf16 v[72:75], v[228:231], v[204:207], v[72:75]
	v_mfma_f32_16x16x32_bf16 v[68:71], v[220:223], v[212:215], v[68:71]
	v_mfma_f32_16x16x32_bf16 v[64:67], v[228:231], v[212:215], v[64:67]
	v_mfma_f32_16x16x32_bf16 v[92:95], v[224:227], v[192:195], v[92:95]
	v_mfma_f32_16x16x32_bf16 v[88:91], v[232:235], v[192:195], v[88:91]
	v_mfma_f32_16x16x32_bf16 v[84:87], v[224:227], v[200:203], v[84:87]
	v_mfma_f32_16x16x32_bf16 v[80:83], v[232:235], v[200:203], v[80:83]
	v_mfma_f32_16x16x32_bf16 v[76:79], v[224:227], v[208:211], v[76:79]
	v_mfma_f32_16x16x32_bf16 v[72:75], v[232:235], v[208:211], v[72:75]
	v_mfma_f32_16x16x32_bf16 v[68:71], v[224:227], v[216:219], v[68:71]
	v_mfma_f32_16x16x32_bf16 v[64:67], v[232:235], v[216:219], v[64:67]
	s_setprio 0
	v_readfirstlane_b32 s1, v146
	v_lshl_add_u64 v[244:245], v[236:237], 0, s[22:23]
	s_mov_b32 m0, s1
	v_readfirstlane_b32 s1, v152
	s_barrier
	ds_read_b128 v[188:191], v151 offset:16384
	ds_read_b128 v[192:195], v151 offset:17408
	ds_read_b128 v[196:199], v150 offset:16384
	ds_read_b128 v[200:203], v150 offset:17408
	ds_read_b128 v[204:207], v149 offset:16384
	ds_read_b128 v[208:211], v149 offset:17408
	ds_read_b128 v[212:215], v147 offset:16384
	ds_read_b128 v[216:219], v147 offset:17408
	global_load_lds_dwordx4 v[244:245], off
	v_lshl_add_u64 v[244:245], v[238:239], 0, s[22:23]
	s_mov_b32 m0, s1
	s_nop 0
	global_load_lds_dwordx4 v[244:245], off
	s_barrier
	s_waitcnt lgkmcnt(0)
	s_setprio 1
	s_waitcnt lgkmcnt(0)
	v_mfma_f32_16x16x32_bf16 v[60:63], v[170:173], v[188:191], v[60:63]
	v_mfma_f32_16x16x32_bf16 v[56:59], v[178:181], v[188:191], v[56:59]
	v_mfma_f32_16x16x32_bf16 v[52:55], v[170:173], v[196:199], v[52:55]
	v_mfma_f32_16x16x32_bf16 v[48:51], v[178:181], v[196:199], v[48:51]
	v_mfma_f32_16x16x32_bf16 v[44:47], v[170:173], v[204:207], v[44:47]
	v_mfma_f32_16x16x32_bf16 v[40:43], v[178:181], v[204:207], v[40:43]
	v_mfma_f32_16x16x32_bf16 v[36:39], v[170:173], v[212:215], v[36:39]
	v_mfma_f32_16x16x32_bf16 v[32:35], v[178:181], v[212:215], v[32:35]
	v_mfma_f32_16x16x32_bf16 v[60:63], v[174:177], v[192:195], v[60:63]
	v_mfma_f32_16x16x32_bf16 v[56:59], v[184:187], v[192:195], v[56:59]
	v_mfma_f32_16x16x32_bf16 v[52:55], v[174:177], v[200:203], v[52:55]
	v_mfma_f32_16x16x32_bf16 v[48:51], v[184:187], v[200:203], v[48:51]
	v_mfma_f32_16x16x32_bf16 v[44:47], v[174:177], v[208:211], v[44:47]
	v_mfma_f32_16x16x32_bf16 v[40:43], v[184:187], v[208:211], v[40:43]
	v_mfma_f32_16x16x32_bf16 v[36:39], v[174:177], v[216:219], v[36:39]
	v_mfma_f32_16x16x32_bf16 v[32:35], v[184:187], v[216:219], v[32:35]
	s_setprio 0
	s_barrier
	v_readfirstlane_b32 s1, v156
	v_lshl_add_u64 v[170:171], v[240:241], 0, s[24:25]
	s_mov_b32 m0, s1
	v_readfirstlane_b32 s1, v157
	global_load_lds_dwordx4 v[170:171], off
	v_lshl_add_u64 v[170:171], v[242:243], 0, s[24:25]
	s_mov_b32 m0, s1
	s_nop 0
	global_load_lds_dwordx4 v[170:171], off
	s_cmp_eq_u32 s0, -2
	s_cselect_b32 s101, s98, 0
	s_cmp_lg_u32 s101, 0
	s_cbranch_scc1 .Lg3_w22
	s_waitcnt vmcnt(6)
; #define STAGE(P, BASE, br, kt) do { const long _g = (long)(br) * K + (long)(kt) * 64; \
;     _Pragma("unroll") for (int _i = 0; _i < 2; ++_i) { const int _b = tidx * 16 + _i * 8192; int _r, _c; stage_rc8(_b, _r, _c); \
;       __builtin_amdgcn_global_load_lds((const unsigned*)(BASE + _g + (long)_r * K + _c), (LAS unsigned*)((LAS char*)(P) + _b), 16, 0, 0); } } while (0)
; #define LDA(dst, b, h) _Pragma("unroll") for (int m = 0; m < 4; ++m) _Pragma("unroll") for (int k = 0; k < 2; ++k) \
;     dst[m][k] = *reinterpret_cast<const bf16x8*>((const char*)SA(b, h) + lds_byte8(wr * 64 + m * 16 + fr, k * 32 + fq * 8))
; #define LDB(dst, b, h) _Pragma("unroll") for (int n = 0; n < 2; ++n) _Pragma("unroll") for (int k = 0; k < 2; ++k) \
;     dst[n][k] = *reinterpret_cast<const bf16x8*>((const char*)SB(b, h) + lds_byte8(wc * 32 + n * 16 + fr, k * 32 + fq * 8))
; #define MMA(ai, bj, At_, Bt_) do { __builtin_amdgcn_s_setprio(1); \
;     _Pragma("unroll") for (int m = 0; m < 4; ++m) _Pragma("unroll") for (int n = 0; n < 2; ++n) _Pragma("unroll") for (int k = 0; k < 2; ++k) \
;       acc[ai][bj][m][n] = MFMA16(Bt_[n][k], At_[m][k], acc[ai][bj][m][n]); \
;     __builtin_amdgcn_s_setprio(0); } while (0)
; #define WAIT_V(n) asm volatile("s_waitcnt vmcnt(" #n ")" ::: "memory")
; #define WAIT_L(n) asm volatile("s_waitcnt lgkmcnt(" #n ")" ::: "memory")
; #define BAR __builtin_amdgcn_s_barrier()
; #define SCHED __builtin_amdgcn_sched_barrier(0)
; template <class FL, class FS>
; DI void gemm8_tile(char* shmc, const bf16_t* __restrict__ A, const bf16_t* __restrict__ Bt, const int K, const int brow, const int bcol, FL fl, FS fs) {
;     ...
;     WAIT_V(6); BAR; MMA(1, 1, At, B1); BAR;
;     LDB(B0, 1, 0); SCHED; LDA(At, 1, 0); STAGE(SA(0, 1), A, brow + HALF, t + 2);
;     WAIT_L(8); BAR; WAIT_L(0); MMA(0, 0, At, B0); BAR; SCHED;
;     LDB(B1, 1, 1); STAGE(SB(1, 0), Bt, bcol, t + 3);
;     BAR; WAIT_L(0); MMA(0, 1, At, B1); BAR;
;     LDA(At, 1, 1); STAGE(SA(1, 0), A, brow, t + 3);
;     BAR; WAIT_L(0); MMA(1, 0, At, B0); BAR; SCHED;
.Lg3_wd:
	s_barrier
	s_setprio 1
	v_mfma_f32_16x16x32_bf16 v[28:31], v[220:223], v[188:191], v[28:31]
	v_mfma_f32_16x16x32_bf16 v[24:27], v[228:231], v[188:191], v[24:27]
	v_mfma_f32_16x16x32_bf16 v[20:23], v[220:223], v[196:199], v[20:23]
	v_mfma_f32_16x16x32_bf16 v[16:19], v[228:231], v[196:199], v[16:19]
	v_mfma_f32_16x16x32_bf16 v[12:15], v[220:223], v[204:207], v[12:15]
	v_mfma_f32_16x16x32_bf16 v[8:11], v[228:231], v[204:207], v[8:11]
	v_mfma_f32_16x16x32_bf16 v[4:7], v[220:223], v[212:215], v[4:7]
	v_mfma_f32_16x16x32_bf16 v[0:3], v[228:231], v[212:215], v[0:3]
	v_mfma_f32_16x16x32_bf16 v[28:31], v[224:227], v[192:195], v[28:31]
	v_mfma_f32_16x16x32_bf16 v[24:27], v[232:235], v[192:195], v[24:27]
	v_mfma_f32_16x16x32_bf16 v[20:23], v[224:227], v[200:203], v[20:23]
	v_mfma_f32_16x16x32_bf16 v[16:19], v[232:235], v[200:203], v[16:19]
	v_mfma_f32_16x16x32_bf16 v[12:15], v[224:227], v[208:211], v[12:15]
	v_mfma_f32_16x16x32_bf16 v[8:11], v[232:235], v[208:211], v[8:11]
	v_mfma_f32_16x16x32_bf16 v[4:7], v[224:227], v[216:219], v[4:7]
	v_mfma_f32_16x16x32_bf16 v[0:3], v[232:235], v[216:219], v[0:3]
	s_setprio 0
	s_barrier
	ds_read_b128 v[170:173], v155
	ds_read_b128 v[174:177], v155 offset:1024
	ds_read_b128 v[178:181], v155 offset:2048
	ds_read_b128 v[184:187], v155 offset:3072
	v_readfirstlane_b32 s1, v158
	v_lshl_add_u64 v[220:221], v[236:237], 0, s[26:27]
	s_mov_b32 m0, s1
	v_readfirstlane_b32 s1, v159
	ds_read_b128 v[188:191], v151 offset:32768
	ds_read_b128 v[192:195], v151 offset:33792
	ds_read_b128 v[196:199], v150 offset:32768
	ds_read_b128 v[200:203], v150 offset:33792
	ds_read_b128 v[204:207], v149 offset:32768
	ds_read_b128 v[208:211], v149 offset:33792
	ds_read_b128 v[212:215], v147 offset:32768
	ds_read_b128 v[216:219], v147 offset:33792
	global_load_lds_dwordx4 v[220:221], off
	v_lshl_add_u64 v[220:221], v[238:239], 0, s[26:27]
	s_mov_b32 m0, s1
	s_nop 0
	global_load_lds_dwordx4 v[220:221], off
	s_nop 0
	s_barrier
	s_waitcnt lgkmcnt(0)
	s_setprio 1
	s_waitcnt lgkmcnt(0)
	v_mfma_f32_16x16x32_bf16 v[124:127], v[170:173], v[188:191], v[124:127]
	v_mfma_f32_16x16x32_bf16 v[120:123], v[178:181], v[188:191], v[120:123]
	v_mfma_f32_16x16x32_bf16 v[116:119], v[170:173], v[196:199], v[116:119]
	v_mfma_f32_16x16x32_bf16 v[112:115], v[178:181], v[196:199], v[112:115]
	v_mfma_f32_16x16x32_bf16 v[108:111], v[170:173], v[204:207], v[108:111]
	v_mfma_f32_16x16x32_bf16 v[104:107], v[178:181], v[204:207], v[104:107]
	v_mfma_f32_16x16x32_bf16 v[100:103], v[170:173], v[212:215], v[100:103]
	v_mfma_f32_16x16x32_bf16 v[96:99], v[178:181], v[212:215], v[96:99]
	v_mfma_f32_16x16x32_bf16 v[124:127], v[174:177], v[192:195], v[124:127]
	v_mfma_f32_16x16x32_bf16 v[120:123], v[184:187], v[192:195], v[120:123]
	v_mfma_f32_16x16x32_bf16 v[116:119], v[174:177], v[200:203], v[116:119]
	v_mfma_f32_16x16x32_bf16 v[112:115], v[184:187], v[200:203], v[112:115]
	v_mfma_f32_16x16x32_bf16 v[108:111], v[174:177], v[208:211], v[108:111]
	v_mfma_f32_16x16x32_bf16 v[104:107], v[184:187], v[208:211], v[104:107]
	v_mfma_f32_16x16x32_bf16 v[100:103], v[174:177], v[216:219], v[100:103]
	v_mfma_f32_16x16x32_bf16 v[96:99], v[184:187], v[216:219], v[96:99]
	s_setprio 0
	s_barrier
	v_readfirstlane_b32 s1, v160
	v_lshl_add_u64 v[244:245], v[240:241], 0, s[28:29]
	s_mov_b32 m0, s1
	v_readfirstlane_b32 s1, v161
	ds_read_b128 v[220:223], v153
	ds_read_b128 v[224:227], v153 offset:1024
	ds_read_b128 v[228:231], v153 offset:2048
	ds_read_b128 v[232:235], v153 offset:3072
	global_load_lds_dwordx4 v[244:245], off
	v_lshl_add_u64 v[244:245], v[242:243], 0, s[28:29]
	s_mov_b32 m0, s1
	s_nop 0
	global_load_lds_dwordx4 v[244:245], off
	s_barrier
	s_waitcnt lgkmcnt(0)
	s_setprio 1
	s_waitcnt lgkmcnt(0)
	v_mfma_f32_16x16x32_bf16 v[92:95], v[220:223], v[188:191], v[92:95]
	v_mfma_f32_16x16x32_bf16 v[88:91], v[228:231], v[188:191], v[88:91]
	v_mfma_f32_16x16x32_bf16 v[84:87], v[220:223], v[196:199], v[84:87]
	v_mfma_f32_16x16x32_bf16 v[80:83], v[228:231], v[196:199], v[80:83]
	v_mfma_f32_16x16x32_bf16 v[76:79], v[220:223], v[204:207], v[76:79]
	v_mfma_f32_16x16x32_bf16 v[72:75], v[228:231], v[204:207], v[72:75]
	v_mfma_f32_16x16x32_bf16 v[68:71], v[220:223], v[212:215], v[68:71]
	v_mfma_f32_16x16x32_bf16 v[64:67], v[228:231], v[212:215], v[64:67]
	v_mfma_f32_16x16x32_bf16 v[92:95], v[224:227], v[192:195], v[92:95]
	v_mfma_f32_16x16x32_bf16 v[88:91], v[232:235], v[192:195], v[88:91]
	v_mfma_f32_16x16x32_bf16 v[84:87], v[224:227], v[200:203], v[84:87]
	v_mfma_f32_16x16x32_bf16 v[80:83], v[232:235], v[200:203], v[80:83]
	v_mfma_f32_16x16x32_bf16 v[76:79], v[224:227], v[208:211], v[76:79]
	v_mfma_f32_16x16x32_bf16 v[72:75], v[232:235], v[208:211], v[72:75]
	v_mfma_f32_16x16x32_bf16 v[68:71], v[224:227], v[216:219], v[68:71]
	v_mfma_f32_16x16x32_bf16 v[64:67], v[232:235], v[216:219], v[64:67]
	s_setprio 0
	v_readfirstlane_b32 s1, v162
	v_lshl_add_u64 v[236:237], v[236:237], 0, s[30:31]
	s_mov_b32 m0, s1
	v_readfirstlane_b32 s1, v163
	s_barrier
	ds_read_b128 v[188:191], v151 offset:49152
	ds_read_b128 v[192:195], v151 offset:50176
	ds_read_b128 v[196:199], v150 offset:49152
	ds_read_b128 v[200:203], v150 offset:50176
	ds_read_b128 v[204:207], v149 offset:49152
	ds_read_b128 v[208:211], v149 offset:50176
	ds_read_b128 v[212:215], v147 offset:49152
	ds_read_b128 v[216:219], v147 offset:50176
	global_load_lds_dwordx4 v[236:237], off
	v_lshl_add_u64 v[236:237], v[238:239], 0, s[30:31]
	s_mov_b32 m0, s1
	s_nop 0
	global_load_lds_dwordx4 v[236:237], off
	s_barrier
; #define STAGE(P, BASE, br, kt) do { const long _g = (long)(br) * K + (long)(kt) * 64; \
;     _Pragma("unroll") for (int _i = 0; _i < 2; ++_i) { const int _b = tidx * 16 + _i * 8192; int _r, _c; stage_rc8(_b, _r, _c); \
;       __builtin_amdgcn_global_load_lds((const unsigned*)(BASE + _g + (long)_r * K + _c), (LAS unsigned*)((LAS char*)(P) + _b), 16, 0, 0); } } while (0)
; #define LDA(dst, b, h) _Pragma("unroll") for (int m = 0; m < 4; ++m) _Pragma("unroll") for (int k = 0; k < 2; ++k) \
;     dst[m][k] = *reinterpret_cast<const bf16x8*>((const char*)SA(b, h) + lds_byte8(wr * 64 + m * 16 + fr, k * 32 + fq * 8))
; #define LDB(dst, b, h) _Pragma("unroll") for (int n = 0; n < 2; ++n) _Pragma("unroll") for (int k = 0; k < 2; ++k) \
;     dst[n][k] = *reinterpret_cast<const bf16x8*>((const char*)SB(b, h) + lds_byte8(wc * 32 + n * 16 + fr, k * 32 + fq * 8))
; #define MMA(ai, bj, At_, Bt_) do { __builtin_amdgcn_s_setprio(1); \
;     _Pragma("unroll") for (int m = 0; m < 4; ++m) _Pragma("unroll") for (int n = 0; n < 2; ++n) _Pragma("unroll") for (int k = 0; k < 2; ++k) \
;       acc[ai][bj][m][n] = MFMA16(Bt_[n][k], At_[m][k], acc[ai][bj][m][n]); \
;     __builtin_amdgcn_s_setprio(0); } while (0)
; #define WAIT_V(n) asm volatile("s_waitcnt vmcnt(" #n ")" ::: "memory")
; #define WAIT_L(n) asm volatile("s_waitcnt lgkmcnt(" #n ")" ::: "memory")
; #define BAR __builtin_amdgcn_s_barrier()
; #define SCHED __builtin_amdgcn_sched_barrier(0)
; template <class FL, class FS>
; DI void gemm8_tile(char* shmc, const bf16_t* __restrict__ A, const bf16_t* __restrict__ Bt, const int K, const int brow, const int bcol, FL fl, FS fs) {
;     ...
;     BAR; WAIT_L(0); MMA(1, 0, At, B0); BAR; SCHED;
;     STAGE(SB(1, 1), Bt, bcol + HALF, t + 3);
;     WAIT_V(6); BAR; MMA(1, 1, At, B1); BAR;
;   }
;   { LDB(B0, 0, 0); LDA(At, 0, 0); STAGE(SA(1, 1), A, brow + HALF, nt - 1);
;     BAR; WAIT_L(0); MMA(0, 0, At, B0); BAR;
	s_waitcnt lgkmcnt(0)
	s_setprio 1
	s_waitcnt lgkmcnt(0)
	v_mfma_f32_16x16x32_bf16 v[60:63], v[170:173], v[188:191], v[60:63]
	v_mfma_f32_16x16x32_bf16 v[56:59], v[178:181], v[188:191], v[56:59]
	v_mfma_f32_16x16x32_bf16 v[52:55], v[170:173], v[196:199], v[52:55]
	v_mfma_f32_16x16x32_bf16 v[48:51], v[178:181], v[196:199], v[48:51]
	v_mfma_f32_16x16x32_bf16 v[44:47], v[170:173], v[204:207], v[44:47]
	v_mfma_f32_16x16x32_bf16 v[40:43], v[178:181], v[204:207], v[40:43]
	v_mfma_f32_16x16x32_bf16 v[36:39], v[170:173], v[212:215], v[36:39]
	v_mfma_f32_16x16x32_bf16 v[32:35], v[178:181], v[212:215], v[32:35]
	v_mfma_f32_16x16x32_bf16 v[60:63], v[174:177], v[192:195], v[60:63]
	v_mfma_f32_16x16x32_bf16 v[56:59], v[184:187], v[192:195], v[56:59]
	v_mfma_f32_16x16x32_bf16 v[52:55], v[174:177], v[200:203], v[52:55]
	v_mfma_f32_16x16x32_bf16 v[48:51], v[184:187], v[200:203], v[48:51]
	v_mfma_f32_16x16x32_bf16 v[44:47], v[174:177], v[208:211], v[44:47]
	v_mfma_f32_16x16x32_bf16 v[40:43], v[184:187], v[208:211], v[40:43]
	v_mfma_f32_16x16x32_bf16 v[36:39], v[174:177], v[216:219], v[36:39]
	v_mfma_f32_16x16x32_bf16 v[32:35], v[184:187], v[216:219], v[32:35]
	s_setprio 0
	s_barrier
	v_readfirstlane_b32 s1, v164
	v_lshl_add_u64 v[170:171], v[240:241], 0, s[34:35]
	s_mov_b32 m0, s1
	v_readfirstlane_b32 s1, v166
	global_load_lds_dwordx4 v[170:171], off
	v_lshl_add_u64 v[170:171], v[242:243], 0, s[34:35]
	s_mov_b32 m0, s1
	s_nop 0
	global_load_lds_dwordx4 v[170:171], off
	s_waitcnt vmcnt(6)
	s_barrier
	s_setprio 1
	v_mfma_f32_16x16x32_bf16 v[28:31], v[220:223], v[188:191], v[28:31]
	v_mfma_f32_16x16x32_bf16 v[24:27], v[228:231], v[188:191], v[24:27]
	v_mfma_f32_16x16x32_bf16 v[20:23], v[220:223], v[196:199], v[20:23]
	v_mfma_f32_16x16x32_bf16 v[16:19], v[228:231], v[196:199], v[16:19]
	v_mfma_f32_16x16x32_bf16 v[12:15], v[220:223], v[204:207], v[12:15]
	v_mfma_f32_16x16x32_bf16 v[8:11], v[228:231], v[204:207], v[8:11]
	v_mfma_f32_16x16x32_bf16 v[4:7], v[220:223], v[212:215], v[4:7]
	v_mfma_f32_16x16x32_bf16 v[0:3], v[228:231], v[212:215], v[0:3]
	v_mfma_f32_16x16x32_bf16 v[28:31], v[224:227], v[192:195], v[28:31]
	v_mfma_f32_16x16x32_bf16 v[24:27], v[232:235], v[192:195], v[24:27]
	v_mfma_f32_16x16x32_bf16 v[20:23], v[224:227], v[200:203], v[20:23]
	v_mfma_f32_16x16x32_bf16 v[16:19], v[232:235], v[200:203], v[16:19]
	v_mfma_f32_16x16x32_bf16 v[12:15], v[224:227], v[208:211], v[12:15]
	v_mfma_f32_16x16x32_bf16 v[8:11], v[232:235], v[208:211], v[8:11]
	v_mfma_f32_16x16x32_bf16 v[4:7], v[224:227], v[216:219], v[4:7]
	v_mfma_f32_16x16x32_bf16 v[0:3], v[232:235], v[216:219], v[0:3]
	s_setprio 0
	s_add_i32 s0, s0, 2
	v_lshl_add_u64 v[132:133], v[132:133], 0, s[36:37]
	v_lshl_add_u64 v[134:135], v[134:135], 0, s[36:37]
	v_lshl_add_u64 v[136:137], v[136:137], 0, s[36:37]
	s_cmp_lt_u32 s0, 12
	v_lshl_add_u64 v[138:139], v[138:139], 0, s[36:37]
	s_barrier
	s_cbranch_scc1 .LBB0_748
	v_readfirstlane_b32 s0, v168
	v_lshl_add_u64 v[128:129], v[128:129], 0, s[38:39]
	s_mov_b32 m0, s0
	v_readfirstlane_b32 s0, v167
	ds_read_b128 v[132:135], v169
	ds_read_b128 v[136:139], v169 offset:1024
	ds_read_b128 v[156:159], v169 offset:2048
	ds_read_b128 v[160:163], v169 offset:3072
	ds_read_b128 v[170:173], v151
	ds_read_b128 v[174:177], v151 offset:1024
	ds_read_b128 v[178:181], v150
	ds_read_b128 v[184:187], v150 offset:1024
	ds_read_b128 v[188:191], v149
	ds_read_b128 v[192:195], v149 offset:1024
	ds_read_b128 v[196:199], v147
	ds_read_b128 v[200:203], v147 offset:1024
	global_load_lds_dwordx4 v[128:129], off
	v_lshl_add_u64 v[128:129], v[130:131], 0, s[38:39]
	s_mov_b32 m0, s0
	s_nop 0
	global_load_lds_dwordx4 v[128:129], off
	s_barrier
	s_waitcnt lgkmcnt(0)
	s_setprio 1
	s_waitcnt lgkmcnt(0)
	v_mfma_f32_16x16x32_bf16 v[124:127], v[132:135], v[170:173], v[124:127]
	v_mfma_f32_16x16x32_bf16 v[120:123], v[156:159], v[170:173], v[120:123]
	v_mfma_f32_16x16x32_bf16 v[116:119], v[132:135], v[178:181], v[116:119]
	v_mfma_f32_16x16x32_bf16 v[96:99], v[156:159], v[196:199], v[96:99]
	v_mfma_f32_16x16x32_bf16 v[124:127], v[136:139], v[174:177], v[124:127]
	v_mfma_f32_16x16x32_bf16 v[120:123], v[160:163], v[174:177], v[120:123]
	v_mfma_f32_16x16x32_bf16 v[116:119], v[136:139], v[184:187], v[116:119]
	v_mfma_f32_16x16x32_bf16 v[112:115], v[156:159], v[178:181], v[112:115]
	v_mfma_f32_16x16x32_bf16 v[108:111], v[132:135], v[188:191], v[108:111]
	v_mfma_f32_16x16x32_bf16 v[104:107], v[156:159], v[188:191], v[104:107]
	v_mfma_f32_16x16x32_bf16 v[100:103], v[132:135], v[196:199], v[100:103]
	v_mfma_f32_16x16x32_bf16 v[96:99], v[160:163], v[200:203], v[96:99]
	v_mfma_f32_16x16x32_bf16 v[128:131], v[160:163], v[184:187], v[112:115]
	v_mfma_f32_16x16x32_bf16 v[166:169], v[136:139], v[192:195], v[108:111]
	v_mfma_f32_16x16x32_bf16 v[204:207], v[160:163], v[192:195], v[104:107]
	v_mfma_f32_16x16x32_bf16 v[208:211], v[136:139], v[200:203], v[100:103]
	s_setprio 0
	s_barrier
	ds_read_b128 v[100:103], v165
	ds_read_b128 v[104:107], v165 offset:1024
	ds_read_b128 v[108:111], v165 offset:2048
	ds_read_b128 v[112:115], v165 offset:3072
	s_barrier
; #define LDA(dst, b, h) _Pragma("unroll") for (int m = 0; m < 4; ++m) _Pragma("unroll") for (int k = 0; k < 2; ++k) \
;     dst[m][k] = *reinterpret_cast<const bf16x8*>((const char*)SA(b, h) + lds_byte8(wr * 64 + m * 16 + fr, k * 32 + fq * 8))
; #define LDB(dst, b, h) _Pragma("unroll") for (int n = 0; n < 2; ++n) _Pragma("unroll") for (int k = 0; k < 2; ++k) \
;     dst[n][k] = *reinterpret_cast<const bf16x8*>((const char*)SB(b, h) + lds_byte8(wc * 32 + n * 16 + fr, k * 32 + fq * 8))
; #define MMA(ai, bj, At_, Bt_) do { __builtin_amdgcn_s_setprio(1); \
;     _Pragma("unroll") for (int m = 0; m < 4; ++m) _Pragma("unroll") for (int n = 0; n < 2; ++n) _Pragma("unroll") for (int k = 0; k < 2; ++k) \
;       acc[ai][bj][m][n] = MFMA16(Bt_[n][k], At_[m][k], acc[ai][bj][m][n]); \
;     __builtin_amdgcn_s_setprio(0); } while (0)
; #define WAIT_V(n) asm volatile("s_waitcnt vmcnt(" #n ")" ::: "memory")
; #define WAIT_L(n) asm volatile("s_waitcnt lgkmcnt(" #n ")" ::: "memory")
; #define BAR __builtin_amdgcn_s_barrier()
; template <class FL, class FS>
; DI void gemm8_tile(char* shmc, const bf16_t* __restrict__ A, const bf16_t* __restrict__ Bt, const int K, const int brow, const int bcol, FL fl, FS fs) {
;     ...
;     BAR; WAIT_L(0); MMA(0, 0, At, B0); BAR;
;     LDB(B1, 0, 1); BAR; WAIT_L(0); MMA(0, 1, At, B1); BAR;
;     LDA(At, 0, 1); WAIT_V(4); BAR; WAIT_L(0); MMA(1, 0, At, B0); MMA(1, 1, At, B1); BAR; }
;   { LDB(B0, 1, 0); LDA(At, 1, 0); WAIT_V(2); BAR; WAIT_L(0); MMA(0, 0, At, B0); BAR;
	s_waitcnt lgkmcnt(0)
	s_setprio 1
	s_waitcnt lgkmcnt(3)
	v_mfma_f32_16x16x32_bf16 v[92:95], v[100:103], v[170:173], v[92:95]
	s_waitcnt lgkmcnt(1)
	v_mfma_f32_16x16x32_bf16 v[88:91], v[108:111], v[170:173], v[88:91]
	v_mfma_f32_16x16x32_bf16 v[84:87], v[100:103], v[178:181], v[84:87]
	v_mfma_f32_16x16x32_bf16 v[64:67], v[108:111], v[196:199], v[64:67]
	v_mfma_f32_16x16x32_bf16 v[92:95], v[104:107], v[174:177], v[92:95]
	s_waitcnt lgkmcnt(0)
	v_mfma_f32_16x16x32_bf16 v[88:91], v[112:115], v[174:177], v[88:91]
	v_mfma_f32_16x16x32_bf16 v[84:87], v[104:107], v[184:187], v[84:87]
	v_mfma_f32_16x16x32_bf16 v[80:83], v[108:111], v[178:181], v[80:83]
	v_mfma_f32_16x16x32_bf16 v[76:79], v[100:103], v[188:191], v[76:79]
	v_mfma_f32_16x16x32_bf16 v[72:75], v[108:111], v[188:191], v[72:75]
	v_mfma_f32_16x16x32_bf16 v[68:71], v[100:103], v[196:199], v[68:71]
	v_mfma_f32_16x16x32_bf16 v[64:67], v[112:115], v[200:203], v[64:67]
	v_mfma_f32_16x16x32_bf16 v[170:173], v[112:115], v[184:187], v[80:83]
	v_mfma_f32_16x16x32_bf16 v[174:177], v[104:107], v[192:195], v[76:79]
	v_mfma_f32_16x16x32_bf16 v[178:181], v[112:115], v[192:195], v[72:75]
	v_mfma_f32_16x16x32_bf16 v[184:187], v[104:107], v[200:203], v[68:71]
	s_setprio 0
	s_barrier
	s_nop 0
	ds_read_b128 v[68:71], v151 offset:16384
	ds_read_b128 v[72:75], v151 offset:17408
	ds_read_b128 v[76:79], v150 offset:16384
	ds_read_b128 v[80:83], v150 offset:17408
	ds_read_b128 v[188:191], v149 offset:16384
	ds_read_b128 v[192:195], v149 offset:17408
	ds_read_b128 v[196:199], v147 offset:16384
	ds_read_b128 v[200:203], v147 offset:17408
	s_waitcnt vmcnt(4)
	s_barrier
	s_waitcnt lgkmcnt(0)
	s_setprio 1
	s_waitcnt lgkmcnt(7)
	v_mfma_f32_16x16x32_bf16 v[60:63], v[132:135], v[68:71], v[60:63]
	v_mfma_f32_16x16x32_bf16 v[56:59], v[156:159], v[68:71], v[56:59]
	s_waitcnt lgkmcnt(3)
	v_mfma_f32_16x16x32_bf16 v[44:47], v[132:135], v[188:191], v[44:47]
	s_waitcnt lgkmcnt(1)
	v_mfma_f32_16x16x32_bf16 v[32:35], v[156:159], v[196:199], v[32:35]
	v_mfma_f32_16x16x32_bf16 v[60:63], v[136:139], v[72:75], v[60:63]
	v_mfma_f32_16x16x32_bf16 v[56:59], v[160:163], v[72:75], v[56:59]
	v_mfma_f32_16x16x32_bf16 v[52:55], v[132:135], v[76:79], v[52:55]
	v_mfma_f32_16x16x32_bf16 v[48:51], v[156:159], v[76:79], v[48:51]
	v_mfma_f32_16x16x32_bf16 v[44:47], v[136:139], v[192:195], v[44:47]
	v_mfma_f32_16x16x32_bf16 v[40:43], v[156:159], v[188:191], v[40:43]
	v_mfma_f32_16x16x32_bf16 v[36:39], v[132:135], v[196:199], v[36:39]
	s_waitcnt lgkmcnt(0)
	v_mfma_f32_16x16x32_bf16 v[32:35], v[160:163], v[200:203], v[32:35]
	v_mfma_f32_16x16x32_bf16 v[212:215], v[136:139], v[80:83], v[52:55]
	v_mfma_f32_16x16x32_bf16 v[216:219], v[160:163], v[80:83], v[48:51]
	v_mfma_f32_16x16x32_bf16 v[220:223], v[160:163], v[192:195], v[40:43]
	v_mfma_f32_16x16x32_bf16 v[132:135], v[136:139], v[200:203], v[36:39]
	s_setprio 0
	s_setprio 1
	v_mfma_f32_16x16x32_bf16 v[28:31], v[100:103], v[68:71], v[28:31]
	v_mfma_f32_16x16x32_bf16 v[24:27], v[108:111], v[68:71], v[24:27]
	v_mfma_f32_16x16x32_bf16 v[12:15], v[100:103], v[188:191], v[12:15]
	v_mfma_f32_16x16x32_bf16 v[0:3], v[108:111], v[196:199], v[0:3]
	v_mfma_f32_16x16x32_bf16 v[28:31], v[104:107], v[72:75], v[28:31]
	v_mfma_f32_16x16x32_bf16 v[24:27], v[112:115], v[72:75], v[24:27]
	v_mfma_f32_16x16x32_bf16 v[20:23], v[100:103], v[76:79], v[20:23]
	v_mfma_f32_16x16x32_bf16 v[16:19], v[108:111], v[76:79], v[16:19]
	v_mfma_f32_16x16x32_bf16 v[12:15], v[104:107], v[192:195], v[12:15]
	v_mfma_f32_16x16x32_bf16 v[8:11], v[108:111], v[188:191], v[8:11]
	v_mfma_f32_16x16x32_bf16 v[4:7], v[100:103], v[196:199], v[4:7]
	v_mfma_f32_16x16x32_bf16 v[0:3], v[112:115], v[200:203], v[0:3]
	v_mfma_f32_16x16x32_bf16 v[136:139], v[104:107], v[80:83], v[20:23]
	v_mfma_f32_16x16x32_bf16 v[156:159], v[112:115], v[80:83], v[16:19]
	v_mfma_f32_16x16x32_bf16 v[160:163], v[112:115], v[192:195], v[8:11]
	v_mfma_f32_16x16x32_bf16 v[188:191], v[104:107], v[200:203], v[4:7]
	s_setprio 0
	s_barrier
	s_nop 0
	ds_read_b128 v[4:7], v155
	ds_read_b128 v[8:11], v155 offset:1024
	ds_read_b128 v[192:195], v155 offset:2048
	ds_read_b128 v[196:199], v155 offset:3072
	ds_read_b128 v[16:19], v151 offset:32768
	ds_read_b128 v[20:23], v151 offset:33792
	ds_read_b128 v[36:39], v150 offset:32768
	ds_read_b128 v[40:43], v150 offset:33792
	ds_read_b128 v[48:51], v149 offset:32768
	ds_read_b128 v[52:55], v149 offset:33792
	ds_read_b128 v[200:203], v147 offset:32768
	ds_read_b128 v[224:227], v147 offset:33792
	s_waitcnt vmcnt(2)
	s_barrier
; #define LDA(dst, b, h) _Pragma("unroll") for (int m = 0; m < 4; ++m) _Pragma("unroll") for (int k = 0; k < 2; ++k) \
;     dst[m][k] = *reinterpret_cast<const bf16x8*>((const char*)SA(b, h) + lds_byte8(wr * 64 + m * 16 + fr, k * 32 + fq * 8))
; #define LDB(dst, b, h) _Pragma("unroll") for (int n = 0; n < 2; ++n) _Pragma("unroll") for (int k = 0; k < 2; ++k) \
;     dst[n][k] = *reinterpret_cast<const bf16x8*>((const char*)SB(b, h) + lds_byte8(wc * 32 + n * 16 + fr, k * 32 + fq * 8))
; #define MMA(ai, bj, At_, Bt_) do { __builtin_amdgcn_s_setprio(1); \
;     _Pragma("unroll") for (int m = 0; m < 4; ++m) _Pragma("unroll") for (int n = 0; n < 2; ++n) _Pragma("unroll") for (int k = 0; k < 2; ++k) \
;       acc[ai][bj][m][n] = MFMA16(Bt_[n][k], At_[m][k], acc[ai][bj][m][n]); \
;     __builtin_amdgcn_s_setprio(0); } while (0)
; #define WAIT_V(n) asm volatile("s_waitcnt vmcnt(" #n ")" ::: "memory")
; #define WAIT_L(n) asm volatile("s_waitcnt lgkmcnt(" #n ")" ::: "memory")
; #define BAR __builtin_amdgcn_s_barrier()
; template <class FL, class FS>
; DI void gemm8_tile(char* shmc, const bf16_t* __restrict__ A, const bf16_t* __restrict__ Bt, const int K, const int brow, const int bcol, FL fl, FS fs) {
;     ...
;   { LDB(B0, 1, 0); LDA(At, 1, 0); WAIT_V(2); BAR; WAIT_L(0); MMA(0, 0, At, B0); BAR;
;     LDB(B1, 1, 1); WAIT_V(0); BAR; WAIT_L(0); MMA(0, 1, At, B1); BAR;
;     LDA(At, 1, 1); BAR; WAIT_L(0); MMA(1, 0, At, B0); MMA(1, 1, At, B1); BAR; }
;   if (wr == 0) BAR;
	s_waitcnt lgkmcnt(0)
	s_setprio 1
	s_waitcnt lgkmcnt(7)
	v_mfma_f32_16x16x32_bf16 v[68:71], v[4:7], v[16:19], v[124:127]
	s_waitcnt lgkmcnt(6)
	v_mfma_f32_16x16x32_bf16 v[108:111], v[8:11], v[20:23], v[68:71]
	v_mfma_f32_16x16x32_bf16 v[68:71], v[192:195], v[16:19], v[120:123]
	v_mfma_f32_16x16x32_bf16 v[112:115], v[196:199], v[20:23], v[68:71]
	s_waitcnt lgkmcnt(5)
	v_mfma_f32_16x16x32_bf16 v[68:71], v[4:7], v[36:39], v[116:119]
	s_waitcnt lgkmcnt(4)
	v_mfma_f32_16x16x32_bf16 v[104:107], v[8:11], v[40:43], v[68:71]
	v_mfma_f32_16x16x32_bf16 v[68:71], v[192:195], v[36:39], v[128:131]
	v_mfma_f32_16x16x32_bf16 v[100:103], v[196:199], v[40:43], v[68:71]
	s_waitcnt lgkmcnt(3)
	v_mfma_f32_16x16x32_bf16 v[68:71], v[4:7], v[48:51], v[166:169]
	s_waitcnt lgkmcnt(2)
	v_mfma_f32_16x16x32_bf16 v[80:83], v[8:11], v[52:55], v[68:71]
	v_mfma_f32_16x16x32_bf16 v[68:71], v[192:195], v[48:51], v[204:207]
	v_mfma_f32_16x16x32_bf16 v[76:79], v[196:199], v[52:55], v[68:71]
	s_waitcnt lgkmcnt(1)
	v_mfma_f32_16x16x32_bf16 v[68:71], v[4:7], v[200:203], v[208:211]
	s_waitcnt lgkmcnt(0)
	v_mfma_f32_16x16x32_bf16 v[72:75], v[8:11], v[224:227], v[68:71]
	v_mfma_f32_16x16x32_bf16 v[68:71], v[192:195], v[200:203], v[96:99]
	v_mfma_f32_16x16x32_bf16 v[68:71], v[196:199], v[224:227], v[68:71]
	s_setprio 0
	s_barrier
	ds_read_b128 v[128:131], v153
	ds_read_b128 v[164:167], v153 offset:1024
	ds_read_b128 v[204:207], v153 offset:2048
	ds_read_b128 v[152:155], v153 offset:3072
	s_waitcnt vmcnt(0)
	s_barrier
	s_waitcnt lgkmcnt(0)
	s_setprio 1
	s_waitcnt lgkmcnt(3)
	v_mfma_f32_16x16x32_bf16 v[92:95], v[128:131], v[16:19], v[92:95]
	s_waitcnt lgkmcnt(1)
	v_mfma_f32_16x16x32_bf16 v[16:19], v[204:207], v[16:19], v[88:91]
	s_waitcnt lgkmcnt(0)
	v_mfma_f32_16x16x32_bf16 v[120:123], v[152:155], v[20:23], v[16:19]
	v_mfma_f32_16x16x32_bf16 v[16:19], v[128:131], v[36:39], v[84:87]
	v_mfma_f32_16x16x32_bf16 v[116:119], v[164:167], v[40:43], v[16:19]
	v_mfma_f32_16x16x32_bf16 v[16:19], v[204:207], v[36:39], v[170:173]
	v_mfma_f32_16x16x32_bf16 v[96:99], v[152:155], v[40:43], v[16:19]
	v_mfma_f32_16x16x32_bf16 v[16:19], v[128:131], v[48:51], v[174:177]
	v_mfma_f32_16x16x32_bf16 v[124:127], v[164:167], v[20:23], v[92:95]
	v_mfma_f32_16x16x32_bf16 v[92:95], v[164:167], v[52:55], v[16:19]
	v_mfma_f32_16x16x32_bf16 v[16:19], v[204:207], v[48:51], v[178:181]
	v_mfma_f32_16x16x32_bf16 v[88:91], v[152:155], v[52:55], v[16:19]
	v_mfma_f32_16x16x32_bf16 v[16:19], v[128:131], v[200:203], v[184:187]
	v_mfma_f32_16x16x32_bf16 v[84:87], v[164:167], v[224:227], v[16:19]
	v_mfma_f32_16x16x32_bf16 v[16:19], v[204:207], v[200:203], v[64:67]
	v_mfma_f32_16x16x32_bf16 v[64:67], v[152:155], v[224:227], v[16:19]
	s_setprio 0
	s_barrier
	ds_read_b128 v[168:171], v151 offset:49152
	ds_read_b128 v[172:175], v151 offset:50176
	ds_read_b128 v[176:179], v150 offset:49152
	ds_read_b128 v[184:187], v150 offset:50176
	ds_read_b128 v[200:203], v149 offset:49152
	ds_read_b128 v[148:151], v149 offset:50176
	ds_read_b128 v[208:211], v147 offset:49152
	ds_read_b128 v[224:227], v147 offset:50176
	s_barrier
	s_waitcnt lgkmcnt(0)
	s_setprio 1
	s_waitcnt lgkmcnt(7)
	v_mfma_f32_16x16x32_bf16 v[16:19], v[4:7], v[168:171], v[60:63]
	s_waitcnt lgkmcnt(6)
	v_mfma_f32_16x16x32_bf16 v[52:55], v[8:11], v[172:175], v[16:19]
	v_mfma_f32_16x16x32_bf16 v[16:19], v[192:195], v[168:171], v[56:59]
	v_mfma_f32_16x16x32_bf16 v[48:51], v[196:199], v[172:175], v[16:19]
	s_waitcnt lgkmcnt(5)
	v_mfma_f32_16x16x32_bf16 v[16:19], v[4:7], v[176:179], v[212:215]
	s_waitcnt lgkmcnt(4)
	v_mfma_f32_16x16x32_bf16 v[40:43], v[8:11], v[184:187], v[16:19]
	v_mfma_f32_16x16x32_bf16 v[16:19], v[192:195], v[176:179], v[216:219]
	v_mfma_f32_16x16x32_bf16 v[36:39], v[196:199], v[184:187], v[16:19]
	s_waitcnt lgkmcnt(3)
	v_mfma_f32_16x16x32_bf16 v[16:19], v[4:7], v[200:203], v[44:47]
	s_waitcnt lgkmcnt(1)
	v_mfma_f32_16x16x32_bf16 v[4:7], v[4:7], v[208:211], v[132:135]
	v_mfma_f32_16x16x32_bf16 v[20:23], v[8:11], v[148:151], v[16:19]
	v_mfma_f32_16x16x32_bf16 v[16:19], v[192:195], v[200:203], v[220:223]
	s_waitcnt lgkmcnt(0)
	v_mfma_f32_16x16x32_bf16 v[8:11], v[8:11], v[224:227], v[4:7]
	v_mfma_f32_16x16x32_bf16 v[4:7], v[192:195], v[208:211], v[32:35]
	v_mfma_f32_16x16x32_bf16 v[16:19], v[196:199], v[148:151], v[16:19]
	v_mfma_f32_16x16x32_bf16 v[4:7], v[196:199], v[224:227], v[4:7]
	s_setprio 0
	s_setprio 1
	v_mfma_f32_16x16x32_bf16 v[24:27], v[204:207], v[168:171], v[24:27]
	v_mfma_f32_16x16x32_bf16 v[28:31], v[128:131], v[168:171], v[28:31]
	v_mfma_f32_16x16x32_bf16 v[56:59], v[152:155], v[172:175], v[24:27]
	v_mfma_f32_16x16x32_bf16 v[24:27], v[128:131], v[176:179], v[136:139]
	v_mfma_f32_16x16x32_bf16 v[12:15], v[128:131], v[200:203], v[12:15]
	v_mfma_f32_16x16x32_bf16 v[60:63], v[164:167], v[172:175], v[28:31]
	v_mfma_f32_16x16x32_bf16 v[44:47], v[164:167], v[184:187], v[24:27]
	v_mfma_f32_16x16x32_bf16 v[24:27], v[204:207], v[176:179], v[156:159]
	v_mfma_f32_16x16x32_bf16 v[28:31], v[164:167], v[148:151], v[12:15]
	v_mfma_f32_16x16x32_bf16 v[12:15], v[204:207], v[200:203], v[160:163]
	v_mfma_f32_16x16x32_bf16 v[32:35], v[152:155], v[184:187], v[24:27]
	v_mfma_f32_16x16x32_bf16 v[24:27], v[152:155], v[148:151], v[12:15]
	v_mfma_f32_16x16x32_bf16 v[12:15], v[128:131], v[208:211], v[188:191]
	v_mfma_f32_16x16x32_bf16 v[0:3], v[204:207], v[208:211], v[0:3]
	v_mfma_f32_16x16x32_bf16 v[12:15], v[164:167], v[224:227], v[12:15]
	v_mfma_f32_16x16x32_bf16 v[0:3], v[152:155], v[224:227], v[0:3]
	s_setprio 0
	v_cmp_gt_u32_e32 vcc, s54, v140
	s_barrier
	s_and_saveexec_b64 s[0:1], vcc
	s_cbranch_execz .Lg3_wr0
	s_barrier

; #define STAGE(P, BASE, br, kt) do { const long _g = (long)(br) * K + (long)(kt) * 64; \
;     _Pragma("unroll") for (int _i = 0; _i < 2; ++_i) { const int _b = tidx * 16 + _i * 8192; int _r, _c; stage_rc8(_b, _r, _c); \
;       __builtin_amdgcn_global_load_lds((const unsigned*)(BASE + _g + (long)_r * K + _c), (LAS unsigned*)((LAS char*)(P) + _b), 16, 0, 0); } } while (0)
; #define LDA(dst, b, h) _Pragma("unroll") for (int m = 0; m < 4; ++m) _Pragma("unroll") for (int k = 0; k < 2; ++k) \
;     dst[m][k] = *reinterpret_cast<const bf16x8*>((const char*)SA(b, h) + lds_byte8(wr * 64 + m * 16 + fr, k * 32 + fq * 8))
; #define LDB(dst, b, h) _Pragma("unroll") for (int n = 0; n < 2; ++n) _Pragma("unroll") for (int k = 0; k < 2; ++k) \
;     dst[n][k] = *reinterpret_cast<const bf16x8*>((const char*)SB(b, h) + lds_byte8(wc * 32 + n * 16 + fr, k * 32 + fq * 8))
; #define MMA(ai, bj, At_, Bt_) do { __builtin_amdgcn_s_setprio(1); \
;     _Pragma("unroll") for (int m = 0; m < 4; ++m) _Pragma("unroll") for (int n = 0; n < 2; ++n) _Pragma("unroll") for (int k = 0; k < 2; ++k) \
;       acc[ai][bj][m][n] = MFMA16(Bt_[n][k], At_[m][k], acc[ai][bj][m][n]); \
;     __builtin_amdgcn_s_setprio(0); } while (0)
; #define WAIT_V(n) asm volatile("s_waitcnt vmcnt(" #n ")" ::: "memory")
; #define WAIT_L(n) asm volatile("s_waitcnt lgkmcnt(" #n ")" ::: "memory")
; #define BAR __builtin_amdgcn_s_barrier()
; #define SCHED __builtin_amdgcn_sched_barrier(0)
; template <class FL, class FS>
; DI void gemm8_tile(char* shmc, const bf16_t* __restrict__ A, const bf16_t* __restrict__ Bt, const int K, const int brow, const int bcol, FL fl, FS fs) {
;     ...
;     LDB(B0, 0, 0); SCHED; LDA(At, 0, 0); STAGE(SA(1, 1), A, brow + HALF, t + 1);
;     WAIT_L(8); BAR; WAIT_L(0); MMA(0, 0, At, B0); BAR; SCHED;
;     LDB(B1, 0, 1); STAGE(SB(0, 0), Bt, bcol, t + 2);
;     BAR; WAIT_L(0); MMA(0, 1, At, B1); BAR;
;     LDA(At, 0, 1); STAGE(SA(0, 0), A, brow, t + 2);
;     BAR; WAIT_L(0); MMA(1, 0, At, B0); BAR; SCHED;
;     STAGE(SB(0, 1), Bt, bcol + HALF, t + 2);
;     WAIT_V(6); BAR; MMA(1, 1, At, B1); BAR;
.Lg4_p1skip:
	s_nop 0
	s_barrier
	s_waitcnt lgkmcnt(0)
	s_setprio 1
	s_waitcnt lgkmcnt(0)
	v_mfma_f32_16x16x32_bf16 v[124:127], v[172:175], v[192:195], v[124:127]
	v_mfma_f32_16x16x32_bf16 v[120:123], v[184:187], v[192:195], v[120:123]
	v_mfma_f32_16x16x32_bf16 v[116:119], v[172:175], v[200:203], v[116:119]
	v_mfma_f32_16x16x32_bf16 v[112:115], v[184:187], v[200:203], v[112:115]
	v_mfma_f32_16x16x32_bf16 v[108:111], v[172:175], v[208:211], v[108:111]
	v_mfma_f32_16x16x32_bf16 v[104:107], v[184:187], v[208:211], v[104:107]
	v_mfma_f32_16x16x32_bf16 v[100:103], v[172:175], v[216:219], v[100:103]
	v_mfma_f32_16x16x32_bf16 v[96:99], v[184:187], v[216:219], v[96:99]
	v_mfma_f32_16x16x32_bf16 v[124:127], v[176:179], v[196:199], v[124:127]
	v_mfma_f32_16x16x32_bf16 v[120:123], v[188:191], v[196:199], v[120:123]
	v_mfma_f32_16x16x32_bf16 v[116:119], v[176:179], v[204:207], v[116:119]
	v_mfma_f32_16x16x32_bf16 v[112:115], v[188:191], v[204:207], v[112:115]
	v_mfma_f32_16x16x32_bf16 v[108:111], v[176:179], v[212:215], v[108:111]
	v_mfma_f32_16x16x32_bf16 v[104:107], v[188:191], v[212:215], v[104:107]
	v_mfma_f32_16x16x32_bf16 v[100:103], v[176:179], v[220:223], v[100:103]
	v_mfma_f32_16x16x32_bf16 v[96:99], v[188:191], v[220:223], v[96:99]
	s_setprio 0
	s_barrier
	v_lshl_add_u64 v[242:243], s[22:23], 0, v[134:135]
	v_readfirstlane_b32 s1, v149
	v_lshl_add_u64 v[244:245], v[242:243], 0, s[38:39]
	s_mov_b32 m0, s1
	ds_read_b128 v[224:227], v166
	ds_read_b128 v[228:231], v166 offset:1024
	ds_read_b128 v[232:235], v166 offset:2048
	ds_read_b128 v[236:239], v166 offset:3072
	global_load_lds_dwordx4 v[244:245], off
	v_lshl_add_u64 v[244:245], s[22:23], 0, v[136:137]
	v_readfirstlane_b32 s1, v155
	v_lshl_add_u64 v[246:247], v[244:245], 0, s[38:39]
	s_mov_b32 m0, s1
	s_nop 0
	global_load_lds_dwordx4 v[246:247], off
	s_barrier
	s_waitcnt lgkmcnt(0)
	s_setprio 1
	s_waitcnt lgkmcnt(0)
	v_mfma_f32_16x16x32_bf16 v[92:95], v[224:227], v[192:195], v[92:95]
	v_mfma_f32_16x16x32_bf16 v[88:91], v[232:235], v[192:195], v[88:91]
	v_mfma_f32_16x16x32_bf16 v[84:87], v[224:227], v[200:203], v[84:87]
	v_mfma_f32_16x16x32_bf16 v[80:83], v[232:235], v[200:203], v[80:83]
	v_mfma_f32_16x16x32_bf16 v[76:79], v[224:227], v[208:211], v[76:79]
	v_mfma_f32_16x16x32_bf16 v[72:75], v[232:235], v[208:211], v[72:75]
	v_mfma_f32_16x16x32_bf16 v[68:71], v[224:227], v[216:219], v[68:71]
	v_mfma_f32_16x16x32_bf16 v[64:67], v[232:235], v[216:219], v[64:67]
	v_mfma_f32_16x16x32_bf16 v[92:95], v[228:231], v[196:199], v[92:95]
	v_mfma_f32_16x16x32_bf16 v[88:91], v[236:239], v[196:199], v[88:91]
	v_mfma_f32_16x16x32_bf16 v[84:87], v[228:231], v[204:207], v[84:87]
	v_mfma_f32_16x16x32_bf16 v[80:83], v[236:239], v[204:207], v[80:83]
	v_mfma_f32_16x16x32_bf16 v[76:79], v[228:231], v[212:215], v[76:79]
	v_mfma_f32_16x16x32_bf16 v[72:75], v[236:239], v[212:215], v[72:75]
	v_mfma_f32_16x16x32_bf16 v[68:71], v[228:231], v[220:223], v[68:71]
	v_mfma_f32_16x16x32_bf16 v[64:67], v[236:239], v[220:223], v[64:67]
	s_setprio 0
	v_readfirstlane_b32 s1, v147
	v_lshl_add_u64 v[246:247], v[180:181], 0, s[40:41]
	s_mov_b32 m0, s1
	v_readfirstlane_b32 s1, v153
	s_barrier
	ds_read_b128 v[192:195], v152 offset:16384
	ds_read_b128 v[196:199], v152 offset:17408
	ds_read_b128 v[200:203], v151 offset:16384
	ds_read_b128 v[204:207], v151 offset:17408
	ds_read_b128 v[208:211], v150 offset:16384
	ds_read_b128 v[212:215], v150 offset:17408
	ds_read_b128 v[216:219], v148 offset:16384
	ds_read_b128 v[220:223], v148 offset:17408
	global_load_lds_dwordx4 v[246:247], off
	v_lshl_add_u64 v[246:247], v[240:241], 0, s[40:41]
	s_mov_b32 m0, s1
	s_nop 0
	global_load_lds_dwordx4 v[246:247], off
	s_barrier
	s_waitcnt lgkmcnt(0)
	s_setprio 1
	s_waitcnt lgkmcnt(0)
	v_mfma_f32_16x16x32_bf16 v[60:63], v[172:175], v[192:195], v[60:63]
	v_mfma_f32_16x16x32_bf16 v[56:59], v[184:187], v[192:195], v[56:59]
	v_mfma_f32_16x16x32_bf16 v[52:55], v[172:175], v[200:203], v[52:55]
	v_mfma_f32_16x16x32_bf16 v[48:51], v[184:187], v[200:203], v[48:51]
	v_mfma_f32_16x16x32_bf16 v[44:47], v[172:175], v[208:211], v[44:47]
	v_mfma_f32_16x16x32_bf16 v[40:43], v[184:187], v[208:211], v[40:43]
	v_mfma_f32_16x16x32_bf16 v[36:39], v[172:175], v[216:219], v[36:39]
	v_mfma_f32_16x16x32_bf16 v[32:35], v[184:187], v[216:219], v[32:35]
	v_mfma_f32_16x16x32_bf16 v[60:63], v[176:179], v[196:199], v[60:63]
	v_mfma_f32_16x16x32_bf16 v[56:59], v[188:191], v[196:199], v[56:59]
	v_mfma_f32_16x16x32_bf16 v[52:55], v[176:179], v[204:207], v[52:55]
	v_mfma_f32_16x16x32_bf16 v[48:51], v[188:191], v[204:207], v[48:51]
	v_mfma_f32_16x16x32_bf16 v[44:47], v[176:179], v[212:215], v[44:47]
	v_mfma_f32_16x16x32_bf16 v[40:43], v[188:191], v[212:215], v[40:43]
	v_mfma_f32_16x16x32_bf16 v[36:39], v[176:179], v[220:223], v[36:39]
	v_mfma_f32_16x16x32_bf16 v[32:35], v[188:191], v[220:223], v[32:35]
	s_setprio 0
	s_barrier
	v_readfirstlane_b32 s1, v157
	v_lshl_add_u64 v[172:173], v[242:243], 0, s[42:43]
	s_mov_b32 m0, s1
	v_readfirstlane_b32 s1, v158
	global_load_lds_dwordx4 v[172:173], off
	v_lshl_add_u64 v[172:173], v[244:245], 0, s[42:43]
	s_mov_b32 m0, s1
	s_nop 0
	global_load_lds_dwordx4 v[172:173], off
	s_cmp_eq_u32 s0, -2
	s_cselect_b32 s1, s98, 0
	s_cmp_lg_u32 s1, 0
	s_cbranch_scc1 .Lg4_w22
	s_waitcnt vmcnt(6)
; #define STAGE(P, BASE, br, kt) do { const long _g = (long)(br) * K + (long)(kt) * 64; \
;     _Pragma("unroll") for (int _i = 0; _i < 2; ++_i) { const int _b = tidx * 16 + _i * 8192; int _r, _c; stage_rc8(_b, _r, _c); \
;       __builtin_amdgcn_global_load_lds((const unsigned*)(BASE + _g + (long)_r * K + _c), (LAS unsigned*)((LAS char*)(P) + _b), 16, 0, 0); } } while (0)
; #define LDA(dst, b, h) _Pragma("unroll") for (int m = 0; m < 4; ++m) _Pragma("unroll") for (int k = 0; k < 2; ++k) \
;     dst[m][k] = *reinterpret_cast<const bf16x8*>((const char*)SA(b, h) + lds_byte8(wr * 64 + m * 16 + fr, k * 32 + fq * 8))
; #define LDB(dst, b, h) _Pragma("unroll") for (int n = 0; n < 2; ++n) _Pragma("unroll") for (int k = 0; k < 2; ++k) \
;     dst[n][k] = *reinterpret_cast<const bf16x8*>((const char*)SB(b, h) + lds_byte8(wc * 32 + n * 16 + fr, k * 32 + fq * 8))
; #define MMA(ai, bj, At_, Bt_) do { __builtin_amdgcn_s_setprio(1); \
;     _Pragma("unroll") for (int m = 0; m < 4; ++m) _Pragma("unroll") for (int n = 0; n < 2; ++n) _Pragma("unroll") for (int k = 0; k < 2; ++k) \
;       acc[ai][bj][m][n] = MFMA16(Bt_[n][k], At_[m][k], acc[ai][bj][m][n]); \
;     __builtin_amdgcn_s_setprio(0); } while (0)
; #define WAIT_V(n) asm volatile("s_waitcnt vmcnt(" #n ")" ::: "memory")
; #define WAIT_L(n) asm volatile("s_waitcnt lgkmcnt(" #n ")" ::: "memory")
; #define BAR __builtin_amdgcn_s_barrier()
; #define SCHED __builtin_amdgcn_sched_barrier(0)
; template <class FL, class FS>
; DI void gemm8_tile(char* shmc, const bf16_t* __restrict__ A, const bf16_t* __restrict__ Bt, const int K, const int brow, const int bcol, FL fl, FS fs) {
;     ...
;     WAIT_V(6); BAR; MMA(1, 1, At, B1); BAR;
;     LDB(B0, 1, 0); SCHED; LDA(At, 1, 0); STAGE(SA(0, 1), A, brow + HALF, t + 2);
;     WAIT_L(8); BAR; WAIT_L(0); MMA(0, 0, At, B0); BAR; SCHED;
;     LDB(B1, 1, 1); STAGE(SB(1, 0), Bt, bcol, t + 3);
;     BAR; WAIT_L(0); MMA(0, 1, At, B1); BAR;
;     LDA(At, 1, 1); STAGE(SA(1, 0), A, brow, t + 3);
;     BAR; WAIT_L(0); MMA(1, 0, At, B0); BAR; SCHED;
.Lg4_wd:
	s_barrier
	s_setprio 1
	v_mfma_f32_16x16x32_bf16 v[28:31], v[224:227], v[192:195], v[28:31]
	v_mfma_f32_16x16x32_bf16 v[24:27], v[232:235], v[192:195], v[24:27]
	v_mfma_f32_16x16x32_bf16 v[20:23], v[224:227], v[200:203], v[20:23]
	v_mfma_f32_16x16x32_bf16 v[16:19], v[232:235], v[200:203], v[16:19]
	v_mfma_f32_16x16x32_bf16 v[12:15], v[224:227], v[208:211], v[12:15]
	v_mfma_f32_16x16x32_bf16 v[8:11], v[232:235], v[208:211], v[8:11]
	v_mfma_f32_16x16x32_bf16 v[4:7], v[224:227], v[216:219], v[4:7]
	v_mfma_f32_16x16x32_bf16 v[0:3], v[232:235], v[216:219], v[0:3]
	v_mfma_f32_16x16x32_bf16 v[28:31], v[228:231], v[196:199], v[28:31]
	v_mfma_f32_16x16x32_bf16 v[24:27], v[236:239], v[196:199], v[24:27]
	v_mfma_f32_16x16x32_bf16 v[20:23], v[228:231], v[204:207], v[20:23]
	v_mfma_f32_16x16x32_bf16 v[16:19], v[236:239], v[204:207], v[16:19]
	v_mfma_f32_16x16x32_bf16 v[12:15], v[228:231], v[212:215], v[12:15]
	v_mfma_f32_16x16x32_bf16 v[8:11], v[236:239], v[212:215], v[8:11]
	v_mfma_f32_16x16x32_bf16 v[4:7], v[228:231], v[220:223], v[4:7]
	v_mfma_f32_16x16x32_bf16 v[0:3], v[236:239], v[220:223], v[0:3]
	s_setprio 0
	s_barrier
	ds_read_b128 v[172:175], v156
	ds_read_b128 v[176:179], v156 offset:1024
	ds_read_b128 v[184:187], v156 offset:2048
	ds_read_b128 v[188:191], v156 offset:3072
	v_readfirstlane_b32 s1, v159
	v_lshl_add_u64 v[224:225], v[180:181], 0, s[44:45]
	s_mov_b32 m0, s1
	v_readfirstlane_b32 s1, v160
	ds_read_b128 v[192:195], v152 offset:32768
	ds_read_b128 v[196:199], v152 offset:33792
	ds_read_b128 v[200:203], v151 offset:32768
	ds_read_b128 v[204:207], v151 offset:33792
	ds_read_b128 v[208:211], v150 offset:32768
	ds_read_b128 v[212:215], v150 offset:33792
	ds_read_b128 v[216:219], v148 offset:32768
	ds_read_b128 v[220:223], v148 offset:33792
	global_load_lds_dwordx4 v[224:225], off
	v_lshl_add_u64 v[224:225], v[240:241], 0, s[44:45]
	s_mov_b32 m0, s1
	s_nop 0
	global_load_lds_dwordx4 v[224:225], off
	s_nop 0
	s_barrier
	s_waitcnt lgkmcnt(0)
	s_setprio 1
	s_waitcnt lgkmcnt(0)
	v_mfma_f32_16x16x32_bf16 v[124:127], v[172:175], v[192:195], v[124:127]
	v_mfma_f32_16x16x32_bf16 v[120:123], v[184:187], v[192:195], v[120:123]
	v_mfma_f32_16x16x32_bf16 v[116:119], v[172:175], v[200:203], v[116:119]
	v_mfma_f32_16x16x32_bf16 v[112:115], v[184:187], v[200:203], v[112:115]
	v_mfma_f32_16x16x32_bf16 v[108:111], v[172:175], v[208:211], v[108:111]
	v_mfma_f32_16x16x32_bf16 v[104:107], v[184:187], v[208:211], v[104:107]
	v_mfma_f32_16x16x32_bf16 v[100:103], v[172:175], v[216:219], v[100:103]
	v_mfma_f32_16x16x32_bf16 v[96:99], v[184:187], v[216:219], v[96:99]
	v_mfma_f32_16x16x32_bf16 v[124:127], v[176:179], v[196:199], v[124:127]
	v_mfma_f32_16x16x32_bf16 v[120:123], v[188:191], v[196:199], v[120:123]
	v_mfma_f32_16x16x32_bf16 v[116:119], v[176:179], v[204:207], v[116:119]
	v_mfma_f32_16x16x32_bf16 v[112:115], v[188:191], v[204:207], v[112:115]
	v_mfma_f32_16x16x32_bf16 v[108:111], v[176:179], v[212:215], v[108:111]
	v_mfma_f32_16x16x32_bf16 v[104:107], v[188:191], v[212:215], v[104:107]
	v_mfma_f32_16x16x32_bf16 v[100:103], v[176:179], v[220:223], v[100:103]
	v_mfma_f32_16x16x32_bf16 v[96:99], v[188:191], v[220:223], v[96:99]
	s_setprio 0
	s_barrier
	v_readfirstlane_b32 s1, v161
	v_lshl_add_u64 v[246:247], v[242:243], 0, s[46:47]
	s_mov_b32 m0, s1
	v_readfirstlane_b32 s1, v162
	ds_read_b128 v[224:227], v154
	ds_read_b128 v[228:231], v154 offset:1024
	ds_read_b128 v[232:235], v154 offset:2048
	ds_read_b128 v[236:239], v154 offset:3072
	global_load_lds_dwordx4 v[246:247], off
	v_lshl_add_u64 v[246:247], v[244:245], 0, s[46:47]
	s_mov_b32 m0, s1
	s_nop 0
	global_load_lds_dwordx4 v[246:247], off
	s_barrier
	s_waitcnt lgkmcnt(0)
	s_setprio 1
	s_waitcnt lgkmcnt(0)
	v_mfma_f32_16x16x32_bf16 v[92:95], v[224:227], v[192:195], v[92:95]
	v_mfma_f32_16x16x32_bf16 v[88:91], v[232:235], v[192:195], v[88:91]
	v_mfma_f32_16x16x32_bf16 v[84:87], v[224:227], v[200:203], v[84:87]
	v_mfma_f32_16x16x32_bf16 v[80:83], v[232:235], v[200:203], v[80:83]
	v_mfma_f32_16x16x32_bf16 v[76:79], v[224:227], v[208:211], v[76:79]
	v_mfma_f32_16x16x32_bf16 v[72:75], v[232:235], v[208:211], v[72:75]
	v_mfma_f32_16x16x32_bf16 v[68:71], v[224:227], v[216:219], v[68:71]
	v_mfma_f32_16x16x32_bf16 v[64:67], v[232:235], v[216:219], v[64:67]
	v_mfma_f32_16x16x32_bf16 v[92:95], v[228:231], v[196:199], v[92:95]
	v_mfma_f32_16x16x32_bf16 v[88:91], v[236:239], v[196:199], v[88:91]
	v_mfma_f32_16x16x32_bf16 v[84:87], v[228:231], v[204:207], v[84:87]
	v_mfma_f32_16x16x32_bf16 v[80:83], v[236:239], v[204:207], v[80:83]
	v_mfma_f32_16x16x32_bf16 v[76:79], v[228:231], v[212:215], v[76:79]
	v_mfma_f32_16x16x32_bf16 v[72:75], v[236:239], v[212:215], v[72:75]
	v_mfma_f32_16x16x32_bf16 v[68:71], v[228:231], v[220:223], v[68:71]
	v_mfma_f32_16x16x32_bf16 v[64:67], v[236:239], v[220:223], v[64:67]
	s_setprio 0
	v_readfirstlane_b32 s1, v163
	v_lshl_add_u64 v[180:181], v[180:181], 0, s[48:49]
	s_mov_b32 m0, s1
	v_readfirstlane_b32 s1, v164
	s_barrier
	ds_read_b128 v[192:195], v152 offset:49152
	ds_read_b128 v[196:199], v152 offset:50176
	ds_read_b128 v[200:203], v151 offset:49152
	ds_read_b128 v[204:207], v151 offset:50176
	ds_read_b128 v[208:211], v150 offset:49152
	ds_read_b128 v[212:215], v150 offset:50176
	ds_read_b128 v[216:219], v148 offset:49152
	ds_read_b128 v[220:223], v148 offset:50176
	global_load_lds_dwordx4 v[180:181], off
	v_lshl_add_u64 v[180:181], v[240:241], 0, s[48:49]
	s_mov_b32 m0, s1
	s_nop 0
	global_load_lds_dwordx4 v[180:181], off
	s_barrier
; #define STAGE(P, BASE, br, kt) do { const long _g = (long)(br) * K + (long)(kt) * 64; \
;     _Pragma("unroll") for (int _i = 0; _i < 2; ++_i) { const int _b = tidx * 16 + _i * 8192; int _r, _c; stage_rc8(_b, _r, _c); \
;       __builtin_amdgcn_global_load_lds((const unsigned*)(BASE + _g + (long)_r * K + _c), (LAS unsigned*)((LAS char*)(P) + _b), 16, 0, 0); } } while (0)
; #define LDA(dst, b, h) _Pragma("unroll") for (int m = 0; m < 4; ++m) _Pragma("unroll") for (int k = 0; k < 2; ++k) \
;     dst[m][k] = *reinterpret_cast<const bf16x8*>((const char*)SA(b, h) + lds_byte8(wr * 64 + m * 16 + fr, k * 32 + fq * 8))
; #define LDB(dst, b, h) _Pragma("unroll") for (int n = 0; n < 2; ++n) _Pragma("unroll") for (int k = 0; k < 2; ++k) \
;     dst[n][k] = *reinterpret_cast<const bf16x8*>((const char*)SB(b, h) + lds_byte8(wc * 32 + n * 16 + fr, k * 32 + fq * 8))
; #define MMA(ai, bj, At_, Bt_) do { __builtin_amdgcn_s_setprio(1); \
;     _Pragma("unroll") for (int m = 0; m < 4; ++m) _Pragma("unroll") for (int n = 0; n < 2; ++n) _Pragma("unroll") for (int k = 0; k < 2; ++k) \
;       acc[ai][bj][m][n] = MFMA16(Bt_[n][k], At_[m][k], acc[ai][bj][m][n]); \
;     __builtin_amdgcn_s_setprio(0); } while (0)
; #define WAIT_V(n) asm volatile("s_waitcnt vmcnt(" #n ")" ::: "memory")
; #define WAIT_L(n) asm volatile("s_waitcnt lgkmcnt(" #n ")" ::: "memory")
; #define BAR __builtin_amdgcn_s_barrier()
; #define SCHED __builtin_amdgcn_sched_barrier(0)
; template <class FL, class FS>
; DI void gemm8_tile(char* shmc, const bf16_t* __restrict__ A, const bf16_t* __restrict__ Bt, const int K, const int brow, const int bcol, FL fl, FS fs) {
;     ...
;     BAR; WAIT_L(0); MMA(1, 0, At, B0); BAR; SCHED;
;     STAGE(SB(1, 1), Bt, bcol + HALF, t + 3);
;     WAIT_V(6); BAR; MMA(1, 1, At, B1); BAR;
;   }
;   { LDB(B0, 0, 0); LDA(At, 0, 0); STAGE(SA(1, 1), A, brow + HALF, nt - 1);
;     BAR; WAIT_L(0); MMA(0, 0, At, B0); BAR;
;     LDB(B1, 0, 1); BAR; WAIT_L(0); MMA(0, 1, At, B1); BAR;
	s_waitcnt lgkmcnt(0)
	s_setprio 1
	s_waitcnt lgkmcnt(0)
	v_mfma_f32_16x16x32_bf16 v[60:63], v[172:175], v[192:195], v[60:63]
	v_mfma_f32_16x16x32_bf16 v[56:59], v[184:187], v[192:195], v[56:59]
	v_mfma_f32_16x16x32_bf16 v[52:55], v[172:175], v[200:203], v[52:55]
	v_mfma_f32_16x16x32_bf16 v[48:51], v[184:187], v[200:203], v[48:51]
	v_mfma_f32_16x16x32_bf16 v[44:47], v[172:175], v[208:211], v[44:47]
	v_mfma_f32_16x16x32_bf16 v[40:43], v[184:187], v[208:211], v[40:43]
	v_mfma_f32_16x16x32_bf16 v[36:39], v[172:175], v[216:219], v[36:39]
	v_mfma_f32_16x16x32_bf16 v[32:35], v[184:187], v[216:219], v[32:35]
	v_mfma_f32_16x16x32_bf16 v[60:63], v[176:179], v[196:199], v[60:63]
	v_mfma_f32_16x16x32_bf16 v[56:59], v[188:191], v[196:199], v[56:59]
	v_mfma_f32_16x16x32_bf16 v[52:55], v[176:179], v[204:207], v[52:55]
	v_mfma_f32_16x16x32_bf16 v[48:51], v[188:191], v[204:207], v[48:51]
	v_mfma_f32_16x16x32_bf16 v[44:47], v[176:179], v[212:215], v[44:47]
	v_mfma_f32_16x16x32_bf16 v[40:43], v[188:191], v[212:215], v[40:43]
	v_mfma_f32_16x16x32_bf16 v[36:39], v[176:179], v[220:223], v[36:39]
	v_mfma_f32_16x16x32_bf16 v[32:35], v[188:191], v[220:223], v[32:35]
	s_setprio 0
	s_barrier
	v_readfirstlane_b32 s1, v165
	v_lshl_add_u64 v[172:173], v[242:243], 0, s[50:51]
	s_mov_b32 m0, s1
	v_readfirstlane_b32 s1, v167
	global_load_lds_dwordx4 v[172:173], off
	v_lshl_add_u64 v[172:173], v[244:245], 0, s[50:51]
	s_mov_b32 m0, s1
	s_nop 0
	global_load_lds_dwordx4 v[172:173], off
	s_waitcnt vmcnt(6)
	s_barrier
	s_setprio 1
	v_mfma_f32_16x16x32_bf16 v[28:31], v[224:227], v[192:195], v[28:31]
	v_mfma_f32_16x16x32_bf16 v[24:27], v[232:235], v[192:195], v[24:27]
	v_mfma_f32_16x16x32_bf16 v[20:23], v[224:227], v[200:203], v[20:23]
	v_mfma_f32_16x16x32_bf16 v[16:19], v[232:235], v[200:203], v[16:19]
	v_mfma_f32_16x16x32_bf16 v[12:15], v[224:227], v[208:211], v[12:15]
	v_mfma_f32_16x16x32_bf16 v[8:11], v[232:235], v[208:211], v[8:11]
	v_mfma_f32_16x16x32_bf16 v[4:7], v[224:227], v[216:219], v[4:7]
	v_mfma_f32_16x16x32_bf16 v[0:3], v[232:235], v[216:219], v[0:3]
	v_mfma_f32_16x16x32_bf16 v[28:31], v[228:231], v[196:199], v[28:31]
	v_mfma_f32_16x16x32_bf16 v[24:27], v[236:239], v[196:199], v[24:27]
	v_mfma_f32_16x16x32_bf16 v[20:23], v[228:231], v[204:207], v[20:23]
	v_mfma_f32_16x16x32_bf16 v[16:19], v[236:239], v[204:207], v[16:19]
	v_mfma_f32_16x16x32_bf16 v[12:15], v[228:231], v[212:215], v[12:15]
	v_mfma_f32_16x16x32_bf16 v[8:11], v[236:239], v[212:215], v[8:11]
	v_mfma_f32_16x16x32_bf16 v[4:7], v[228:231], v[220:223], v[4:7]
	v_mfma_f32_16x16x32_bf16 v[0:3], v[236:239], v[220:223], v[0:3]
	s_setprio 0
	s_add_i32 s0, s0, 2
	v_lshl_add_u64 v[134:135], v[134:135], 0, s[52:53]
	v_lshl_add_u64 v[136:137], v[136:137], 0, s[52:53]
	v_lshl_add_u64 v[138:139], v[138:139], 0, s[52:53]
	s_cmp_lt_u32 s0, 12
	v_lshl_add_u64 v[140:141], v[140:141], 0, s[52:53]
	s_barrier
	s_cbranch_scc1 .LBB0_869
	v_readfirstlane_b32 s0, v169
	v_lshl_add_u64 v[130:131], v[130:131], 0, s[54:55]
	s_mov_b32 m0, s0
	v_readfirstlane_b32 s0, v168
	ds_read_b128 v[134:137], v170
	ds_read_b128 v[138:141], v170 offset:1024
	ds_read_b128 v[158:161], v170 offset:2048
	ds_read_b128 v[162:165], v170 offset:3072
	ds_read_b128 v[170:173], v152
	ds_read_b128 v[174:177], v152 offset:1024
	ds_read_b128 v[178:181], v151
	ds_read_b128 v[184:187], v151 offset:1024
	ds_read_b128 v[188:191], v150
	ds_read_b128 v[192:195], v150 offset:1024
	ds_read_b128 v[196:199], v148
	ds_read_b128 v[200:203], v148 offset:1024
	global_load_lds_dwordx4 v[130:131], off
	v_lshl_add_u64 v[130:131], v[132:133], 0, s[54:55]
	s_mov_b32 m0, s0
	s_nop 0
	global_load_lds_dwordx4 v[130:131], off
	s_barrier
	s_waitcnt lgkmcnt(0)
	s_setprio 1
	s_waitcnt lgkmcnt(0)
	v_mfma_f32_16x16x32_bf16 v[124:127], v[134:137], v[170:173], v[124:127]
	v_mfma_f32_16x16x32_bf16 v[120:123], v[158:161], v[170:173], v[120:123]
	v_mfma_f32_16x16x32_bf16 v[116:119], v[134:137], v[178:181], v[116:119]
	v_mfma_f32_16x16x32_bf16 v[112:115], v[158:161], v[178:181], v[112:115]
	v_mfma_f32_16x16x32_bf16 v[100:103], v[134:137], v[196:199], v[100:103]
	v_mfma_f32_16x16x32_bf16 v[96:99], v[158:161], v[196:199], v[96:99]
	v_mfma_f32_16x16x32_bf16 v[124:127], v[138:141], v[174:177], v[124:127]
	v_mfma_f32_16x16x32_bf16 v[120:123], v[162:165], v[174:177], v[120:123]
	v_mfma_f32_16x16x32_bf16 v[116:119], v[138:141], v[184:187], v[116:119]
	v_mfma_f32_16x16x32_bf16 v[112:115], v[162:165], v[184:187], v[112:115]
	v_mfma_f32_16x16x32_bf16 v[108:111], v[134:137], v[188:191], v[108:111]
	v_mfma_f32_16x16x32_bf16 v[104:107], v[158:161], v[188:191], v[104:107]
	v_mfma_f32_16x16x32_bf16 v[100:103], v[138:141], v[200:203], v[100:103]
	v_mfma_f32_16x16x32_bf16 v[96:99], v[162:165], v[200:203], v[96:99]
	v_mfma_f32_16x16x32_bf16 v[130:133], v[138:141], v[192:195], v[108:111]
	v_mfma_f32_16x16x32_bf16 v[204:207], v[162:165], v[192:195], v[104:107]
	s_setprio 0
	s_barrier
	s_nop 0
	ds_read_b128 v[104:107], v166
	ds_read_b128 v[108:111], v166 offset:1024
	ds_read_b128 v[208:211], v166 offset:2048
	ds_read_b128 v[166:169], v166 offset:3072
	s_barrier
; #define LDA(dst, b, h) _Pragma("unroll") for (int m = 0; m < 4; ++m) _Pragma("unroll") for (int k = 0; k < 2; ++k) \
;     dst[m][k] = *reinterpret_cast<const bf16x8*>((const char*)SA(b, h) + lds_byte8(wr * 64 + m * 16 + fr, k * 32 + fq * 8))
; #define LDB(dst, b, h) _Pragma("unroll") for (int n = 0; n < 2; ++n) _Pragma("unroll") for (int k = 0; k < 2; ++k) \
;     dst[n][k] = *reinterpret_cast<const bf16x8*>((const char*)SB(b, h) + lds_byte8(wc * 32 + n * 16 + fr, k * 32 + fq * 8))
; #define MMA(ai, bj, At_, Bt_) do { __builtin_amdgcn_s_setprio(1); \
;     _Pragma("unroll") for (int m = 0; m < 4; ++m) _Pragma("unroll") for (int n = 0; n < 2; ++n) _Pragma("unroll") for (int k = 0; k < 2; ++k) \
;       acc[ai][bj][m][n] = MFMA16(Bt_[n][k], At_[m][k], acc[ai][bj][m][n]); \
;     __builtin_amdgcn_s_setprio(0); } while (0)
; #define WAIT_V(n) asm volatile("s_waitcnt vmcnt(" #n ")" ::: "memory")
; #define WAIT_L(n) asm volatile("s_waitcnt lgkmcnt(" #n ")" ::: "memory")
; #define BAR __builtin_amdgcn_s_barrier()
; template <class FL, class FS>
; DI void gemm8_tile(char* shmc, const bf16_t* __restrict__ A, const bf16_t* __restrict__ Bt, const int K, const int brow, const int bcol, FL fl, FS fs) {
;     ...
;     BAR; WAIT_L(0); MMA(0, 0, At, B0); BAR;
;     LDB(B1, 0, 1); BAR; WAIT_L(0); MMA(0, 1, At, B1); BAR;
;     LDA(At, 0, 1); WAIT_V(4); BAR; WAIT_L(0); MMA(1, 0, At, B0); MMA(1, 1, At, B1); BAR; }
;   { LDB(B0, 1, 0); LDA(At, 1, 0); WAIT_V(2); BAR; WAIT_L(0); MMA(0, 0, At, B0); BAR;
	s_waitcnt lgkmcnt(0)
	s_setprio 1
	s_waitcnt lgkmcnt(3)
	v_mfma_f32_16x16x32_bf16 v[84:87], v[104:107], v[178:181], v[84:87]
	s_waitcnt lgkmcnt(1)
	v_mfma_f32_16x16x32_bf16 v[80:83], v[208:211], v[178:181], v[80:83]
	v_mfma_f32_16x16x32_bf16 v[68:71], v[104:107], v[196:199], v[68:71]
	v_mfma_f32_16x16x32_bf16 v[64:67], v[208:211], v[196:199], v[64:67]
	v_mfma_f32_16x16x32_bf16 v[92:95], v[104:107], v[170:173], v[92:95]
	v_mfma_f32_16x16x32_bf16 v[88:91], v[208:211], v[170:173], v[88:91]
	v_mfma_f32_16x16x32_bf16 v[84:87], v[108:111], v[184:187], v[84:87]
	s_waitcnt lgkmcnt(0)
	v_mfma_f32_16x16x32_bf16 v[80:83], v[166:169], v[184:187], v[80:83]
	v_mfma_f32_16x16x32_bf16 v[76:79], v[104:107], v[188:191], v[76:79]
	v_mfma_f32_16x16x32_bf16 v[72:75], v[208:211], v[188:191], v[72:75]
	v_mfma_f32_16x16x32_bf16 v[68:71], v[108:111], v[200:203], v[68:71]
	v_mfma_f32_16x16x32_bf16 v[64:67], v[166:169], v[200:203], v[64:67]
	v_mfma_f32_16x16x32_bf16 v[212:215], v[108:111], v[174:177], v[92:95]
	v_mfma_f32_16x16x32_bf16 v[170:173], v[166:169], v[174:177], v[88:91]
	v_mfma_f32_16x16x32_bf16 v[174:177], v[108:111], v[192:195], v[76:79]
	v_mfma_f32_16x16x32_bf16 v[178:181], v[166:169], v[192:195], v[72:75]
	s_setprio 0
	s_barrier
	s_nop 0
	ds_read_b128 v[72:75], v152 offset:16384
	ds_read_b128 v[76:79], v152 offset:17408
	ds_read_b128 v[88:91], v151 offset:16384
	ds_read_b128 v[92:95], v151 offset:17408
	ds_read_b128 v[184:187], v150 offset:16384
	ds_read_b128 v[188:191], v150 offset:17408
	ds_read_b128 v[192:195], v148 offset:16384
	ds_read_b128 v[196:199], v148 offset:17408
	s_waitcnt vmcnt(4)
	s_barrier
	s_waitcnt lgkmcnt(0)
	s_setprio 1
	s_waitcnt lgkmcnt(7)
	v_mfma_f32_16x16x32_bf16 v[60:63], v[134:137], v[72:75], v[60:63]
	v_mfma_f32_16x16x32_bf16 v[56:59], v[158:161], v[72:75], v[56:59]
	s_waitcnt lgkmcnt(5)
	v_mfma_f32_16x16x32_bf16 v[52:55], v[134:137], v[88:91], v[52:55]
	v_mfma_f32_16x16x32_bf16 v[48:51], v[158:161], v[88:91], v[48:51]
	s_waitcnt lgkmcnt(1)
	v_mfma_f32_16x16x32_bf16 v[36:39], v[134:137], v[192:195], v[36:39]
	v_mfma_f32_16x16x32_bf16 v[32:35], v[158:161], v[192:195], v[32:35]
	v_mfma_f32_16x16x32_bf16 v[60:63], v[138:141], v[76:79], v[60:63]
	v_mfma_f32_16x16x32_bf16 v[56:59], v[162:165], v[76:79], v[56:59]
	v_mfma_f32_16x16x32_bf16 v[52:55], v[138:141], v[92:95], v[52:55]
	v_mfma_f32_16x16x32_bf16 v[48:51], v[162:165], v[92:95], v[48:51]
	v_mfma_f32_16x16x32_bf16 v[44:47], v[134:137], v[184:187], v[44:47]
	v_mfma_f32_16x16x32_bf16 v[40:43], v[158:161], v[184:187], v[40:43]
	s_waitcnt lgkmcnt(0)
	v_mfma_f32_16x16x32_bf16 v[36:39], v[138:141], v[196:199], v[36:39]
	v_mfma_f32_16x16x32_bf16 v[32:35], v[162:165], v[196:199], v[32:35]
	v_mfma_f32_16x16x32_bf16 v[200:203], v[138:141], v[188:191], v[44:47]
	v_mfma_f32_16x16x32_bf16 v[216:219], v[162:165], v[188:191], v[40:43]
	s_setprio 0
	s_setprio 1
	v_mfma_f32_16x16x32_bf16 v[20:23], v[104:107], v[88:91], v[20:23]
	v_mfma_f32_16x16x32_bf16 v[16:19], v[208:211], v[88:91], v[16:19]
	v_mfma_f32_16x16x32_bf16 v[4:7], v[104:107], v[192:195], v[4:7]
	v_mfma_f32_16x16x32_bf16 v[0:3], v[208:211], v[192:195], v[0:3]
	v_mfma_f32_16x16x32_bf16 v[28:31], v[104:107], v[72:75], v[28:31]
	v_mfma_f32_16x16x32_bf16 v[24:27], v[208:211], v[72:75], v[24:27]
	v_mfma_f32_16x16x32_bf16 v[20:23], v[108:111], v[92:95], v[20:23]
	v_mfma_f32_16x16x32_bf16 v[16:19], v[166:169], v[92:95], v[16:19]
	v_mfma_f32_16x16x32_bf16 v[12:15], v[104:107], v[184:187], v[12:15]
	v_mfma_f32_16x16x32_bf16 v[8:11], v[208:211], v[184:187], v[8:11]
	v_mfma_f32_16x16x32_bf16 v[4:7], v[108:111], v[196:199], v[4:7]
	v_mfma_f32_16x16x32_bf16 v[0:3], v[166:169], v[196:199], v[0:3]
	v_mfma_f32_16x16x32_bf16 v[134:137], v[108:111], v[76:79], v[28:31]
	v_mfma_f32_16x16x32_bf16 v[138:141], v[166:169], v[76:79], v[24:27]
	v_mfma_f32_16x16x32_bf16 v[158:161], v[108:111], v[188:191], v[12:15]
	v_mfma_f32_16x16x32_bf16 v[162:165], v[166:169], v[188:191], v[8:11]
	s_setprio 0
	s_barrier
	s_nop 0
	ds_read_b128 v[8:11], v156
	ds_read_b128 v[12:15], v156 offset:1024
	ds_read_b128 v[166:169], v156 offset:2048
	ds_read_b128 v[184:187], v156 offset:3072
	ds_read_b128 v[24:27], v152 offset:32768
	ds_read_b128 v[28:31], v152 offset:33792
	ds_read_b128 v[40:43], v151 offset:32768
	ds_read_b128 v[44:47], v151 offset:33792
	ds_read_b128 v[188:191], v150 offset:32768
	ds_read_b128 v[192:195], v150 offset:33792
	ds_read_b128 v[196:199], v148 offset:32768
	ds_read_b128 v[208:211], v148 offset:33792
	s_waitcnt vmcnt(2)
	s_barrier
; #define LDA(dst, b, h) _Pragma("unroll") for (int m = 0; m < 4; ++m) _Pragma("unroll") for (int k = 0; k < 2; ++k) \
;     dst[m][k] = *reinterpret_cast<const bf16x8*>((const char*)SA(b, h) + lds_byte8(wr * 64 + m * 16 + fr, k * 32 + fq * 8))
; #define LDB(dst, b, h) _Pragma("unroll") for (int n = 0; n < 2; ++n) _Pragma("unroll") for (int k = 0; k < 2; ++k) \
;     dst[n][k] = *reinterpret_cast<const bf16x8*>((const char*)SB(b, h) + lds_byte8(wc * 32 + n * 16 + fr, k * 32 + fq * 8))
; #define MMA(ai, bj, At_, Bt_) do { __builtin_amdgcn_s_setprio(1); \
;     _Pragma("unroll") for (int m = 0; m < 4; ++m) _Pragma("unroll") for (int n = 0; n < 2; ++n) _Pragma("unroll") for (int k = 0; k < 2; ++k) \
;       acc[ai][bj][m][n] = MFMA16(Bt_[n][k], At_[m][k], acc[ai][bj][m][n]); \
;     __builtin_amdgcn_s_setprio(0); } while (0)
; #define WAIT_V(n) asm volatile("s_waitcnt vmcnt(" #n ")" ::: "memory")
; #define WAIT_L(n) asm volatile("s_waitcnt lgkmcnt(" #n ")" ::: "memory")
; #define BAR __builtin_amdgcn_s_barrier()
; template <class FL, class FS>
; DI void gemm8_tile(char* shmc, const bf16_t* __restrict__ A, const bf16_t* __restrict__ Bt, const int K, const int brow, const int bcol, FL fl, FS fs) {
;     ...
;   { LDB(B0, 1, 0); LDA(At, 1, 0); WAIT_V(2); BAR; WAIT_L(0); MMA(0, 0, At, B0); BAR;
;     LDB(B1, 1, 1); WAIT_V(0); BAR; WAIT_L(0); MMA(0, 1, At, B1); BAR;
;     LDA(At, 1, 1); BAR; WAIT_L(0); MMA(1, 0, At, B0); MMA(1, 1, At, B1); BAR; }
;   if (wr == 0) BAR;
	s_waitcnt lgkmcnt(0)
	s_setprio 1
	s_waitcnt lgkmcnt(7)
	v_mfma_f32_16x16x32_bf16 v[72:75], v[8:11], v[24:27], v[124:127]
	s_waitcnt lgkmcnt(6)
	v_mfma_f32_16x16x32_bf16 v[124:127], v[12:15], v[28:31], v[72:75]
	v_mfma_f32_16x16x32_bf16 v[72:75], v[166:169], v[24:27], v[120:123]
	v_mfma_f32_16x16x32_bf16 v[120:123], v[184:187], v[28:31], v[72:75]
	s_waitcnt lgkmcnt(5)
	v_mfma_f32_16x16x32_bf16 v[72:75], v[8:11], v[40:43], v[116:119]
	s_waitcnt lgkmcnt(4)
	v_mfma_f32_16x16x32_bf16 v[108:111], v[12:15], v[44:47], v[72:75]
	v_mfma_f32_16x16x32_bf16 v[72:75], v[166:169], v[40:43], v[112:115]
	v_mfma_f32_16x16x32_bf16 v[104:107], v[184:187], v[44:47], v[72:75]
	s_waitcnt lgkmcnt(3)
	v_mfma_f32_16x16x32_bf16 v[72:75], v[8:11], v[188:191], v[130:133]
	s_waitcnt lgkmcnt(2)
	v_mfma_f32_16x16x32_bf16 v[92:95], v[12:15], v[192:195], v[72:75]
	v_mfma_f32_16x16x32_bf16 v[72:75], v[166:169], v[188:191], v[204:207]
	v_mfma_f32_16x16x32_bf16 v[88:91], v[184:187], v[192:195], v[72:75]
	s_waitcnt lgkmcnt(1)
	v_mfma_f32_16x16x32_bf16 v[72:75], v[8:11], v[196:199], v[100:103]
	s_waitcnt lgkmcnt(0)
	v_mfma_f32_16x16x32_bf16 v[76:79], v[12:15], v[208:211], v[72:75]
	v_mfma_f32_16x16x32_bf16 v[72:75], v[166:169], v[196:199], v[96:99]
	v_mfma_f32_16x16x32_bf16 v[72:75], v[184:187], v[208:211], v[72:75]
	s_setprio 0
	s_barrier
	ds_read_b128 v[130:133], v154
	ds_read_b128 v[204:207], v154 offset:1024
	ds_read_b128 v[220:223], v154 offset:2048
	ds_read_b128 v[154:157], v154 offset:3072
	s_waitcnt vmcnt(0)
	s_barrier
	s_waitcnt lgkmcnt(0)
	s_setprio 1
	s_waitcnt lgkmcnt(3)
	v_mfma_f32_16x16x32_bf16 v[96:99], v[130:133], v[24:27], v[212:215]
	s_waitcnt lgkmcnt(1)
	v_mfma_f32_16x16x32_bf16 v[24:27], v[220:223], v[24:27], v[170:173]
	s_waitcnt lgkmcnt(0)
	v_mfma_f32_16x16x32_bf16 v[112:115], v[154:157], v[28:31], v[24:27]
	v_mfma_f32_16x16x32_bf16 v[24:27], v[130:133], v[40:43], v[84:87]
	v_mfma_f32_16x16x32_bf16 v[100:103], v[204:207], v[44:47], v[24:27]
	v_mfma_f32_16x16x32_bf16 v[24:27], v[220:223], v[40:43], v[80:83]
	v_mfma_f32_16x16x32_bf16 v[116:119], v[204:207], v[28:31], v[96:99]
	v_mfma_f32_16x16x32_bf16 v[96:99], v[154:157], v[44:47], v[24:27]
	v_mfma_f32_16x16x32_bf16 v[24:27], v[130:133], v[188:191], v[174:177]
	v_mfma_f32_16x16x32_bf16 v[84:87], v[204:207], v[192:195], v[24:27]
	v_mfma_f32_16x16x32_bf16 v[24:27], v[220:223], v[188:191], v[178:181]
	v_mfma_f32_16x16x32_bf16 v[80:83], v[154:157], v[192:195], v[24:27]
	v_mfma_f32_16x16x32_bf16 v[24:27], v[130:133], v[196:199], v[68:71]
	v_mfma_f32_16x16x32_bf16 v[68:71], v[204:207], v[208:211], v[24:27]
	v_mfma_f32_16x16x32_bf16 v[24:27], v[220:223], v[196:199], v[64:67]
	v_mfma_f32_16x16x32_bf16 v[64:67], v[154:157], v[208:211], v[24:27]
	s_setprio 0
	s_barrier
	ds_read_b128 v[170:173], v152 offset:49152
	ds_read_b128 v[174:177], v152 offset:50176
	ds_read_b128 v[178:181], v151 offset:49152
	ds_read_b128 v[188:191], v151 offset:50176
	ds_read_b128 v[192:195], v150 offset:49152
	ds_read_b128 v[150:153], v150 offset:50176
	ds_read_b128 v[196:199], v148 offset:49152
	ds_read_b128 v[208:211], v148 offset:50176
	s_barrier
	s_waitcnt lgkmcnt(0)
	s_setprio 1
	s_waitcnt lgkmcnt(7)
	v_mfma_f32_16x16x32_bf16 v[24:27], v[8:11], v[170:173], v[60:63]
	s_waitcnt lgkmcnt(6)
	v_mfma_f32_16x16x32_bf16 v[60:63], v[12:15], v[174:177], v[24:27]
	v_mfma_f32_16x16x32_bf16 v[24:27], v[166:169], v[170:173], v[56:59]
	v_mfma_f32_16x16x32_bf16 v[56:59], v[184:187], v[174:177], v[24:27]
	s_waitcnt lgkmcnt(5)
	v_mfma_f32_16x16x32_bf16 v[24:27], v[8:11], v[178:181], v[52:55]
	s_waitcnt lgkmcnt(4)
	v_mfma_f32_16x16x32_bf16 v[44:47], v[12:15], v[188:191], v[24:27]
	v_mfma_f32_16x16x32_bf16 v[24:27], v[166:169], v[178:181], v[48:51]
	v_mfma_f32_16x16x32_bf16 v[40:43], v[184:187], v[188:191], v[24:27]
	s_waitcnt lgkmcnt(3)
	v_mfma_f32_16x16x32_bf16 v[24:27], v[8:11], v[192:195], v[200:203]
	s_waitcnt lgkmcnt(1)
	v_mfma_f32_16x16x32_bf16 v[8:11], v[8:11], v[196:199], v[36:39]
	v_mfma_f32_16x16x32_bf16 v[28:31], v[12:15], v[150:153], v[24:27]
	v_mfma_f32_16x16x32_bf16 v[24:27], v[166:169], v[192:195], v[216:219]
	s_waitcnt lgkmcnt(0)
	v_mfma_f32_16x16x32_bf16 v[12:15], v[12:15], v[208:211], v[8:11]
	v_mfma_f32_16x16x32_bf16 v[8:11], v[166:169], v[196:199], v[32:35]
	v_mfma_f32_16x16x32_bf16 v[24:27], v[184:187], v[150:153], v[24:27]
	v_mfma_f32_16x16x32_bf16 v[8:11], v[184:187], v[208:211], v[8:11]
	s_setprio 0
	s_setprio 1
	v_mfma_f32_16x16x32_bf16 v[32:35], v[130:133], v[170:173], v[134:137]
	v_mfma_f32_16x16x32_bf16 v[52:55], v[204:207], v[174:177], v[32:35]
	v_mfma_f32_16x16x32_bf16 v[32:35], v[220:223], v[170:173], v[138:141]
	v_mfma_f32_16x16x32_bf16 v[16:19], v[220:223], v[178:181], v[16:19]
	v_mfma_f32_16x16x32_bf16 v[48:51], v[154:157], v[174:177], v[32:35]
	v_mfma_f32_16x16x32_bf16 v[20:23], v[130:133], v[178:181], v[20:23]
	v_mfma_f32_16x16x32_bf16 v[32:35], v[154:157], v[188:191], v[16:19]
	v_mfma_f32_16x16x32_bf16 v[16:19], v[130:133], v[192:195], v[158:161]
	v_mfma_f32_16x16x32_bf16 v[36:39], v[204:207], v[188:191], v[20:23]
	v_mfma_f32_16x16x32_bf16 v[20:23], v[204:207], v[150:153], v[16:19]
	v_mfma_f32_16x16x32_bf16 v[16:19], v[220:223], v[192:195], v[162:165]
	v_mfma_f32_16x16x32_bf16 v[4:7], v[130:133], v[196:199], v[4:7]
	v_mfma_f32_16x16x32_bf16 v[0:3], v[220:223], v[196:199], v[0:3]
	v_mfma_f32_16x16x32_bf16 v[16:19], v[154:157], v[150:153], v[16:19]
	v_mfma_f32_16x16x32_bf16 v[4:7], v[204:207], v[208:211], v[4:7]
	v_mfma_f32_16x16x32_bf16 v[0:3], v[154:157], v[208:211], v[0:3]
	s_setprio 0
	v_cmp_gt_u32_e32 vcc, s67, v128
	s_barrier
	s_and_saveexec_b64 s[0:1], vcc
	s_cbranch_execz .LBB0_872
	s_barrier

; #define STAGE(P, BASE, br, kt) do { const long _g = (long)(br) * K + (long)(kt) * 64; \
;     _Pragma("unroll") for (int _i = 0; _i < 2; ++_i) { const int _b = tidx * 16 + _i * 8192; int _r, _c; stage_rc8(_b, _r, _c); \
;       __builtin_amdgcn_global_load_lds((const unsigned*)(BASE + _g + (long)_r * K + _c), (LAS unsigned*)((LAS char*)(P) + _b), 16, 0, 0); } } while (0)
; #define LDA(dst, b, h) _Pragma("unroll") for (int m = 0; m < 4; ++m) _Pragma("unroll") for (int k = 0; k < 2; ++k) \
;     dst[m][k] = *reinterpret_cast<const bf16x8*>((const char*)SA(b, h) + lds_byte8(wr * 64 + m * 16 + fr, k * 32 + fq * 8))
; #define LDB(dst, b, h) _Pragma("unroll") for (int n = 0; n < 2; ++n) _Pragma("unroll") for (int k = 0; k < 2; ++k) \
;     dst[n][k] = *reinterpret_cast<const bf16x8*>((const char*)SB(b, h) + lds_byte8(wc * 32 + n * 16 + fr, k * 32 + fq * 8))
; #define MMA(ai, bj, At_, Bt_) do { __builtin_amdgcn_s_setprio(1); \
;     _Pragma("unroll") for (int m = 0; m < 4; ++m) _Pragma("unroll") for (int n = 0; n < 2; ++n) _Pragma("unroll") for (int k = 0; k < 2; ++k) \
;       acc[ai][bj][m][n] = MFMA16(Bt_[n][k], At_[m][k], acc[ai][bj][m][n]); \
;     __builtin_amdgcn_s_setprio(0); } while (0)
; #define WAIT_V(n) asm volatile("s_waitcnt vmcnt(" #n ")" ::: "memory")
; #define WAIT_L(n) asm volatile("s_waitcnt lgkmcnt(" #n ")" ::: "memory")
; #define BAR __builtin_amdgcn_s_barrier()
; #define SCHED __builtin_amdgcn_sched_barrier(0)
; template <class FL, class FS>
; DI void gemm8_tile(char* shmc, const bf16_t* __restrict__ A, const bf16_t* __restrict__ Bt, const int K, const int brow, const int bcol, FL fl, FS fs) {
;     ...
;     LDB(B0, 0, 0); SCHED; LDA(At, 0, 0); STAGE(SA(1, 1), A, brow + HALF, t + 1);
;     WAIT_L(8); BAR; WAIT_L(0); MMA(0, 0, At, B0); BAR; SCHED;
;     LDB(B1, 0, 1); STAGE(SB(0, 0), Bt, bcol, t + 2);
;     BAR; WAIT_L(0); MMA(0, 1, At, B1); BAR;
;     LDA(At, 0, 1); STAGE(SA(0, 0), A, brow, t + 2);
;     BAR; WAIT_L(0); MMA(1, 0, At, B0); BAR; SCHED;
;     STAGE(SB(0, 1), Bt, bcol + HALF, t + 2);
;     WAIT_V(6); BAR; MMA(1, 1, At, B1); BAR;
.Lg5_p1skip:
	s_nop 0
	s_barrier
	s_waitcnt lgkmcnt(0)
	s_setprio 1
	s_waitcnt lgkmcnt(0)
	v_mfma_f32_16x16x32_bf16 v[124:127], v[174:177], v[192:195], v[124:127]
	v_mfma_f32_16x16x32_bf16 v[120:123], v[184:187], v[192:195], v[120:123]
	v_mfma_f32_16x16x32_bf16 v[116:119], v[174:177], v[200:203], v[116:119]
	v_mfma_f32_16x16x32_bf16 v[112:115], v[184:187], v[200:203], v[112:115]
	v_mfma_f32_16x16x32_bf16 v[108:111], v[174:177], v[208:211], v[108:111]
	v_mfma_f32_16x16x32_bf16 v[104:107], v[184:187], v[208:211], v[104:107]
	v_mfma_f32_16x16x32_bf16 v[100:103], v[174:177], v[216:219], v[100:103]
	v_mfma_f32_16x16x32_bf16 v[96:99], v[184:187], v[216:219], v[96:99]
	v_mfma_f32_16x16x32_bf16 v[124:127], v[178:181], v[196:199], v[124:127]
	v_mfma_f32_16x16x32_bf16 v[120:123], v[188:191], v[196:199], v[120:123]
	v_mfma_f32_16x16x32_bf16 v[116:119], v[178:181], v[204:207], v[116:119]
	v_mfma_f32_16x16x32_bf16 v[112:115], v[188:191], v[204:207], v[112:115]
	v_mfma_f32_16x16x32_bf16 v[108:111], v[178:181], v[212:215], v[108:111]
	v_mfma_f32_16x16x32_bf16 v[104:107], v[188:191], v[212:215], v[104:107]
	v_mfma_f32_16x16x32_bf16 v[100:103], v[178:181], v[220:223], v[100:103]
	v_mfma_f32_16x16x32_bf16 v[96:99], v[188:191], v[220:223], v[96:99]
	s_setprio 0
	s_barrier
	v_lshl_add_u64 v[244:245], s[6:7], 0, v[132:133]
	v_readfirstlane_b32 s1, v152
	v_lshl_add_u64 v[246:247], v[244:245], 0, s[16:17]
	s_mov_b32 m0, s1
	ds_read_b128 v[224:227], v169
	ds_read_b128 v[228:231], v169 offset:1024
	ds_read_b128 v[232:235], v169 offset:2048
	ds_read_b128 v[236:239], v169 offset:3072
	global_load_lds_dwordx4 v[246:247], off
	v_lshl_add_u64 v[246:247], s[6:7], 0, v[134:135]
	v_readfirstlane_b32 s1, v158
	v_lshl_add_u64 v[248:249], v[246:247], 0, s[16:17]
	s_mov_b32 m0, s1
	s_nop 0
	global_load_lds_dwordx4 v[248:249], off
	s_barrier
	s_waitcnt lgkmcnt(0)
	s_setprio 1
	s_waitcnt lgkmcnt(0)
	v_mfma_f32_16x16x32_bf16 v[92:95], v[224:227], v[192:195], v[92:95]
	v_mfma_f32_16x16x32_bf16 v[88:91], v[232:235], v[192:195], v[88:91]
	v_mfma_f32_16x16x32_bf16 v[84:87], v[224:227], v[200:203], v[84:87]
	v_mfma_f32_16x16x32_bf16 v[80:83], v[232:235], v[200:203], v[80:83]
	v_mfma_f32_16x16x32_bf16 v[76:79], v[224:227], v[208:211], v[76:79]
	v_mfma_f32_16x16x32_bf16 v[72:75], v[232:235], v[208:211], v[72:75]
	v_mfma_f32_16x16x32_bf16 v[68:71], v[224:227], v[216:219], v[68:71]
	v_mfma_f32_16x16x32_bf16 v[64:67], v[232:235], v[216:219], v[64:67]
	v_mfma_f32_16x16x32_bf16 v[92:95], v[228:231], v[196:199], v[92:95]
	v_mfma_f32_16x16x32_bf16 v[88:91], v[236:239], v[196:199], v[88:91]
	v_mfma_f32_16x16x32_bf16 v[84:87], v[228:231], v[204:207], v[84:87]
	v_mfma_f32_16x16x32_bf16 v[80:83], v[236:239], v[204:207], v[80:83]
	v_mfma_f32_16x16x32_bf16 v[76:79], v[228:231], v[212:215], v[76:79]
	v_mfma_f32_16x16x32_bf16 v[72:75], v[236:239], v[212:215], v[72:75]
	v_mfma_f32_16x16x32_bf16 v[68:71], v[228:231], v[220:223], v[68:71]
	v_mfma_f32_16x16x32_bf16 v[64:67], v[236:239], v[220:223], v[64:67]
	s_setprio 0
	v_readfirstlane_b32 s1, v150
	v_lshl_add_u64 v[248:249], v[240:241], 0, s[18:19]
	s_mov_b32 m0, s1
	v_readfirstlane_b32 s1, v156
	s_barrier
	ds_read_b128 v[192:195], v155 offset:16384
	ds_read_b128 v[196:199], v155 offset:17408
	ds_read_b128 v[200:203], v154 offset:16384
	ds_read_b128 v[204:207], v154 offset:17408
	ds_read_b128 v[208:211], v153 offset:16384
	ds_read_b128 v[212:215], v153 offset:17408
	ds_read_b128 v[216:219], v151 offset:16384
	ds_read_b128 v[220:223], v151 offset:17408
	global_load_lds_dwordx4 v[248:249], off
	v_lshl_add_u64 v[248:249], v[242:243], 0, s[18:19]
	s_mov_b32 m0, s1
	s_nop 0
	global_load_lds_dwordx4 v[248:249], off
	s_barrier
	s_waitcnt lgkmcnt(0)
	s_setprio 1
	s_waitcnt lgkmcnt(0)
	v_mfma_f32_16x16x32_bf16 v[60:63], v[174:177], v[192:195], v[60:63]
	v_mfma_f32_16x16x32_bf16 v[56:59], v[184:187], v[192:195], v[56:59]
	v_mfma_f32_16x16x32_bf16 v[52:55], v[174:177], v[200:203], v[52:55]
	v_mfma_f32_16x16x32_bf16 v[48:51], v[184:187], v[200:203], v[48:51]
	v_mfma_f32_16x16x32_bf16 v[44:47], v[174:177], v[208:211], v[44:47]
	v_mfma_f32_16x16x32_bf16 v[40:43], v[184:187], v[208:211], v[40:43]
	v_mfma_f32_16x16x32_bf16 v[36:39], v[174:177], v[216:219], v[36:39]
	v_mfma_f32_16x16x32_bf16 v[32:35], v[184:187], v[216:219], v[32:35]
	v_mfma_f32_16x16x32_bf16 v[60:63], v[178:181], v[196:199], v[60:63]
	v_mfma_f32_16x16x32_bf16 v[56:59], v[188:191], v[196:199], v[56:59]
	v_mfma_f32_16x16x32_bf16 v[52:55], v[178:181], v[204:207], v[52:55]
	v_mfma_f32_16x16x32_bf16 v[48:51], v[188:191], v[204:207], v[48:51]
	v_mfma_f32_16x16x32_bf16 v[44:47], v[178:181], v[212:215], v[44:47]
	v_mfma_f32_16x16x32_bf16 v[40:43], v[188:191], v[212:215], v[40:43]
	v_mfma_f32_16x16x32_bf16 v[36:39], v[178:181], v[220:223], v[36:39]
	v_mfma_f32_16x16x32_bf16 v[32:35], v[188:191], v[220:223], v[32:35]
	s_setprio 0
	s_barrier
	v_readfirstlane_b32 s1, v160
	v_lshl_add_u64 v[174:175], v[244:245], 0, s[20:21]
	s_mov_b32 m0, s1
	v_readfirstlane_b32 s1, v161
	global_load_lds_dwordx4 v[174:175], off
	v_lshl_add_u64 v[174:175], v[246:247], 0, s[20:21]
	s_mov_b32 m0, s1
	s_nop 0
	global_load_lds_dwordx4 v[174:175], off
	s_cmp_eq_u32 s0, -2
	s_cselect_b32 s101, s98, 0
	s_cmp_lg_u32 s101, 0
	s_cbranch_scc1 .Lg5_w22
	s_waitcnt vmcnt(6)
; #define STAGE(P, BASE, br, kt) do { const long _g = (long)(br) * K + (long)(kt) * 64; \
;     _Pragma("unroll") for (int _i = 0; _i < 2; ++_i) { const int _b = tidx * 16 + _i * 8192; int _r, _c; stage_rc8(_b, _r, _c); \
;       __builtin_amdgcn_global_load_lds((const unsigned*)(BASE + _g + (long)_r * K + _c), (LAS unsigned*)((LAS char*)(P) + _b), 16, 0, 0); } } while (0)
; #define LDA(dst, b, h) _Pragma("unroll") for (int m = 0; m < 4; ++m) _Pragma("unroll") for (int k = 0; k < 2; ++k) \
;     dst[m][k] = *reinterpret_cast<const bf16x8*>((const char*)SA(b, h) + lds_byte8(wr * 64 + m * 16 + fr, k * 32 + fq * 8))
; #define LDB(dst, b, h) _Pragma("unroll") for (int n = 0; n < 2; ++n) _Pragma("unroll") for (int k = 0; k < 2; ++k) \
;     dst[n][k] = *reinterpret_cast<const bf16x8*>((const char*)SB(b, h) + lds_byte8(wc * 32 + n * 16 + fr, k * 32 + fq * 8))
; #define MMA(ai, bj, At_, Bt_) do { __builtin_amdgcn_s_setprio(1); \
;     _Pragma("unroll") for (int m = 0; m < 4; ++m) _Pragma("unroll") for (int n = 0; n < 2; ++n) _Pragma("unroll") for (int k = 0; k < 2; ++k) \
;       acc[ai][bj][m][n] = MFMA16(Bt_[n][k], At_[m][k], acc[ai][bj][m][n]); \
;     __builtin_amdgcn_s_setprio(0); } while (0)
; #define WAIT_V(n) asm volatile("s_waitcnt vmcnt(" #n ")" ::: "memory")
; #define WAIT_L(n) asm volatile("s_waitcnt lgkmcnt(" #n ")" ::: "memory")
; #define BAR __builtin_amdgcn_s_barrier()
; #define SCHED __builtin_amdgcn_sched_barrier(0)
; template <class FL, class FS>
; DI void gemm8_tile(char* shmc, const bf16_t* __restrict__ A, const bf16_t* __restrict__ Bt, const int K, const int brow, const int bcol, FL fl, FS fs) {
;     ...
;     WAIT_V(6); BAR; MMA(1, 1, At, B1); BAR;
;     LDB(B0, 1, 0); SCHED; LDA(At, 1, 0); STAGE(SA(0, 1), A, brow + HALF, t + 2);
;     WAIT_L(8); BAR; WAIT_L(0); MMA(0, 0, At, B0); BAR; SCHED;
;     LDB(B1, 1, 1); STAGE(SB(1, 0), Bt, bcol, t + 3);
;     BAR; WAIT_L(0); MMA(0, 1, At, B1); BAR;
;     LDA(At, 1, 1); STAGE(SA(1, 0), A, brow, t + 3);
;     BAR; WAIT_L(0); MMA(1, 0, At, B0); BAR; SCHED;
.Lg5_wd:
	s_barrier
	s_setprio 1
	v_mfma_f32_16x16x32_bf16 v[28:31], v[224:227], v[192:195], v[28:31]
	v_mfma_f32_16x16x32_bf16 v[24:27], v[232:235], v[192:195], v[24:27]
	v_mfma_f32_16x16x32_bf16 v[20:23], v[224:227], v[200:203], v[20:23]
	v_mfma_f32_16x16x32_bf16 v[16:19], v[232:235], v[200:203], v[16:19]
	v_mfma_f32_16x16x32_bf16 v[12:15], v[224:227], v[208:211], v[12:15]
	v_mfma_f32_16x16x32_bf16 v[8:11], v[232:235], v[208:211], v[8:11]
	v_mfma_f32_16x16x32_bf16 v[4:7], v[224:227], v[216:219], v[4:7]
	v_mfma_f32_16x16x32_bf16 v[0:3], v[232:235], v[216:219], v[0:3]
	v_mfma_f32_16x16x32_bf16 v[28:31], v[228:231], v[196:199], v[28:31]
	v_mfma_f32_16x16x32_bf16 v[24:27], v[236:239], v[196:199], v[24:27]
	v_mfma_f32_16x16x32_bf16 v[20:23], v[228:231], v[204:207], v[20:23]
	v_mfma_f32_16x16x32_bf16 v[16:19], v[236:239], v[204:207], v[16:19]
	v_mfma_f32_16x16x32_bf16 v[12:15], v[228:231], v[212:215], v[12:15]
	v_mfma_f32_16x16x32_bf16 v[8:11], v[236:239], v[212:215], v[8:11]
	v_mfma_f32_16x16x32_bf16 v[4:7], v[228:231], v[220:223], v[4:7]
	v_mfma_f32_16x16x32_bf16 v[0:3], v[236:239], v[220:223], v[0:3]
	s_setprio 0
	s_barrier
	ds_read_b128 v[174:177], v159
	ds_read_b128 v[178:181], v159 offset:1024
	ds_read_b128 v[184:187], v159 offset:2048
	ds_read_b128 v[188:191], v159 offset:3072
	v_readfirstlane_b32 s1, v162
	v_lshl_add_u64 v[224:225], v[240:241], 0, s[22:23]
	s_mov_b32 m0, s1
	v_readfirstlane_b32 s1, v163
	ds_read_b128 v[192:195], v155 offset:32768
	ds_read_b128 v[196:199], v155 offset:33792
	ds_read_b128 v[200:203], v154 offset:32768
	ds_read_b128 v[204:207], v154 offset:33792
	ds_read_b128 v[208:211], v153 offset:32768
	ds_read_b128 v[212:215], v153 offset:33792
	ds_read_b128 v[216:219], v151 offset:32768
	ds_read_b128 v[220:223], v151 offset:33792
	global_load_lds_dwordx4 v[224:225], off
	v_lshl_add_u64 v[224:225], v[242:243], 0, s[22:23]
	s_mov_b32 m0, s1
	s_nop 0
	global_load_lds_dwordx4 v[224:225], off
	s_nop 0
	s_barrier
	s_waitcnt lgkmcnt(0)
	s_setprio 1
	s_waitcnt lgkmcnt(0)
	v_mfma_f32_16x16x32_bf16 v[124:127], v[174:177], v[192:195], v[124:127]
	v_mfma_f32_16x16x32_bf16 v[120:123], v[184:187], v[192:195], v[120:123]
	v_mfma_f32_16x16x32_bf16 v[116:119], v[174:177], v[200:203], v[116:119]
	v_mfma_f32_16x16x32_bf16 v[112:115], v[184:187], v[200:203], v[112:115]
	v_mfma_f32_16x16x32_bf16 v[108:111], v[174:177], v[208:211], v[108:111]
	v_mfma_f32_16x16x32_bf16 v[104:107], v[184:187], v[208:211], v[104:107]
	v_mfma_f32_16x16x32_bf16 v[100:103], v[174:177], v[216:219], v[100:103]
	v_mfma_f32_16x16x32_bf16 v[96:99], v[184:187], v[216:219], v[96:99]
	v_mfma_f32_16x16x32_bf16 v[124:127], v[178:181], v[196:199], v[124:127]
	v_mfma_f32_16x16x32_bf16 v[120:123], v[188:191], v[196:199], v[120:123]
	v_mfma_f32_16x16x32_bf16 v[116:119], v[178:181], v[204:207], v[116:119]
	v_mfma_f32_16x16x32_bf16 v[112:115], v[188:191], v[204:207], v[112:115]
	v_mfma_f32_16x16x32_bf16 v[108:111], v[178:181], v[212:215], v[108:111]
	v_mfma_f32_16x16x32_bf16 v[104:107], v[188:191], v[212:215], v[104:107]
	v_mfma_f32_16x16x32_bf16 v[100:103], v[178:181], v[220:223], v[100:103]
	v_mfma_f32_16x16x32_bf16 v[96:99], v[188:191], v[220:223], v[96:99]
	s_setprio 0
	s_barrier
	v_readfirstlane_b32 s1, v164
	v_lshl_add_u64 v[248:249], v[244:245], 0, s[24:25]
	s_mov_b32 m0, s1
	v_readfirstlane_b32 s1, v165
	ds_read_b128 v[224:227], v157
	ds_read_b128 v[228:231], v157 offset:1024
	ds_read_b128 v[232:235], v157 offset:2048
	ds_read_b128 v[236:239], v157 offset:3072
	global_load_lds_dwordx4 v[248:249], off
	v_lshl_add_u64 v[248:249], v[246:247], 0, s[24:25]
	s_mov_b32 m0, s1
	s_nop 0
	global_load_lds_dwordx4 v[248:249], off
	s_barrier
	s_waitcnt lgkmcnt(0)
	s_setprio 1
	s_waitcnt lgkmcnt(0)
	v_mfma_f32_16x16x32_bf16 v[92:95], v[224:227], v[192:195], v[92:95]
	v_mfma_f32_16x16x32_bf16 v[88:91], v[232:235], v[192:195], v[88:91]
	v_mfma_f32_16x16x32_bf16 v[84:87], v[224:227], v[200:203], v[84:87]
	v_mfma_f32_16x16x32_bf16 v[80:83], v[232:235], v[200:203], v[80:83]
	v_mfma_f32_16x16x32_bf16 v[76:79], v[224:227], v[208:211], v[76:79]
	v_mfma_f32_16x16x32_bf16 v[72:75], v[232:235], v[208:211], v[72:75]
	v_mfma_f32_16x16x32_bf16 v[68:71], v[224:227], v[216:219], v[68:71]
	v_mfma_f32_16x16x32_bf16 v[64:67], v[232:235], v[216:219], v[64:67]
	v_mfma_f32_16x16x32_bf16 v[92:95], v[228:231], v[196:199], v[92:95]
	v_mfma_f32_16x16x32_bf16 v[88:91], v[236:239], v[196:199], v[88:91]
	v_mfma_f32_16x16x32_bf16 v[84:87], v[228:231], v[204:207], v[84:87]
	v_mfma_f32_16x16x32_bf16 v[80:83], v[236:239], v[204:207], v[80:83]
	v_mfma_f32_16x16x32_bf16 v[76:79], v[228:231], v[212:215], v[76:79]
	v_mfma_f32_16x16x32_bf16 v[72:75], v[236:239], v[212:215], v[72:75]
	v_mfma_f32_16x16x32_bf16 v[68:71], v[228:231], v[220:223], v[68:71]
	v_mfma_f32_16x16x32_bf16 v[64:67], v[236:239], v[220:223], v[64:67]
	s_setprio 0
	v_readfirstlane_b32 s1, v166
	v_lshl_add_u64 v[240:241], v[240:241], 0, s[26:27]
	s_mov_b32 m0, s1
	v_readfirstlane_b32 s1, v167
	s_barrier
	ds_read_b128 v[192:195], v155 offset:49152
	ds_read_b128 v[196:199], v155 offset:50176
	ds_read_b128 v[200:203], v154 offset:49152
	ds_read_b128 v[204:207], v154 offset:50176
	ds_read_b128 v[208:211], v153 offset:49152
	ds_read_b128 v[212:215], v153 offset:50176
	ds_read_b128 v[216:219], v151 offset:49152
	ds_read_b128 v[220:223], v151 offset:50176
	global_load_lds_dwordx4 v[240:241], off
	v_lshl_add_u64 v[240:241], v[242:243], 0, s[26:27]
	s_mov_b32 m0, s1
	s_nop 0
	global_load_lds_dwordx4 v[240:241], off
	s_barrier
; #define STAGE(P, BASE, br, kt) do { const long _g = (long)(br) * K + (long)(kt) * 64; \
;     _Pragma("unroll") for (int _i = 0; _i < 2; ++_i) { const int _b = tidx * 16 + _i * 8192; int _r, _c; stage_rc8(_b, _r, _c); \
;       __builtin_amdgcn_global_load_lds((const unsigned*)(BASE + _g + (long)_r * K + _c), (LAS unsigned*)((LAS char*)(P) + _b), 16, 0, 0); } } while (0)
; #define LDA(dst, b, h) _Pragma("unroll") for (int m = 0; m < 4; ++m) _Pragma("unroll") for (int k = 0; k < 2; ++k) \
;     dst[m][k] = *reinterpret_cast<const bf16x8*>((const char*)SA(b, h) + lds_byte8(wr * 64 + m * 16 + fr, k * 32 + fq * 8))
; #define LDB(dst, b, h) _Pragma("unroll") for (int n = 0; n < 2; ++n) _Pragma("unroll") for (int k = 0; k < 2; ++k) \
;     dst[n][k] = *reinterpret_cast<const bf16x8*>((const char*)SB(b, h) + lds_byte8(wc * 32 + n * 16 + fr, k * 32 + fq * 8))
; #define MMA(ai, bj, At_, Bt_) do { __builtin_amdgcn_s_setprio(1); \
;     _Pragma("unroll") for (int m = 0; m < 4; ++m) _Pragma("unroll") for (int n = 0; n < 2; ++n) _Pragma("unroll") for (int k = 0; k < 2; ++k) \
;       acc[ai][bj][m][n] = MFMA16(Bt_[n][k], At_[m][k], acc[ai][bj][m][n]); \
;     __builtin_amdgcn_s_setprio(0); } while (0)
; #define WAIT_V(n) asm volatile("s_waitcnt vmcnt(" #n ")" ::: "memory")
; #define WAIT_L(n) asm volatile("s_waitcnt lgkmcnt(" #n ")" ::: "memory")
; #define BAR __builtin_amdgcn_s_barrier()
; #define SCHED __builtin_amdgcn_sched_barrier(0)
; template <class FL, class FS>
; DI void gemm8_tile(char* shmc, const bf16_t* __restrict__ A, const bf16_t* __restrict__ Bt, const int K, const int brow, const int bcol, FL fl, FS fs) {
;     ...
;     BAR; WAIT_L(0); MMA(1, 0, At, B0); BAR; SCHED;
;     STAGE(SB(1, 1), Bt, bcol + HALF, t + 3);
;     WAIT_V(6); BAR; MMA(1, 1, At, B1); BAR;
;   }
;   { LDB(B0, 0, 0); LDA(At, 0, 0); STAGE(SA(1, 1), A, brow + HALF, nt - 1);
;     BAR; WAIT_L(0); MMA(0, 0, At, B0); BAR;
	s_waitcnt lgkmcnt(0)
	s_setprio 1
	s_waitcnt lgkmcnt(0)
	v_mfma_f32_16x16x32_bf16 v[60:63], v[174:177], v[192:195], v[60:63]
	v_mfma_f32_16x16x32_bf16 v[56:59], v[184:187], v[192:195], v[56:59]
	v_mfma_f32_16x16x32_bf16 v[52:55], v[174:177], v[200:203], v[52:55]
	v_mfma_f32_16x16x32_bf16 v[48:51], v[184:187], v[200:203], v[48:51]
	v_mfma_f32_16x16x32_bf16 v[44:47], v[174:177], v[208:211], v[44:47]
	v_mfma_f32_16x16x32_bf16 v[40:43], v[184:187], v[208:211], v[40:43]
	v_mfma_f32_16x16x32_bf16 v[36:39], v[174:177], v[216:219], v[36:39]
	v_mfma_f32_16x16x32_bf16 v[32:35], v[184:187], v[216:219], v[32:35]
	v_mfma_f32_16x16x32_bf16 v[60:63], v[178:181], v[196:199], v[60:63]
	v_mfma_f32_16x16x32_bf16 v[56:59], v[188:191], v[196:199], v[56:59]
	v_mfma_f32_16x16x32_bf16 v[52:55], v[178:181], v[204:207], v[52:55]
	v_mfma_f32_16x16x32_bf16 v[48:51], v[188:191], v[204:207], v[48:51]
	v_mfma_f32_16x16x32_bf16 v[44:47], v[178:181], v[212:215], v[44:47]
	v_mfma_f32_16x16x32_bf16 v[40:43], v[188:191], v[212:215], v[40:43]
	v_mfma_f32_16x16x32_bf16 v[36:39], v[178:181], v[220:223], v[36:39]
	v_mfma_f32_16x16x32_bf16 v[32:35], v[188:191], v[220:223], v[32:35]
	s_setprio 0
	s_barrier
	v_readfirstlane_b32 s1, v168
	v_lshl_add_u64 v[174:175], v[244:245], 0, s[28:29]
	s_mov_b32 m0, s1
	v_readfirstlane_b32 s1, v170
	global_load_lds_dwordx4 v[174:175], off
	v_lshl_add_u64 v[174:175], v[246:247], 0, s[28:29]
	s_mov_b32 m0, s1
	s_nop 0
	global_load_lds_dwordx4 v[174:175], off
	s_waitcnt vmcnt(6)
	s_barrier
	s_setprio 1
	v_mfma_f32_16x16x32_bf16 v[28:31], v[224:227], v[192:195], v[28:31]
	v_mfma_f32_16x16x32_bf16 v[24:27], v[232:235], v[192:195], v[24:27]
	v_mfma_f32_16x16x32_bf16 v[20:23], v[224:227], v[200:203], v[20:23]
	v_mfma_f32_16x16x32_bf16 v[16:19], v[232:235], v[200:203], v[16:19]
	v_mfma_f32_16x16x32_bf16 v[12:15], v[224:227], v[208:211], v[12:15]
	v_mfma_f32_16x16x32_bf16 v[8:11], v[232:235], v[208:211], v[8:11]
	v_mfma_f32_16x16x32_bf16 v[4:7], v[224:227], v[216:219], v[4:7]
	v_mfma_f32_16x16x32_bf16 v[0:3], v[232:235], v[216:219], v[0:3]
	v_mfma_f32_16x16x32_bf16 v[28:31], v[228:231], v[196:199], v[28:31]
	v_mfma_f32_16x16x32_bf16 v[24:27], v[236:239], v[196:199], v[24:27]
	v_mfma_f32_16x16x32_bf16 v[20:23], v[228:231], v[204:207], v[20:23]
	v_mfma_f32_16x16x32_bf16 v[16:19], v[236:239], v[204:207], v[16:19]
	v_mfma_f32_16x16x32_bf16 v[12:15], v[228:231], v[212:215], v[12:15]
	v_mfma_f32_16x16x32_bf16 v[8:11], v[236:239], v[212:215], v[8:11]
	v_mfma_f32_16x16x32_bf16 v[4:7], v[228:231], v[220:223], v[4:7]
	v_mfma_f32_16x16x32_bf16 v[0:3], v[236:239], v[220:223], v[0:3]
	s_setprio 0
	s_add_i32 s0, s0, 2
	v_lshl_add_u64 v[132:133], v[132:133], 0, s[30:31]
	v_lshl_add_u64 v[134:135], v[134:135], 0, s[30:31]
	v_lshl_add_u64 v[136:137], v[136:137], 0, s[30:31]
	s_cmp_lt_u32 s0, 12
	v_lshl_add_u64 v[138:139], v[138:139], 0, s[30:31]
	s_barrier
	s_cbranch_scc1 .LBB0_2092
	v_readfirstlane_b32 s0, v172
	v_lshl_add_u64 v[128:129], v[128:129], 0, s[34:35]
	s_mov_b32 m0, s0
	v_readfirstlane_b32 s0, v171
	ds_read_b128 v[132:135], v173
	ds_read_b128 v[136:139], v173 offset:1024
	ds_read_b128 v[160:163], v173 offset:2048
	ds_read_b128 v[164:167], v173 offset:3072
	ds_read_b128 v[174:177], v155
	ds_read_b128 v[178:181], v155 offset:1024
	ds_read_b128 v[184:187], v154
	ds_read_b128 v[188:191], v154 offset:1024
	ds_read_b128 v[192:195], v153
	ds_read_b128 v[196:199], v153 offset:1024
	ds_read_b128 v[200:203], v151
	ds_read_b128 v[204:207], v151 offset:1024
	global_load_lds_dwordx4 v[128:129], off
	v_lshl_add_u64 v[128:129], v[130:131], 0, s[34:35]
	s_mov_b32 m0, s0
	s_nop 0
	global_load_lds_dwordx4 v[128:129], off
	s_barrier
	s_waitcnt lgkmcnt(0)
	s_setprio 1
	s_waitcnt lgkmcnt(0)
	v_mfma_f32_16x16x32_bf16 v[124:127], v[132:135], v[174:177], v[124:127]
	v_mfma_f32_16x16x32_bf16 v[120:123], v[160:163], v[174:177], v[120:123]
	v_mfma_f32_16x16x32_bf16 v[116:119], v[132:135], v[184:187], v[116:119]
	v_mfma_f32_16x16x32_bf16 v[96:99], v[160:163], v[200:203], v[96:99]
	v_mfma_f32_16x16x32_bf16 v[124:127], v[136:139], v[178:181], v[124:127]
	v_mfma_f32_16x16x32_bf16 v[120:123], v[164:167], v[178:181], v[120:123]
	v_mfma_f32_16x16x32_bf16 v[116:119], v[136:139], v[188:191], v[116:119]
	v_mfma_f32_16x16x32_bf16 v[112:115], v[160:163], v[184:187], v[112:115]
	v_mfma_f32_16x16x32_bf16 v[108:111], v[132:135], v[192:195], v[108:111]
	v_mfma_f32_16x16x32_bf16 v[104:107], v[160:163], v[192:195], v[104:107]
	v_mfma_f32_16x16x32_bf16 v[100:103], v[132:135], v[200:203], v[100:103]
	v_mfma_f32_16x16x32_bf16 v[96:99], v[164:167], v[204:207], v[96:99]
	v_mfma_f32_16x16x32_bf16 v[128:131], v[164:167], v[188:191], v[112:115]
	v_mfma_f32_16x16x32_bf16 v[170:173], v[136:139], v[196:199], v[108:111]
	v_mfma_f32_16x16x32_bf16 v[208:211], v[164:167], v[196:199], v[104:107]
	v_mfma_f32_16x16x32_bf16 v[212:215], v[136:139], v[204:207], v[100:103]
	s_setprio 0
	s_barrier
	ds_read_b128 v[100:103], v169
	ds_read_b128 v[104:107], v169 offset:1024
	ds_read_b128 v[108:111], v169 offset:2048
	ds_read_b128 v[112:115], v169 offset:3072
	s_barrier
; #define LDA(dst, b, h) _Pragma("unroll") for (int m = 0; m < 4; ++m) _Pragma("unroll") for (int k = 0; k < 2; ++k) \
;     dst[m][k] = *reinterpret_cast<const bf16x8*>((const char*)SA(b, h) + lds_byte8(wr * 64 + m * 16 + fr, k * 32 + fq * 8))
; #define LDB(dst, b, h) _Pragma("unroll") for (int n = 0; n < 2; ++n) _Pragma("unroll") for (int k = 0; k < 2; ++k) \
;     dst[n][k] = *reinterpret_cast<const bf16x8*>((const char*)SB(b, h) + lds_byte8(wc * 32 + n * 16 + fr, k * 32 + fq * 8))
; #define MMA(ai, bj, At_, Bt_) do { __builtin_amdgcn_s_setprio(1); \
;     _Pragma("unroll") for (int m = 0; m < 4; ++m) _Pragma("unroll") for (int n = 0; n < 2; ++n) _Pragma("unroll") for (int k = 0; k < 2; ++k) \
;       acc[ai][bj][m][n] = MFMA16(Bt_[n][k], At_[m][k], acc[ai][bj][m][n]); \
;     __builtin_amdgcn_s_setprio(0); } while (0)
; #define WAIT_V(n) asm volatile("s_waitcnt vmcnt(" #n ")" ::: "memory")
; #define WAIT_L(n) asm volatile("s_waitcnt lgkmcnt(" #n ")" ::: "memory")
; #define BAR __builtin_amdgcn_s_barrier()
; template <class FL, class FS>
; DI void gemm8_tile(char* shmc, const bf16_t* __restrict__ A, const bf16_t* __restrict__ Bt, const int K, const int brow, const int bcol, FL fl, FS fs) {
;     ...
;     BAR; WAIT_L(0); MMA(0, 0, At, B0); BAR;
;     LDB(B1, 0, 1); BAR; WAIT_L(0); MMA(0, 1, At, B1); BAR;
;     LDA(At, 0, 1); WAIT_V(4); BAR; WAIT_L(0); MMA(1, 0, At, B0); MMA(1, 1, At, B1); BAR; }
;   { LDB(B0, 1, 0); LDA(At, 1, 0); WAIT_V(2); BAR; WAIT_L(0); MMA(0, 0, At, B0); BAR;
	s_waitcnt lgkmcnt(0)
	s_setprio 1
	s_waitcnt lgkmcnt(3)
	v_mfma_f32_16x16x32_bf16 v[92:95], v[100:103], v[174:177], v[92:95]
	s_waitcnt lgkmcnt(1)
	v_mfma_f32_16x16x32_bf16 v[88:91], v[108:111], v[174:177], v[88:91]
	v_mfma_f32_16x16x32_bf16 v[84:87], v[100:103], v[184:187], v[84:87]
	v_mfma_f32_16x16x32_bf16 v[64:67], v[108:111], v[200:203], v[64:67]
	v_mfma_f32_16x16x32_bf16 v[92:95], v[104:107], v[178:181], v[92:95]
	s_waitcnt lgkmcnt(0)
	v_mfma_f32_16x16x32_bf16 v[88:91], v[112:115], v[178:181], v[88:91]
	v_mfma_f32_16x16x32_bf16 v[84:87], v[104:107], v[188:191], v[84:87]
	v_mfma_f32_16x16x32_bf16 v[80:83], v[108:111], v[184:187], v[80:83]
	v_mfma_f32_16x16x32_bf16 v[76:79], v[100:103], v[192:195], v[76:79]
	v_mfma_f32_16x16x32_bf16 v[72:75], v[108:111], v[192:195], v[72:75]
	v_mfma_f32_16x16x32_bf16 v[68:71], v[100:103], v[200:203], v[68:71]
	v_mfma_f32_16x16x32_bf16 v[64:67], v[112:115], v[204:207], v[64:67]
	v_mfma_f32_16x16x32_bf16 v[174:177], v[112:115], v[188:191], v[80:83]
	v_mfma_f32_16x16x32_bf16 v[178:181], v[104:107], v[196:199], v[76:79]
	v_mfma_f32_16x16x32_bf16 v[184:187], v[112:115], v[196:199], v[72:75]
	v_mfma_f32_16x16x32_bf16 v[188:191], v[104:107], v[204:207], v[68:71]
	s_setprio 0
	s_barrier
	s_nop 0
	ds_read_b128 v[68:71], v155 offset:16384
	ds_read_b128 v[72:75], v155 offset:17408
	ds_read_b128 v[76:79], v154 offset:16384
	ds_read_b128 v[80:83], v154 offset:17408
	ds_read_b128 v[192:195], v153 offset:16384
	ds_read_b128 v[196:199], v153 offset:17408
	ds_read_b128 v[200:203], v151 offset:16384
	ds_read_b128 v[204:207], v151 offset:17408
	s_waitcnt vmcnt(4)
	s_barrier
	s_waitcnt lgkmcnt(0)
	s_setprio 1
	s_waitcnt lgkmcnt(7)
	v_mfma_f32_16x16x32_bf16 v[60:63], v[132:135], v[68:71], v[60:63]
	v_mfma_f32_16x16x32_bf16 v[56:59], v[160:163], v[68:71], v[56:59]
	s_waitcnt lgkmcnt(3)
	v_mfma_f32_16x16x32_bf16 v[44:47], v[132:135], v[192:195], v[44:47]
	s_waitcnt lgkmcnt(1)
	v_mfma_f32_16x16x32_bf16 v[32:35], v[160:163], v[200:203], v[32:35]
	v_mfma_f32_16x16x32_bf16 v[60:63], v[136:139], v[72:75], v[60:63]
	v_mfma_f32_16x16x32_bf16 v[56:59], v[164:167], v[72:75], v[56:59]
	v_mfma_f32_16x16x32_bf16 v[52:55], v[132:135], v[76:79], v[52:55]
	v_mfma_f32_16x16x32_bf16 v[48:51], v[160:163], v[76:79], v[48:51]
	v_mfma_f32_16x16x32_bf16 v[44:47], v[136:139], v[196:199], v[44:47]
	v_mfma_f32_16x16x32_bf16 v[40:43], v[160:163], v[192:195], v[40:43]
	v_mfma_f32_16x16x32_bf16 v[36:39], v[132:135], v[200:203], v[36:39]
	s_waitcnt lgkmcnt(0)
	v_mfma_f32_16x16x32_bf16 v[32:35], v[164:167], v[204:207], v[32:35]
	v_mfma_f32_16x16x32_bf16 v[216:219], v[136:139], v[80:83], v[52:55]
	v_mfma_f32_16x16x32_bf16 v[220:223], v[164:167], v[80:83], v[48:51]
	v_mfma_f32_16x16x32_bf16 v[224:227], v[164:167], v[196:199], v[40:43]
	v_mfma_f32_16x16x32_bf16 v[132:135], v[136:139], v[204:207], v[36:39]
	s_setprio 0
	s_setprio 1
	v_mfma_f32_16x16x32_bf16 v[28:31], v[100:103], v[68:71], v[28:31]
	v_mfma_f32_16x16x32_bf16 v[24:27], v[108:111], v[68:71], v[24:27]
	v_mfma_f32_16x16x32_bf16 v[12:15], v[100:103], v[192:195], v[12:15]
	v_mfma_f32_16x16x32_bf16 v[0:3], v[108:111], v[200:203], v[0:3]
	v_mfma_f32_16x16x32_bf16 v[28:31], v[104:107], v[72:75], v[28:31]
	v_mfma_f32_16x16x32_bf16 v[24:27], v[112:115], v[72:75], v[24:27]
	v_mfma_f32_16x16x32_bf16 v[20:23], v[100:103], v[76:79], v[20:23]
	v_mfma_f32_16x16x32_bf16 v[16:19], v[108:111], v[76:79], v[16:19]
	v_mfma_f32_16x16x32_bf16 v[12:15], v[104:107], v[196:199], v[12:15]
	v_mfma_f32_16x16x32_bf16 v[8:11], v[108:111], v[192:195], v[8:11]
	v_mfma_f32_16x16x32_bf16 v[4:7], v[100:103], v[200:203], v[4:7]
	v_mfma_f32_16x16x32_bf16 v[0:3], v[112:115], v[204:207], v[0:3]
	v_mfma_f32_16x16x32_bf16 v[136:139], v[104:107], v[80:83], v[20:23]
	v_mfma_f32_16x16x32_bf16 v[160:163], v[112:115], v[80:83], v[16:19]
	v_mfma_f32_16x16x32_bf16 v[164:167], v[112:115], v[196:199], v[8:11]
	v_mfma_f32_16x16x32_bf16 v[192:195], v[104:107], v[204:207], v[4:7]
	s_setprio 0
	s_barrier
	s_nop 0
	ds_read_b128 v[4:7], v159
	ds_read_b128 v[8:11], v159 offset:1024
	ds_read_b128 v[196:199], v159 offset:2048
	ds_read_b128 v[200:203], v159 offset:3072
	ds_read_b128 v[16:19], v155 offset:32768
	ds_read_b128 v[20:23], v155 offset:33792
	ds_read_b128 v[36:39], v154 offset:32768
	ds_read_b128 v[40:43], v154 offset:33792
	ds_read_b128 v[48:51], v153 offset:32768
	ds_read_b128 v[52:55], v153 offset:33792
	ds_read_b128 v[204:207], v151 offset:32768
	ds_read_b128 v[228:231], v151 offset:33792
	s_waitcnt vmcnt(2)
	s_barrier
; #define LDA(dst, b, h) _Pragma("unroll") for (int m = 0; m < 4; ++m) _Pragma("unroll") for (int k = 0; k < 2; ++k) \
;     dst[m][k] = *reinterpret_cast<const bf16x8*>((const char*)SA(b, h) + lds_byte8(wr * 64 + m * 16 + fr, k * 32 + fq * 8))
; #define LDB(dst, b, h) _Pragma("unroll") for (int n = 0; n < 2; ++n) _Pragma("unroll") for (int k = 0; k < 2; ++k) \
;     dst[n][k] = *reinterpret_cast<const bf16x8*>((const char*)SB(b, h) + lds_byte8(wc * 32 + n * 16 + fr, k * 32 + fq * 8))
; #define MMA(ai, bj, At_, Bt_) do { __builtin_amdgcn_s_setprio(1); \
;     _Pragma("unroll") for (int m = 0; m < 4; ++m) _Pragma("unroll") for (int n = 0; n < 2; ++n) _Pragma("unroll") for (int k = 0; k < 2; ++k) \
;       acc[ai][bj][m][n] = MFMA16(Bt_[n][k], At_[m][k], acc[ai][bj][m][n]); \
;     __builtin_amdgcn_s_setprio(0); } while (0)
; #define WAIT_V(n) asm volatile("s_waitcnt vmcnt(" #n ")" ::: "memory")
; #define WAIT_L(n) asm volatile("s_waitcnt lgkmcnt(" #n ")" ::: "memory")
; #define BAR __builtin_amdgcn_s_barrier()
; template <class FL, class FS>
; DI void gemm8_tile(char* shmc, const bf16_t* __restrict__ A, const bf16_t* __restrict__ Bt, const int K, const int brow, const int bcol, FL fl, FS fs) {
;     ...
;   { LDB(B0, 1, 0); LDA(At, 1, 0); WAIT_V(2); BAR; WAIT_L(0); MMA(0, 0, At, B0); BAR;
;     LDB(B1, 1, 1); WAIT_V(0); BAR; WAIT_L(0); MMA(0, 1, At, B1); BAR;
;     LDA(At, 1, 1); BAR; WAIT_L(0); MMA(1, 0, At, B0); MMA(1, 1, At, B1); BAR; }
;   if (wr == 0) BAR;
	s_waitcnt lgkmcnt(0)
	s_setprio 1
	s_waitcnt lgkmcnt(7)
	v_mfma_f32_16x16x32_bf16 v[68:71], v[4:7], v[16:19], v[124:127]
	s_waitcnt lgkmcnt(6)
	v_mfma_f32_16x16x32_bf16 v[112:115], v[8:11], v[20:23], v[68:71]
	v_mfma_f32_16x16x32_bf16 v[68:71], v[196:199], v[16:19], v[120:123]
	v_mfma_f32_16x16x32_bf16 v[108:111], v[200:203], v[20:23], v[68:71]
	s_waitcnt lgkmcnt(5)
	v_mfma_f32_16x16x32_bf16 v[68:71], v[4:7], v[36:39], v[116:119]
	s_waitcnt lgkmcnt(4)
	v_mfma_f32_16x16x32_bf16 v[104:107], v[8:11], v[40:43], v[68:71]
	v_mfma_f32_16x16x32_bf16 v[68:71], v[196:199], v[36:39], v[128:131]
	v_mfma_f32_16x16x32_bf16 v[100:103], v[200:203], v[40:43], v[68:71]
	s_waitcnt lgkmcnt(3)
	v_mfma_f32_16x16x32_bf16 v[68:71], v[4:7], v[48:51], v[170:173]
	s_waitcnt lgkmcnt(2)
	v_mfma_f32_16x16x32_bf16 v[80:83], v[8:11], v[52:55], v[68:71]
	v_mfma_f32_16x16x32_bf16 v[68:71], v[196:199], v[48:51], v[208:211]
	v_mfma_f32_16x16x32_bf16 v[76:79], v[200:203], v[52:55], v[68:71]
	s_waitcnt lgkmcnt(1)
	v_mfma_f32_16x16x32_bf16 v[68:71], v[4:7], v[204:207], v[212:215]
	s_waitcnt lgkmcnt(0)
	v_mfma_f32_16x16x32_bf16 v[72:75], v[8:11], v[228:231], v[68:71]
	v_mfma_f32_16x16x32_bf16 v[68:71], v[196:199], v[204:207], v[96:99]
	v_mfma_f32_16x16x32_bf16 v[68:71], v[200:203], v[228:231], v[68:71]
	s_setprio 0
	s_barrier
	ds_read_b128 v[128:131], v157
	ds_read_b128 v[168:171], v157 offset:1024
	ds_read_b128 v[208:211], v157 offset:2048
	ds_read_b128 v[156:159], v157 offset:3072
	s_waitcnt vmcnt(0)
	s_barrier
	s_waitcnt lgkmcnt(0)
	s_setprio 1
	s_waitcnt lgkmcnt(3)
	v_mfma_f32_16x16x32_bf16 v[92:95], v[128:131], v[16:19], v[92:95]
	s_waitcnt lgkmcnt(1)
	v_mfma_f32_16x16x32_bf16 v[16:19], v[208:211], v[16:19], v[88:91]
	s_waitcnt lgkmcnt(0)
	v_mfma_f32_16x16x32_bf16 v[120:123], v[156:159], v[20:23], v[16:19]
	v_mfma_f32_16x16x32_bf16 v[16:19], v[128:131], v[36:39], v[84:87]
	v_mfma_f32_16x16x32_bf16 v[116:119], v[168:171], v[40:43], v[16:19]
	v_mfma_f32_16x16x32_bf16 v[16:19], v[208:211], v[36:39], v[174:177]
	v_mfma_f32_16x16x32_bf16 v[96:99], v[156:159], v[40:43], v[16:19]
	v_mfma_f32_16x16x32_bf16 v[16:19], v[128:131], v[48:51], v[178:181]
	v_mfma_f32_16x16x32_bf16 v[124:127], v[168:171], v[20:23], v[92:95]
	v_mfma_f32_16x16x32_bf16 v[92:95], v[168:171], v[52:55], v[16:19]
	v_mfma_f32_16x16x32_bf16 v[16:19], v[208:211], v[48:51], v[184:187]
	v_mfma_f32_16x16x32_bf16 v[88:91], v[156:159], v[52:55], v[16:19]
	v_mfma_f32_16x16x32_bf16 v[16:19], v[128:131], v[204:207], v[188:191]
	v_mfma_f32_16x16x32_bf16 v[84:87], v[168:171], v[228:231], v[16:19]
	v_mfma_f32_16x16x32_bf16 v[16:19], v[208:211], v[204:207], v[64:67]
	v_mfma_f32_16x16x32_bf16 v[64:67], v[156:159], v[228:231], v[16:19]
	s_setprio 0
	s_barrier
	ds_read_b128 v[172:175], v155 offset:49152
	ds_read_b128 v[176:179], v155 offset:50176
	ds_read_b128 v[184:187], v154 offset:49152
	ds_read_b128 v[188:191], v154 offset:50176
	ds_read_b128 v[204:207], v153 offset:49152
	ds_read_b128 v[152:155], v153 offset:50176
	ds_read_b128 v[212:215], v151 offset:49152
	ds_read_b128 v[228:231], v151 offset:50176
	s_barrier
	s_waitcnt lgkmcnt(0)
	s_setprio 1
	s_waitcnt lgkmcnt(7)
	v_mfma_f32_16x16x32_bf16 v[16:19], v[4:7], v[172:175], v[60:63]
	s_waitcnt lgkmcnt(6)
	v_mfma_f32_16x16x32_bf16 v[52:55], v[8:11], v[176:179], v[16:19]
	v_mfma_f32_16x16x32_bf16 v[16:19], v[196:199], v[172:175], v[56:59]
	v_mfma_f32_16x16x32_bf16 v[48:51], v[200:203], v[176:179], v[16:19]
	s_waitcnt lgkmcnt(5)
	v_mfma_f32_16x16x32_bf16 v[16:19], v[4:7], v[184:187], v[216:219]
	s_waitcnt lgkmcnt(4)
	v_mfma_f32_16x16x32_bf16 v[40:43], v[8:11], v[188:191], v[16:19]
	v_mfma_f32_16x16x32_bf16 v[16:19], v[196:199], v[184:187], v[220:223]
	v_mfma_f32_16x16x32_bf16 v[36:39], v[200:203], v[188:191], v[16:19]
	s_waitcnt lgkmcnt(3)
	v_mfma_f32_16x16x32_bf16 v[16:19], v[4:7], v[204:207], v[44:47]
	s_waitcnt lgkmcnt(1)
	v_mfma_f32_16x16x32_bf16 v[4:7], v[4:7], v[212:215], v[132:135]
	v_mfma_f32_16x16x32_bf16 v[20:23], v[8:11], v[152:155], v[16:19]
	v_mfma_f32_16x16x32_bf16 v[16:19], v[196:199], v[204:207], v[224:227]
	s_waitcnt lgkmcnt(0)
	v_mfma_f32_16x16x32_bf16 v[8:11], v[8:11], v[228:231], v[4:7]
	v_mfma_f32_16x16x32_bf16 v[4:7], v[196:199], v[212:215], v[32:35]
	v_mfma_f32_16x16x32_bf16 v[16:19], v[200:203], v[152:155], v[16:19]
	v_mfma_f32_16x16x32_bf16 v[4:7], v[200:203], v[228:231], v[4:7]
	s_setprio 0
	s_setprio 1
	v_mfma_f32_16x16x32_bf16 v[24:27], v[208:211], v[172:175], v[24:27]
	v_mfma_f32_16x16x32_bf16 v[28:31], v[128:131], v[172:175], v[28:31]
	v_mfma_f32_16x16x32_bf16 v[56:59], v[156:159], v[176:179], v[24:27]
	v_mfma_f32_16x16x32_bf16 v[24:27], v[128:131], v[184:187], v[136:139]
	v_mfma_f32_16x16x32_bf16 v[12:15], v[128:131], v[204:207], v[12:15]
	v_mfma_f32_16x16x32_bf16 v[60:63], v[168:171], v[176:179], v[28:31]
	v_mfma_f32_16x16x32_bf16 v[44:47], v[168:171], v[188:191], v[24:27]
	v_mfma_f32_16x16x32_bf16 v[24:27], v[208:211], v[184:187], v[160:163]
	v_mfma_f32_16x16x32_bf16 v[28:31], v[168:171], v[152:155], v[12:15]
	v_mfma_f32_16x16x32_bf16 v[12:15], v[208:211], v[204:207], v[164:167]
	v_mfma_f32_16x16x32_bf16 v[32:35], v[156:159], v[188:191], v[24:27]
	v_mfma_f32_16x16x32_bf16 v[24:27], v[156:159], v[152:155], v[12:15]
	v_mfma_f32_16x16x32_bf16 v[12:15], v[128:131], v[212:215], v[192:195]
	v_mfma_f32_16x16x32_bf16 v[0:3], v[208:211], v[212:215], v[0:3]
	v_mfma_f32_16x16x32_bf16 v[12:15], v[168:171], v[228:231], v[12:15]
	v_mfma_f32_16x16x32_bf16 v[0:3], v[156:159], v[228:231], v[0:3]
	s_setprio 0
	v_cmp_gt_u32_e32 vcc, s52, v140
	s_barrier
	s_and_saveexec_b64 s[0:1], vcc
	s_cbranch_execz .Lg5_wr0
	s_barrier
